# K-loops: removed the back-to-back s_setprio 0 / s_setprio 1 pair between the two 16-MFMA groups of every MFMA block (two inserted issue slots inside an MFMA-paced run)
# speedup vs baseline: 1.0170x; 1.0170x over previous
; #define PG8_STAGE(bufoff, gbase, voff) do { _Pragma("unroll") for (int _i = 0; _i < 2; ++_i) \
;         __builtin_amdgcn_global_load_lds((const unsigned*)((const char*)(gbase) + (voff)[_i]), (PG8_LAS unsigned*)(lds + (bufoff) + ldsw + _i * 8192), 16, 0, 0); } while (0)
; #define PG8_LDA(dst, b, h) do { _Pragma("unroll") for (int m = 0; m < 4; ++m) _Pragma("unroll") for (int k = 0; k < 2; ++k) dst[m][k] = *(const PG8_LAS bf16x8*)(lds + PG8_SA(b, h) + aoff + m * 2048 + k * 1024); } while (0)
; #define PG8_LDB(dst, b, h) do { _Pragma("unroll") for (int n = 0; n < 2; ++n) _Pragma("unroll") for (int k = 0; k < 2; ++k) dst[n][k] = *(const PG8_LAS bf16x8*)(lds + PG8_SB(b, h) + boff + n * 2048 + k * 1024); } while (0)
; #define PG8_MMA(ai, bj, At, Bt) do { __builtin_amdgcn_s_setprio(1); _Pragma("unroll") for (int m = 0; m < 4; ++m) _Pragma("unroll") for (int n = 0; n < 2; ++n) _Pragma("unroll") for (int k = 0; k < 2; ++k) \
;         acc[ai][bj][m][n] = __builtin_amdgcn_mfma_f32_16x16x32_bf16(Bt[n][k], At[m][k], acc[ai][bj][m][n], 0, 0, 0); __builtin_amdgcn_s_setprio(0); } while (0)
; #define PG8_WAIT_V(n) asm volatile("s_waitcnt vmcnt(" #n ")" ::: "memory")
; #define PG8_WAIT_L(n) asm volatile("s_waitcnt lgkmcnt(" #n ")" ::: "memory")
; #define PG8_BAR __builtin_amdgcn_s_barrier()
; #define PG8_SCHED __builtin_amdgcn_sched_barrier(0)
; template <class Epi, class Sched, bool ALIGN_EPI = false, bool SP2 = false>
; __device__ __forceinline__ void gemm_phase(PG8_LAS unsigned char* lds, const Gemm g, const Sched& S, const Epi& E) {
;     ...
;             PG8_LDB(B0, 0, 0); PG8_LDB(B1, 0, 1); PG8_SCHED; PG8_LDA(At, 0, 0); PG8_STAGE(PG8_SA(1, 1), a1 + hstep, voffA);
;             PG8_WAIT_V(8); PG8_WAIT_L(0); PG8_BAR; PG8_MMA(0, 0, At, B0); PG8_MMA(0, 1, At, B1); PG8_BAR; PG8_SCHED;
;             PG8_LDA(At, 0, 1); PG8_STAGE(PG8_SB(0, 0), b2, voffB); PG8_STAGE(PG8_SB(0, 1), b2 + hstep, voffB); PG8_STAGE(PG8_SA(0, 0), a2, voffA);
;             PG8_WAIT_V(8); PG8_WAIT_L(0); PG8_BAR; PG8_MMA(1, 0, At, B0); PG8_MMA(1, 1, At, B1); PG8_BAR; PG8_SCHED;
.LBB0_283:
	ds_read_b128 v[148:151], v187
	ds_read_b128 v[152:155], v187 offset:1024
	ds_read_b128 v[156:159], v187 offset:2048
	ds_read_b128 v[160:163], v187 offset:3072
	ds_read_b128 v[164:167], v183
	ds_read_b128 v[168:171], v183 offset:1024
	ds_read_b128 v[192:195], v183 offset:2048
	ds_read_b128 v[196:199], v183 offset:3072
	s_add_u32 s6, s10, s4
	s_addc_u32 s7, s11, s5
	s_add_u32 s6, s6, 0xc000100
	s_addc_u32 s7, s7, 0
	s_add_u32 s53, s35, s4
	s_addc_u32 s54, s36, s5
	s_cmpk_eq_i32 s4, 0x700
	s_cselect_b32 s9, s19, s7
	s_cselect_b32 s8, s18, s6
	s_cselect_b32 s7, s29, s54
	s_cselect_b32 s6, s34, s53
	v_lshl_add_u64 v[172:173], v[144:145], 0, s[4:5]
	s_add_i32 m0, s3, 0xc000
	ds_read_b128 v[200:203], v184
	ds_read_b128 v[204:207], v184 offset:1024
	ds_read_b128 v[208:211], v184 offset:2048
	ds_read_b128 v[212:215], v184 offset:3072
	ds_read_b128 v[216:219], v184 offset:4096
	ds_read_b128 v[220:223], v184 offset:5120
	ds_read_b128 v[224:227], v184 offset:6144
	ds_read_b128 v[228:231], v184 offset:7168
	global_load_lds_dwordx4 v[172:173], off
	v_lshl_add_u64 v[172:173], v[146:147], 0, s[4:5]
	s_add_i32 m0, s3, 0xe000
	s_nop 0
	global_load_lds_dwordx4 v[172:173], off
	s_waitcnt vmcnt(8)
	s_waitcnt lgkmcnt(0)
	s_barrier
	s_setprio 1
	s_waitcnt lgkmcnt(0)
	v_mfma_f32_16x16x32_bf16 v[124:127], v[148:151], v[200:203], v[124:127]
	v_mfma_f32_16x16x32_bf16 v[120:123], v[156:159], v[200:203], v[120:123]
	v_mfma_f32_16x16x32_bf16 v[108:111], v[148:151], v[208:211], v[108:111]
	v_mfma_f32_16x16x32_bf16 v[104:107], v[156:159], v[208:211], v[104:107]
	v_mfma_f32_16x16x32_bf16 v[92:95], v[148:151], v[216:219], v[92:95]
	v_mfma_f32_16x16x32_bf16 v[88:91], v[156:159], v[216:219], v[88:91]
	v_mfma_f32_16x16x32_bf16 v[76:79], v[148:151], v[224:227], v[76:79]
	v_mfma_f32_16x16x32_bf16 v[72:75], v[156:159], v[224:227], v[72:75]
	v_mfma_f32_16x16x32_bf16 v[124:127], v[152:155], v[204:207], v[124:127]
	v_mfma_f32_16x16x32_bf16 v[120:123], v[160:163], v[204:207], v[120:123]
	v_mfma_f32_16x16x32_bf16 v[108:111], v[152:155], v[212:215], v[108:111]
	v_mfma_f32_16x16x32_bf16 v[104:107], v[160:163], v[212:215], v[104:107]
	v_mfma_f32_16x16x32_bf16 v[92:95], v[152:155], v[220:223], v[92:95]
	v_mfma_f32_16x16x32_bf16 v[88:91], v[160:163], v[220:223], v[88:91]
	v_mfma_f32_16x16x32_bf16 v[76:79], v[152:155], v[228:231], v[76:79]
	v_mfma_f32_16x16x32_bf16 v[72:75], v[160:163], v[228:231], v[72:75]
	v_mfma_f32_16x16x32_bf16 v[116:119], v[164:167], v[200:203], v[116:119]
	v_mfma_f32_16x16x32_bf16 v[112:115], v[192:195], v[200:203], v[112:115]
	v_mfma_f32_16x16x32_bf16 v[100:103], v[164:167], v[208:211], v[100:103]
	v_mfma_f32_16x16x32_bf16 v[96:99], v[192:195], v[208:211], v[96:99]
	v_mfma_f32_16x16x32_bf16 v[84:87], v[164:167], v[216:219], v[84:87]
	v_mfma_f32_16x16x32_bf16 v[80:83], v[192:195], v[216:219], v[80:83]
	v_mfma_f32_16x16x32_bf16 v[68:71], v[164:167], v[224:227], v[68:71]
	v_mfma_f32_16x16x32_bf16 v[64:67], v[192:195], v[224:227], v[64:67]
	v_mfma_f32_16x16x32_bf16 v[116:119], v[168:171], v[204:207], v[116:119]
	v_mfma_f32_16x16x32_bf16 v[112:115], v[196:199], v[204:207], v[112:115]
	v_mfma_f32_16x16x32_bf16 v[100:103], v[168:171], v[212:215], v[100:103]
	v_mfma_f32_16x16x32_bf16 v[96:99], v[196:199], v[212:215], v[96:99]
	v_mfma_f32_16x16x32_bf16 v[84:87], v[168:171], v[220:223], v[84:87]
	v_mfma_f32_16x16x32_bf16 v[80:83], v[196:199], v[220:223], v[80:83]
	v_mfma_f32_16x16x32_bf16 v[68:71], v[168:171], v[228:231], v[68:71]
	v_mfma_f32_16x16x32_bf16 v[64:67], v[196:199], v[228:231], v[64:67]
	s_setprio 0
	s_barrier
	s_add_i32 s53, s51, s38
	v_lshl_add_u64 v[172:173], s[6:7], 0, v[138:139]
	s_mov_b32 m0, s53
	ds_read_b128 v[200:203], v184 offset:16384
	ds_read_b128 v[204:207], v184 offset:17408
	ds_read_b128 v[208:211], v184 offset:18432
	ds_read_b128 v[212:215], v184 offset:19456
	ds_read_b128 v[216:219], v184 offset:20480
	ds_read_b128 v[220:223], v184 offset:21504
	ds_read_b128 v[224:227], v184 offset:22528
	ds_read_b128 v[228:231], v184 offset:23552
	global_load_lds_dwordx4 v[172:173], off
	s_add_i32 m0, s53, 0x2000
	s_add_u32 s54, s6, 0x40000
	v_lshl_add_u64 v[188:189], s[6:7], 0, v[134:135]
	s_addc_u32 s55, s7, 0
	s_add_i32 s53, s48, s38
	global_load_lds_dwordx4 v[188:189], off
	v_lshl_add_u64 v[232:233], s[54:55], 0, v[138:139]
	s_mov_b32 m0, s53
	v_lshl_add_u64 v[234:235], s[8:9], 0, v[136:137]
	global_load_lds_dwordx4 v[232:233], off
	v_lshl_add_u64 v[232:233], s[54:55], 0, v[134:135]
	s_add_i32 m0, s53, 0x2000
	s_nop 0
	global_load_lds_dwordx4 v[232:233], off
	v_lshl_add_u64 v[232:233], s[8:9], 0, v[140:141]
	s_mov_b32 m0, s3
	s_nop 0
	global_load_lds_dwordx4 v[232:233], off
	s_mov_b32 m0, s39
	s_nop 0
	global_load_lds_dwordx4 v[234:235], off
	s_waitcnt vmcnt(8)
	s_waitcnt lgkmcnt(0)
	s_barrier
; #define PG8_STAGE(bufoff, gbase, voff) do { _Pragma("unroll") for (int _i = 0; _i < 2; ++_i) \
;         __builtin_amdgcn_global_load_lds((const unsigned*)((const char*)(gbase) + (voff)[_i]), (PG8_LAS unsigned*)(lds + (bufoff) + ldsw + _i * 8192), 16, 0, 0); } while (0)
; #define PG8_LDA(dst, b, h) do { _Pragma("unroll") for (int m = 0; m < 4; ++m) _Pragma("unroll") for (int k = 0; k < 2; ++k) dst[m][k] = *(const PG8_LAS bf16x8*)(lds + PG8_SA(b, h) + aoff + m * 2048 + k * 1024); } while (0)
; #define PG8_LDB(dst, b, h) do { _Pragma("unroll") for (int n = 0; n < 2; ++n) _Pragma("unroll") for (int k = 0; k < 2; ++k) dst[n][k] = *(const PG8_LAS bf16x8*)(lds + PG8_SB(b, h) + boff + n * 2048 + k * 1024); } while (0)
; #define PG8_MMA(ai, bj, At, Bt) do { __builtin_amdgcn_s_setprio(1); _Pragma("unroll") for (int m = 0; m < 4; ++m) _Pragma("unroll") for (int n = 0; n < 2; ++n) _Pragma("unroll") for (int k = 0; k < 2; ++k) \
;         acc[ai][bj][m][n] = __builtin_amdgcn_mfma_f32_16x16x32_bf16(Bt[n][k], At[m][k], acc[ai][bj][m][n], 0, 0, 0); __builtin_amdgcn_s_setprio(0); } while (0)
; #define PG8_WAIT_V(n) asm volatile("s_waitcnt vmcnt(" #n ")" ::: "memory")
; #define PG8_WAIT_L(n) asm volatile("s_waitcnt lgkmcnt(" #n ")" ::: "memory")
; #define PG8_BAR __builtin_amdgcn_s_barrier()
; #define PG8_SCHED __builtin_amdgcn_sched_barrier(0)
; template <class Epi, class Sched, bool ALIGN_EPI = false, bool SP2 = false>
; __device__ __forceinline__ void gemm_phase(PG8_LAS unsigned char* lds, const Gemm g, const Sched& S, const Epi& E) {
;     ...
;             PG8_WAIT_V(8); PG8_WAIT_L(0); PG8_BAR; PG8_MMA(1, 0, At, B0); PG8_MMA(1, 1, At, B1); PG8_BAR; PG8_SCHED;
;             PG8_LDB(B0, 1, 0); PG8_LDB(B1, 1, 1); PG8_SCHED; PG8_LDA(At, 1, 0); PG8_STAGE(PG8_SA(0, 1), a2 + hstep, voffA);
;             PG8_WAIT_V(8); PG8_WAIT_L(0); PG8_BAR; PG8_MMA(0, 0, At, B0); PG8_MMA(0, 1, At, B1); PG8_BAR; PG8_SCHED;
	s_setprio 1
	s_waitcnt lgkmcnt(0)
	v_mfma_f32_16x16x32_bf16 v[60:63], v[148:151], v[200:203], v[60:63]
	v_mfma_f32_16x16x32_bf16 v[56:59], v[156:159], v[200:203], v[56:59]
	v_mfma_f32_16x16x32_bf16 v[44:47], v[148:151], v[208:211], v[44:47]
	v_mfma_f32_16x16x32_bf16 v[40:43], v[156:159], v[208:211], v[40:43]
	v_mfma_f32_16x16x32_bf16 v[28:31], v[148:151], v[216:219], v[28:31]
	v_mfma_f32_16x16x32_bf16 v[24:27], v[156:159], v[216:219], v[24:27]
	v_mfma_f32_16x16x32_bf16 v[12:15], v[148:151], v[224:227], v[12:15]
	v_mfma_f32_16x16x32_bf16 v[8:11], v[156:159], v[224:227], v[8:11]
	v_mfma_f32_16x16x32_bf16 v[60:63], v[152:155], v[204:207], v[60:63]
	v_mfma_f32_16x16x32_bf16 v[56:59], v[160:163], v[204:207], v[56:59]
	v_mfma_f32_16x16x32_bf16 v[44:47], v[152:155], v[212:215], v[44:47]
	v_mfma_f32_16x16x32_bf16 v[40:43], v[160:163], v[212:215], v[40:43]
	v_mfma_f32_16x16x32_bf16 v[28:31], v[152:155], v[220:223], v[28:31]
	v_mfma_f32_16x16x32_bf16 v[24:27], v[160:163], v[220:223], v[24:27]
	v_mfma_f32_16x16x32_bf16 v[12:15], v[152:155], v[228:231], v[12:15]
	v_mfma_f32_16x16x32_bf16 v[8:11], v[160:163], v[228:231], v[8:11]
	v_mfma_f32_16x16x32_bf16 v[52:55], v[164:167], v[200:203], v[52:55]
	v_mfma_f32_16x16x32_bf16 v[48:51], v[192:195], v[200:203], v[48:51]
	v_mfma_f32_16x16x32_bf16 v[36:39], v[164:167], v[208:211], v[36:39]
	v_mfma_f32_16x16x32_bf16 v[32:35], v[192:195], v[208:211], v[32:35]
	v_mfma_f32_16x16x32_bf16 v[20:23], v[164:167], v[216:219], v[20:23]
	v_mfma_f32_16x16x32_bf16 v[16:19], v[192:195], v[216:219], v[16:19]
	v_mfma_f32_16x16x32_bf16 v[4:7], v[164:167], v[224:227], v[4:7]
	v_mfma_f32_16x16x32_bf16 v[0:3], v[192:195], v[224:227], v[0:3]
	v_mfma_f32_16x16x32_bf16 v[52:55], v[168:171], v[204:207], v[52:55]
	v_mfma_f32_16x16x32_bf16 v[48:51], v[196:199], v[204:207], v[48:51]
	v_mfma_f32_16x16x32_bf16 v[36:39], v[168:171], v[212:215], v[36:39]
	v_mfma_f32_16x16x32_bf16 v[32:35], v[196:199], v[212:215], v[32:35]
	v_mfma_f32_16x16x32_bf16 v[20:23], v[168:171], v[220:223], v[20:23]
	v_mfma_f32_16x16x32_bf16 v[16:19], v[196:199], v[220:223], v[16:19]
	v_mfma_f32_16x16x32_bf16 v[4:7], v[168:171], v[228:231], v[4:7]
	v_mfma_f32_16x16x32_bf16 v[0:3], v[196:199], v[228:231], v[0:3]
	s_setprio 0
	s_barrier
	s_add_i32 s53, 0, 0x18000
	s_add_i32 s54, 0, 0x1c000
	v_add_u32_e32 v160, s53, v133
	v_add_u32_e32 v191, s54, v133
	ds_read_b128 v[148:151], v160
	ds_read_b128 v[152:155], v160 offset:1024
	ds_read_b128 v[156:159], v160 offset:2048
	ds_read_b128 v[160:163], v160 offset:3072
	ds_read_b128 v[164:167], v191
	ds_read_b128 v[168:171], v191 offset:1024
	ds_read_b128 v[192:195], v191 offset:2048
	ds_read_b128 v[196:199], v191 offset:3072
	s_add_u32 s8, s8, 0x40000
	s_addc_u32 s9, s9, 0
	s_mov_b32 m0, s40
	v_lshl_add_u64 v[236:237], s[8:9], 0, v[140:141]
	ds_read_b128 v[200:203], v184 offset:32768
	ds_read_b128 v[204:207], v184 offset:33792
	ds_read_b128 v[208:211], v184 offset:34816
	ds_read_b128 v[212:215], v184 offset:35840
	ds_read_b128 v[216:219], v184 offset:36864
	ds_read_b128 v[220:223], v184 offset:37888
	ds_read_b128 v[224:227], v184 offset:38912
	ds_read_b128 v[228:231], v184 offset:39936
	global_load_lds_dwordx4 v[236:237], off
	v_lshl_add_u64 v[236:237], s[8:9], 0, v[136:137]
	s_mov_b32 m0, s41
	s_nop 0
	global_load_lds_dwordx4 v[236:237], off
	s_waitcnt vmcnt(8)
	s_waitcnt lgkmcnt(0)
	s_barrier
	s_setprio 1
	s_waitcnt lgkmcnt(0)
	v_mfma_f32_16x16x32_bf16 v[124:127], v[148:151], v[200:203], v[124:127]
	v_mfma_f32_16x16x32_bf16 v[120:123], v[156:159], v[200:203], v[120:123]
	v_mfma_f32_16x16x32_bf16 v[108:111], v[148:151], v[208:211], v[108:111]
	v_mfma_f32_16x16x32_bf16 v[104:107], v[156:159], v[208:211], v[104:107]
	v_mfma_f32_16x16x32_bf16 v[92:95], v[148:151], v[216:219], v[92:95]
	v_mfma_f32_16x16x32_bf16 v[88:91], v[156:159], v[216:219], v[88:91]
	v_mfma_f32_16x16x32_bf16 v[76:79], v[148:151], v[224:227], v[76:79]
	v_mfma_f32_16x16x32_bf16 v[72:75], v[156:159], v[224:227], v[72:75]
	v_mfma_f32_16x16x32_bf16 v[124:127], v[152:155], v[204:207], v[124:127]
	v_mfma_f32_16x16x32_bf16 v[120:123], v[160:163], v[204:207], v[120:123]
	v_mfma_f32_16x16x32_bf16 v[108:111], v[152:155], v[212:215], v[108:111]
	v_mfma_f32_16x16x32_bf16 v[104:107], v[160:163], v[212:215], v[104:107]
	v_mfma_f32_16x16x32_bf16 v[92:95], v[152:155], v[220:223], v[92:95]
	v_mfma_f32_16x16x32_bf16 v[88:91], v[160:163], v[220:223], v[88:91]
	v_mfma_f32_16x16x32_bf16 v[76:79], v[152:155], v[228:231], v[76:79]
	v_mfma_f32_16x16x32_bf16 v[72:75], v[160:163], v[228:231], v[72:75]
	v_mfma_f32_16x16x32_bf16 v[116:119], v[164:167], v[200:203], v[116:119]
	v_mfma_f32_16x16x32_bf16 v[112:115], v[192:195], v[200:203], v[112:115]
	v_mfma_f32_16x16x32_bf16 v[100:103], v[164:167], v[208:211], v[100:103]
	v_mfma_f32_16x16x32_bf16 v[96:99], v[192:195], v[208:211], v[96:99]
	v_mfma_f32_16x16x32_bf16 v[84:87], v[164:167], v[216:219], v[84:87]
	v_mfma_f32_16x16x32_bf16 v[80:83], v[192:195], v[216:219], v[80:83]
	v_mfma_f32_16x16x32_bf16 v[68:71], v[164:167], v[224:227], v[68:71]
	v_mfma_f32_16x16x32_bf16 v[64:67], v[192:195], v[224:227], v[64:67]
	v_mfma_f32_16x16x32_bf16 v[116:119], v[168:171], v[204:207], v[116:119]
	v_mfma_f32_16x16x32_bf16 v[112:115], v[196:199], v[204:207], v[112:115]
	v_mfma_f32_16x16x32_bf16 v[100:103], v[168:171], v[212:215], v[100:103]
	v_mfma_f32_16x16x32_bf16 v[96:99], v[196:199], v[212:215], v[96:99]
	v_mfma_f32_16x16x32_bf16 v[84:87], v[168:171], v[220:223], v[84:87]
	v_mfma_f32_16x16x32_bf16 v[80:83], v[196:199], v[220:223], v[80:83]
	v_mfma_f32_16x16x32_bf16 v[68:71], v[168:171], v[228:231], v[68:71]
	v_mfma_f32_16x16x32_bf16 v[64:67], v[196:199], v[228:231], v[64:67]
	s_setprio 0
	s_barrier
; #define PG8_STAGE(bufoff, gbase, voff) do { _Pragma("unroll") for (int _i = 0; _i < 2; ++_i) \
;         __builtin_amdgcn_global_load_lds((const unsigned*)((const char*)(gbase) + (voff)[_i]), (PG8_LAS unsigned*)(lds + (bufoff) + ldsw + _i * 8192), 16, 0, 0); } while (0)
; #define PG8_LDA(dst, b, h) do { _Pragma("unroll") for (int m = 0; m < 4; ++m) _Pragma("unroll") for (int k = 0; k < 2; ++k) dst[m][k] = *(const PG8_LAS bf16x8*)(lds + PG8_SA(b, h) + aoff + m * 2048 + k * 1024); } while (0)
; #define PG8_MMA(ai, bj, At, Bt) do { __builtin_amdgcn_s_setprio(1); _Pragma("unroll") for (int m = 0; m < 4; ++m) _Pragma("unroll") for (int n = 0; n < 2; ++n) _Pragma("unroll") for (int k = 0; k < 2; ++k) \
;         acc[ai][bj][m][n] = __builtin_amdgcn_mfma_f32_16x16x32_bf16(Bt[n][k], At[m][k], acc[ai][bj][m][n], 0, 0, 0); __builtin_amdgcn_s_setprio(0); } while (0)
; #define PG8_WAIT_V(n) asm volatile("s_waitcnt vmcnt(" #n ")" ::: "memory")
; #define PG8_WAIT_L(n) asm volatile("s_waitcnt lgkmcnt(" #n ")" ::: "memory")
; #define PG8_BAR __builtin_amdgcn_s_barrier()
; #define PG8_SCHED __builtin_amdgcn_sched_barrier(0)
; template <class Epi, class Sched, bool ALIGN_EPI = false, bool SP2 = false>
; __device__ __forceinline__ void gemm_phase(PG8_LAS unsigned char* lds, const Gemm g, const Sched& S, const Epi& E) {
;     ...
;         for (int t = 0; t < nt; t += 2) {
;             const bool last = (t == nt - 2);
;             const char* a1 = cA + (size_t)(t + 1) * kstep;
;             const char* a2 = last ? nA : cA + (size_t)(t + 2) * kstep; const char* b2 = last ? nB : cB + (size_t)(t + 2) * kstep;
;             const char* a3 = a2 + kstep; const char* b3 = b2 + kstep;
;             if (last && has_next) S.a_ready(nxt);
;     ...
;             PG8_LDA(At, 1, 1); PG8_STAGE(PG8_SB(1, 0), b3, voffB); PG8_STAGE(PG8_SB(1, 1), b3 + hstep, voffB); PG8_STAGE(PG8_SA(1, 0), a3, voffA);
;             PG8_WAIT_V(8); PG8_WAIT_L(0); PG8_BAR; PG8_MMA(1, 0, At, B0); PG8_MMA(1, 1, At, B1); PG8_BAR; PG8_SCHED;
	s_add_i32 s8, s53, s38
	v_lshl_add_u64 v[172:173], v[172:173], 0, s[24:25]
	s_mov_b32 m0, s8
	ds_read_b128 v[200:203], v184 offset:49152
	ds_read_b128 v[204:207], v184 offset:50176
	ds_read_b128 v[208:211], v184 offset:51200
	ds_read_b128 v[212:215], v184 offset:52224
	ds_read_b128 v[216:219], v184 offset:53248
	ds_read_b128 v[220:223], v184 offset:54272
	ds_read_b128 v[224:227], v184 offset:55296
	ds_read_b128 v[228:231], v184 offset:56320
	global_load_lds_dwordx4 v[172:173], off
	s_add_i32 m0, s8, 0x2000
	s_add_u32 s6, s6, 0x40080
	v_lshl_add_u64 v[172:173], v[188:189], 0, s[24:25]
	s_addc_u32 s7, s7, 0
	s_add_i32 s8, s54, s38
	global_load_lds_dwordx4 v[172:173], off
	v_lshl_add_u64 v[172:173], s[6:7], 0, v[138:139]
	s_mov_b32 m0, s8
	s_nop 0
	global_load_lds_dwordx4 v[172:173], off
	v_lshl_add_u64 v[172:173], s[6:7], 0, v[134:135]
	s_add_i32 m0, s8, 0x2000
	s_nop 0
	global_load_lds_dwordx4 v[172:173], off
	v_lshl_add_u64 v[172:173], v[232:233], 0, s[24:25]
	s_mov_b32 m0, s43
	s_nop 0
	global_load_lds_dwordx4 v[172:173], off
	v_lshl_add_u64 v[172:173], v[234:235], 0, s[24:25]
	s_mov_b32 m0, s44
	s_nop 0
	global_load_lds_dwordx4 v[172:173], off
	s_waitcnt vmcnt(8)
	s_waitcnt lgkmcnt(0)
	s_barrier
	s_setprio 1
	s_waitcnt lgkmcnt(0)
	v_mfma_f32_16x16x32_bf16 v[60:63], v[148:151], v[200:203], v[60:63]
	v_mfma_f32_16x16x32_bf16 v[56:59], v[156:159], v[200:203], v[56:59]
	v_mfma_f32_16x16x32_bf16 v[44:47], v[148:151], v[208:211], v[44:47]
	v_mfma_f32_16x16x32_bf16 v[40:43], v[156:159], v[208:211], v[40:43]
	v_mfma_f32_16x16x32_bf16 v[28:31], v[148:151], v[216:219], v[28:31]
	v_mfma_f32_16x16x32_bf16 v[24:27], v[156:159], v[216:219], v[24:27]
	v_mfma_f32_16x16x32_bf16 v[12:15], v[148:151], v[224:227], v[12:15]
	v_mfma_f32_16x16x32_bf16 v[8:11], v[156:159], v[224:227], v[8:11]
	v_mfma_f32_16x16x32_bf16 v[60:63], v[152:155], v[204:207], v[60:63]
	v_mfma_f32_16x16x32_bf16 v[56:59], v[160:163], v[204:207], v[56:59]
	v_mfma_f32_16x16x32_bf16 v[44:47], v[152:155], v[212:215], v[44:47]
	v_mfma_f32_16x16x32_bf16 v[40:43], v[160:163], v[212:215], v[40:43]
	v_mfma_f32_16x16x32_bf16 v[28:31], v[152:155], v[220:223], v[28:31]
	v_mfma_f32_16x16x32_bf16 v[24:27], v[160:163], v[220:223], v[24:27]
	v_mfma_f32_16x16x32_bf16 v[12:15], v[152:155], v[228:231], v[12:15]
	v_mfma_f32_16x16x32_bf16 v[8:11], v[160:163], v[228:231], v[8:11]
	v_mfma_f32_16x16x32_bf16 v[52:55], v[164:167], v[200:203], v[52:55]
	v_mfma_f32_16x16x32_bf16 v[48:51], v[192:195], v[200:203], v[48:51]
	v_mfma_f32_16x16x32_bf16 v[36:39], v[164:167], v[208:211], v[36:39]
	v_mfma_f32_16x16x32_bf16 v[32:35], v[192:195], v[208:211], v[32:35]
	v_mfma_f32_16x16x32_bf16 v[20:23], v[164:167], v[216:219], v[20:23]
	v_mfma_f32_16x16x32_bf16 v[16:19], v[192:195], v[216:219], v[16:19]
	v_mfma_f32_16x16x32_bf16 v[4:7], v[164:167], v[224:227], v[4:7]
	v_mfma_f32_16x16x32_bf16 v[0:3], v[192:195], v[224:227], v[0:3]
	v_mfma_f32_16x16x32_bf16 v[52:55], v[168:171], v[204:207], v[52:55]
	v_mfma_f32_16x16x32_bf16 v[48:51], v[196:199], v[204:207], v[48:51]
	v_mfma_f32_16x16x32_bf16 v[36:39], v[168:171], v[212:215], v[36:39]
	v_mfma_f32_16x16x32_bf16 v[32:35], v[196:199], v[212:215], v[32:35]
	v_mfma_f32_16x16x32_bf16 v[20:23], v[168:171], v[220:223], v[20:23]
	v_mfma_f32_16x16x32_bf16 v[16:19], v[196:199], v[220:223], v[16:19]
	v_mfma_f32_16x16x32_bf16 v[4:7], v[168:171], v[228:231], v[4:7]
	v_mfma_f32_16x16x32_bf16 v[0:3], v[196:199], v[228:231], v[0:3]
	s_setprio 0
	s_barrier
	s_add_i32 s37, s37, 2
	s_add_u32 s4, s4, 0x100
	s_addc_u32 s5, s5, 0
	s_cmp_gt_u32 s37, 13
	s_cbranch_scc0 .LBB0_283
	s_and_b64 vcc, exec, s[26:27]
	s_cbranch_vccz .LBB0_286
	s_barrier

; #define PG8_STAGE(bufoff, gbase, voff) do { _Pragma("unroll") for (int _i = 0; _i < 2; ++_i) \
;         __builtin_amdgcn_global_load_lds((const unsigned*)((const char*)(gbase) + (voff)[_i]), (PG8_LAS unsigned*)(lds + (bufoff) + ldsw + _i * 8192), 16, 0, 0); } while (0)
; #define PG8_LDA(dst, b, h) do { _Pragma("unroll") for (int m = 0; m < 4; ++m) _Pragma("unroll") for (int k = 0; k < 2; ++k) dst[m][k] = *(const PG8_LAS bf16x8*)(lds + PG8_SA(b, h) + aoff + m * 2048 + k * 1024); } while (0)
; #define PG8_LDB(dst, b, h) do { _Pragma("unroll") for (int n = 0; n < 2; ++n) _Pragma("unroll") for (int k = 0; k < 2; ++k) dst[n][k] = *(const PG8_LAS bf16x8*)(lds + PG8_SB(b, h) + boff + n * 2048 + k * 1024); } while (0)
; #define PG8_MMA(ai, bj, At, Bt) do { __builtin_amdgcn_s_setprio(1); _Pragma("unroll") for (int m = 0; m < 4; ++m) _Pragma("unroll") for (int n = 0; n < 2; ++n) _Pragma("unroll") for (int k = 0; k < 2; ++k) \
;         acc[ai][bj][m][n] = __builtin_amdgcn_mfma_f32_16x16x32_bf16(Bt[n][k], At[m][k], acc[ai][bj][m][n], 0, 0, 0); __builtin_amdgcn_s_setprio(0); } while (0)
; #define PG8_WAIT_V(n) asm volatile("s_waitcnt vmcnt(" #n ")" ::: "memory")
; #define PG8_WAIT_L(n) asm volatile("s_waitcnt lgkmcnt(" #n ")" ::: "memory")
; #define PG8_BAR __builtin_amdgcn_s_barrier()
; #define PG8_SCHED __builtin_amdgcn_sched_barrier(0)
; template <class Epi, class Sched, bool ALIGN_EPI = false, bool SP2 = false>
; __device__ __forceinline__ void gemm_phase(PG8_LAS unsigned char* lds, const Gemm g, const Sched& S, const Epi& E) {
;     ...
;             PG8_LDB(B0, 0, 0); PG8_LDB(B1, 0, 1); PG8_SCHED; PG8_LDA(At, 0, 0); PG8_STAGE(PG8_SA(1, 1), a1 + hstep, voffA);
;             PG8_WAIT_V(8); PG8_WAIT_L(0); PG8_BAR; PG8_MMA(0, 0, At, B0); PG8_MMA(0, 1, At, B1); PG8_BAR; PG8_SCHED;
;             PG8_LDA(At, 0, 1); PG8_STAGE(PG8_SB(0, 0), b2, voffB); PG8_STAGE(PG8_SB(0, 1), b2 + hstep, voffB); PG8_STAGE(PG8_SA(0, 0), a2, voffA);
;             PG8_WAIT_V(8); PG8_WAIT_L(0); PG8_BAR; PG8_MMA(1, 0, At, B0); PG8_MMA(1, 1, At, B1); PG8_BAR; PG8_SCHED;
.LBB0_592:
	s_add_u32 s4, s10, 0xfffc0080
	s_addc_u32 s5, s11, -1
	s_add_i32 s18, 0, 0x10000
	s_cmp_eq_u32 s64, 12
	s_cselect_b32 s15, s29, s5
	s_cselect_b32 s14, s38, s4
	s_cselect_b32 s13, s27, s55
	s_cselect_b32 s12, s39, s54
	s_add_i32 s4, 0, 0x14000
	v_add_u32_e32 v176, s18, v202
	v_add_u32_e32 v188, s4, v202
	ds_read_b128 v[164:167], v176
	ds_read_b128 v[168:171], v176 offset:1024
	ds_read_b128 v[172:175], v176 offset:2048
	ds_read_b128 v[176:179], v176 offset:3072
	ds_read_b128 v[180:183], v188
	ds_read_b128 v[184:187], v188 offset:1024
	ds_read_b128 v[206:209], v188 offset:2048
	ds_read_b128 v[210:213], v188 offset:3072
	v_lshl_add_u64 v[188:189], s[10:11], 0, v[160:161]
	s_add_i32 m0, s43, 0xc000
	ds_read_b128 v[214:217], v204
	ds_read_b128 v[218:221], v204 offset:1024
	ds_read_b128 v[222:225], v204 offset:2048
	ds_read_b128 v[226:229], v204 offset:3072
	ds_read_b128 v[230:233], v204 offset:4096
	ds_read_b128 v[234:237], v204 offset:5120
	ds_read_b128 v[238:241], v204 offset:6144
	ds_read_b128 v[242:245], v204 offset:7168
	global_load_lds_dwordx4 v[188:189], off
	v_lshl_add_u64 v[188:189], s[10:11], 0, v[162:163]
	s_add_i32 m0, s43, 0xe000
	s_nop 0
	global_load_lds_dwordx4 v[188:189], off
	s_waitcnt vmcnt(8)
	s_waitcnt lgkmcnt(0)
	s_barrier
	s_setprio 1
	s_waitcnt lgkmcnt(0)
	v_mfma_f32_16x16x32_bf16 v[126:129], v[164:167], v[214:217], v[126:129]
	v_mfma_f32_16x16x32_bf16 v[122:125], v[172:175], v[214:217], v[122:125]
	v_mfma_f32_16x16x32_bf16 v[110:113], v[164:167], v[222:225], v[110:113]
	v_mfma_f32_16x16x32_bf16 v[106:109], v[172:175], v[222:225], v[106:109]
	v_mfma_f32_16x16x32_bf16 v[94:97], v[164:167], v[230:233], v[94:97]
	v_mfma_f32_16x16x32_bf16 v[90:93], v[172:175], v[230:233], v[90:93]
	v_mfma_f32_16x16x32_bf16 v[78:81], v[164:167], v[238:241], v[78:81]
	v_mfma_f32_16x16x32_bf16 v[74:77], v[172:175], v[238:241], v[74:77]
	v_mfma_f32_16x16x32_bf16 v[126:129], v[168:171], v[218:221], v[126:129]
	v_mfma_f32_16x16x32_bf16 v[122:125], v[176:179], v[218:221], v[122:125]
	v_mfma_f32_16x16x32_bf16 v[110:113], v[168:171], v[226:229], v[110:113]
	v_mfma_f32_16x16x32_bf16 v[106:109], v[176:179], v[226:229], v[106:109]
	v_mfma_f32_16x16x32_bf16 v[94:97], v[168:171], v[234:237], v[94:97]
	v_mfma_f32_16x16x32_bf16 v[90:93], v[176:179], v[234:237], v[90:93]
	v_mfma_f32_16x16x32_bf16 v[78:81], v[168:171], v[242:245], v[78:81]
	v_mfma_f32_16x16x32_bf16 v[74:77], v[176:179], v[242:245], v[74:77]
	v_mfma_f32_16x16x32_bf16 v[118:121], v[180:183], v[214:217], v[118:121]
	v_mfma_f32_16x16x32_bf16 v[114:117], v[206:209], v[214:217], v[114:117]
	v_mfma_f32_16x16x32_bf16 v[102:105], v[180:183], v[222:225], v[102:105]
	v_mfma_f32_16x16x32_bf16 v[98:101], v[206:209], v[222:225], v[98:101]
	v_mfma_f32_16x16x32_bf16 v[86:89], v[180:183], v[230:233], v[86:89]
	v_mfma_f32_16x16x32_bf16 v[82:85], v[206:209], v[230:233], v[82:85]
	v_mfma_f32_16x16x32_bf16 v[70:73], v[180:183], v[238:241], v[70:73]
	v_mfma_f32_16x16x32_bf16 v[66:69], v[206:209], v[238:241], v[66:69]
	v_mfma_f32_16x16x32_bf16 v[118:121], v[184:187], v[218:221], v[118:121]
	v_mfma_f32_16x16x32_bf16 v[114:117], v[210:213], v[218:221], v[114:117]
	v_mfma_f32_16x16x32_bf16 v[102:105], v[184:187], v[226:229], v[102:105]
	v_mfma_f32_16x16x32_bf16 v[98:101], v[210:213], v[226:229], v[98:101]
	v_mfma_f32_16x16x32_bf16 v[86:89], v[184:187], v[234:237], v[86:89]
	v_mfma_f32_16x16x32_bf16 v[82:85], v[210:213], v[234:237], v[82:85]
	v_mfma_f32_16x16x32_bf16 v[70:73], v[184:187], v[242:245], v[70:73]
	v_mfma_f32_16x16x32_bf16 v[66:69], v[210:213], v[242:245], v[66:69]
	s_setprio 0
	s_barrier
	s_add_i32 s5, s18, s42
	v_lshl_add_u64 v[188:189], s[12:13], 0, v[154:155]
	s_mov_b32 m0, s5
	ds_read_b128 v[214:217], v204 offset:16384
	ds_read_b128 v[218:221], v204 offset:17408
	ds_read_b128 v[222:225], v204 offset:18432
	ds_read_b128 v[226:229], v204 offset:19456
	ds_read_b128 v[230:233], v204 offset:20480
	ds_read_b128 v[234:237], v204 offset:21504
	ds_read_b128 v[238:241], v204 offset:22528
	ds_read_b128 v[242:245], v204 offset:23552
	global_load_lds_dwordx4 v[188:189], off
	s_add_i32 m0, s5, 0x2000
	s_add_u32 s78, s12, 0x40000
	v_lshl_add_u64 v[246:247], s[12:13], 0, v[150:151]
	s_addc_u32 s79, s13, 0
	s_add_i32 s4, s4, s42
	global_load_lds_dwordx4 v[246:247], off
	v_lshl_add_u64 v[248:249], s[78:79], 0, v[154:155]
	s_mov_b32 m0, s4
	v_lshl_add_u64 v[250:251], s[14:15], 0, v[152:153]
	global_load_lds_dwordx4 v[248:249], off
	v_lshl_add_u64 v[248:249], s[78:79], 0, v[150:151]
	s_add_i32 m0, s4, 0x2000
	s_nop 0
	global_load_lds_dwordx4 v[248:249], off
	v_lshl_add_u64 v[248:249], s[14:15], 0, v[156:157]
	s_mov_b32 m0, s43
	s_nop 0
	global_load_lds_dwordx4 v[248:249], off
	s_mov_b32 m0, s44
	s_nop 0
	global_load_lds_dwordx4 v[250:251], off
	s_waitcnt vmcnt(8)
	s_waitcnt lgkmcnt(0)
	s_barrier
; #define PG8_STAGE(bufoff, gbase, voff) do { _Pragma("unroll") for (int _i = 0; _i < 2; ++_i) \
;         __builtin_amdgcn_global_load_lds((const unsigned*)((const char*)(gbase) + (voff)[_i]), (PG8_LAS unsigned*)(lds + (bufoff) + ldsw + _i * 8192), 16, 0, 0); } while (0)
; #define PG8_LDA(dst, b, h) do { _Pragma("unroll") for (int m = 0; m < 4; ++m) _Pragma("unroll") for (int k = 0; k < 2; ++k) dst[m][k] = *(const PG8_LAS bf16x8*)(lds + PG8_SA(b, h) + aoff + m * 2048 + k * 1024); } while (0)
; #define PG8_LDB(dst, b, h) do { _Pragma("unroll") for (int n = 0; n < 2; ++n) _Pragma("unroll") for (int k = 0; k < 2; ++k) dst[n][k] = *(const PG8_LAS bf16x8*)(lds + PG8_SB(b, h) + boff + n * 2048 + k * 1024); } while (0)
; #define PG8_MMA(ai, bj, At, Bt) do { __builtin_amdgcn_s_setprio(1); _Pragma("unroll") for (int m = 0; m < 4; ++m) _Pragma("unroll") for (int n = 0; n < 2; ++n) _Pragma("unroll") for (int k = 0; k < 2; ++k) \
;         acc[ai][bj][m][n] = __builtin_amdgcn_mfma_f32_16x16x32_bf16(Bt[n][k], At[m][k], acc[ai][bj][m][n], 0, 0, 0); __builtin_amdgcn_s_setprio(0); } while (0)
; #define PG8_WAIT_V(n) asm volatile("s_waitcnt vmcnt(" #n ")" ::: "memory")
; #define PG8_WAIT_L(n) asm volatile("s_waitcnt lgkmcnt(" #n ")" ::: "memory")
; #define PG8_BAR __builtin_amdgcn_s_barrier()
; #define PG8_SCHED __builtin_amdgcn_sched_barrier(0)
; template <class Epi, class Sched, bool ALIGN_EPI = false, bool SP2 = false>
; __device__ __forceinline__ void gemm_phase(PG8_LAS unsigned char* lds, const Gemm g, const Sched& S, const Epi& E) {
;     ...
;             PG8_WAIT_V(8); PG8_WAIT_L(0); PG8_BAR; PG8_MMA(1, 0, At, B0); PG8_MMA(1, 1, At, B1); PG8_BAR; PG8_SCHED;
;             PG8_LDB(B0, 1, 0); PG8_LDB(B1, 1, 1); PG8_SCHED; PG8_LDA(At, 1, 0); PG8_STAGE(PG8_SA(0, 1), a2 + hstep, voffA);
;             PG8_WAIT_V(8); PG8_WAIT_L(0); PG8_BAR; PG8_MMA(0, 0, At, B0); PG8_MMA(0, 1, At, B1); PG8_BAR; PG8_SCHED;
	s_setprio 1
	s_waitcnt lgkmcnt(0)
	v_mfma_f32_16x16x32_bf16 v[62:65], v[164:167], v[214:217], v[62:65]
	v_mfma_f32_16x16x32_bf16 v[58:61], v[172:175], v[214:217], v[58:61]
	v_mfma_f32_16x16x32_bf16 v[46:49], v[164:167], v[222:225], v[46:49]
	v_mfma_f32_16x16x32_bf16 v[42:45], v[172:175], v[222:225], v[42:45]
	v_mfma_f32_16x16x32_bf16 v[30:33], v[164:167], v[230:233], v[30:33]
	v_mfma_f32_16x16x32_bf16 v[26:29], v[172:175], v[230:233], v[26:29]
	v_mfma_f32_16x16x32_bf16 v[14:17], v[164:167], v[238:241], v[14:17]
	v_mfma_f32_16x16x32_bf16 v[10:13], v[172:175], v[238:241], v[10:13]
	v_mfma_f32_16x16x32_bf16 v[62:65], v[168:171], v[218:221], v[62:65]
	v_mfma_f32_16x16x32_bf16 v[58:61], v[176:179], v[218:221], v[58:61]
	v_mfma_f32_16x16x32_bf16 v[46:49], v[168:171], v[226:229], v[46:49]
	v_mfma_f32_16x16x32_bf16 v[42:45], v[176:179], v[226:229], v[42:45]
	v_mfma_f32_16x16x32_bf16 v[30:33], v[168:171], v[234:237], v[30:33]
	v_mfma_f32_16x16x32_bf16 v[26:29], v[176:179], v[234:237], v[26:29]
	v_mfma_f32_16x16x32_bf16 v[14:17], v[168:171], v[242:245], v[14:17]
	v_mfma_f32_16x16x32_bf16 v[10:13], v[176:179], v[242:245], v[10:13]
	v_mfma_f32_16x16x32_bf16 v[54:57], v[180:183], v[214:217], v[54:57]
	v_mfma_f32_16x16x32_bf16 v[50:53], v[206:209], v[214:217], v[50:53]
	v_mfma_f32_16x16x32_bf16 v[38:41], v[180:183], v[222:225], v[38:41]
	v_mfma_f32_16x16x32_bf16 v[34:37], v[206:209], v[222:225], v[34:37]
	v_mfma_f32_16x16x32_bf16 v[22:25], v[180:183], v[230:233], v[22:25]
	v_mfma_f32_16x16x32_bf16 v[18:21], v[206:209], v[230:233], v[18:21]
	v_mfma_f32_16x16x32_bf16 v[6:9], v[180:183], v[238:241], v[6:9]
	v_mfma_f32_16x16x32_bf16 v[2:5], v[206:209], v[238:241], v[2:5]
	v_mfma_f32_16x16x32_bf16 v[54:57], v[184:187], v[218:221], v[54:57]
	v_mfma_f32_16x16x32_bf16 v[50:53], v[210:213], v[218:221], v[50:53]
	v_mfma_f32_16x16x32_bf16 v[38:41], v[184:187], v[226:229], v[38:41]
	v_mfma_f32_16x16x32_bf16 v[34:37], v[210:213], v[226:229], v[34:37]
	v_mfma_f32_16x16x32_bf16 v[22:25], v[184:187], v[234:237], v[22:25]
	v_mfma_f32_16x16x32_bf16 v[18:21], v[210:213], v[234:237], v[18:21]
	v_mfma_f32_16x16x32_bf16 v[6:9], v[184:187], v[242:245], v[6:9]
	v_mfma_f32_16x16x32_bf16 v[2:5], v[210:213], v[242:245], v[2:5]
	s_setprio 0
	s_barrier
	s_add_i32 s4, 0, 0x18000
	s_add_i32 s5, 0, 0x1c000
	v_add_u32_e32 v176, s4, v202
	v_add_u32_e32 v205, s5, v202
	ds_read_b128 v[164:167], v176
	ds_read_b128 v[168:171], v176 offset:1024
	ds_read_b128 v[172:175], v176 offset:2048
	ds_read_b128 v[176:179], v176 offset:3072
	ds_read_b128 v[180:183], v205
	ds_read_b128 v[184:187], v205 offset:1024
	ds_read_b128 v[206:209], v205 offset:2048
	ds_read_b128 v[210:213], v205 offset:3072
	s_add_u32 s14, s14, 0x40000
	s_addc_u32 s15, s15, 0
	s_mov_b32 m0, s45
	v_lshl_add_u64 v[252:253], s[14:15], 0, v[156:157]
	ds_read_b128 v[214:217], v204 offset:32768
	ds_read_b128 v[218:221], v204 offset:33792
	ds_read_b128 v[222:225], v204 offset:34816
	ds_read_b128 v[226:229], v204 offset:35840
	ds_read_b128 v[230:233], v204 offset:36864
	ds_read_b128 v[234:237], v204 offset:37888
	ds_read_b128 v[238:241], v204 offset:38912
	ds_read_b128 v[242:245], v204 offset:39936
	global_load_lds_dwordx4 v[252:253], off
	v_lshl_add_u64 v[252:253], s[14:15], 0, v[152:153]
	s_mov_b32 m0, s46
	s_nop 0
	global_load_lds_dwordx4 v[252:253], off
	s_waitcnt vmcnt(8)
	s_waitcnt lgkmcnt(0)
	s_barrier
	s_setprio 1
	s_waitcnt lgkmcnt(0)
	v_mfma_f32_16x16x32_bf16 v[126:129], v[164:167], v[214:217], v[126:129]
	v_mfma_f32_16x16x32_bf16 v[122:125], v[172:175], v[214:217], v[122:125]
	v_mfma_f32_16x16x32_bf16 v[110:113], v[164:167], v[222:225], v[110:113]
	v_mfma_f32_16x16x32_bf16 v[106:109], v[172:175], v[222:225], v[106:109]
	v_mfma_f32_16x16x32_bf16 v[94:97], v[164:167], v[230:233], v[94:97]
	v_mfma_f32_16x16x32_bf16 v[90:93], v[172:175], v[230:233], v[90:93]
	v_mfma_f32_16x16x32_bf16 v[78:81], v[164:167], v[238:241], v[78:81]
	v_mfma_f32_16x16x32_bf16 v[74:77], v[172:175], v[238:241], v[74:77]
	v_mfma_f32_16x16x32_bf16 v[126:129], v[168:171], v[218:221], v[126:129]
	v_mfma_f32_16x16x32_bf16 v[122:125], v[176:179], v[218:221], v[122:125]
	v_mfma_f32_16x16x32_bf16 v[110:113], v[168:171], v[226:229], v[110:113]
	v_mfma_f32_16x16x32_bf16 v[106:109], v[176:179], v[226:229], v[106:109]
	v_mfma_f32_16x16x32_bf16 v[94:97], v[168:171], v[234:237], v[94:97]
	v_mfma_f32_16x16x32_bf16 v[90:93], v[176:179], v[234:237], v[90:93]
	v_mfma_f32_16x16x32_bf16 v[78:81], v[168:171], v[242:245], v[78:81]
	v_mfma_f32_16x16x32_bf16 v[74:77], v[176:179], v[242:245], v[74:77]
	v_mfma_f32_16x16x32_bf16 v[118:121], v[180:183], v[214:217], v[118:121]
	v_mfma_f32_16x16x32_bf16 v[114:117], v[206:209], v[214:217], v[114:117]
	v_mfma_f32_16x16x32_bf16 v[102:105], v[180:183], v[222:225], v[102:105]
	v_mfma_f32_16x16x32_bf16 v[98:101], v[206:209], v[222:225], v[98:101]
	v_mfma_f32_16x16x32_bf16 v[86:89], v[180:183], v[230:233], v[86:89]
	v_mfma_f32_16x16x32_bf16 v[82:85], v[206:209], v[230:233], v[82:85]
	v_mfma_f32_16x16x32_bf16 v[70:73], v[180:183], v[238:241], v[70:73]
	v_mfma_f32_16x16x32_bf16 v[66:69], v[206:209], v[238:241], v[66:69]
	v_mfma_f32_16x16x32_bf16 v[118:121], v[184:187], v[218:221], v[118:121]
	v_mfma_f32_16x16x32_bf16 v[114:117], v[210:213], v[218:221], v[114:117]
	v_mfma_f32_16x16x32_bf16 v[102:105], v[184:187], v[226:229], v[102:105]
	v_mfma_f32_16x16x32_bf16 v[98:101], v[210:213], v[226:229], v[98:101]
	v_mfma_f32_16x16x32_bf16 v[86:89], v[184:187], v[234:237], v[86:89]
	v_mfma_f32_16x16x32_bf16 v[82:85], v[210:213], v[234:237], v[82:85]
	v_mfma_f32_16x16x32_bf16 v[70:73], v[184:187], v[242:245], v[70:73]
	v_mfma_f32_16x16x32_bf16 v[66:69], v[210:213], v[242:245], v[66:69]
	s_setprio 0
	s_barrier
; #define PG8_STAGE(bufoff, gbase, voff) do { _Pragma("unroll") for (int _i = 0; _i < 2; ++_i) \
;         __builtin_amdgcn_global_load_lds((const unsigned*)((const char*)(gbase) + (voff)[_i]), (PG8_LAS unsigned*)(lds + (bufoff) + ldsw + _i * 8192), 16, 0, 0); } while (0)
; #define PG8_LDA(dst, b, h) do { _Pragma("unroll") for (int m = 0; m < 4; ++m) _Pragma("unroll") for (int k = 0; k < 2; ++k) dst[m][k] = *(const PG8_LAS bf16x8*)(lds + PG8_SA(b, h) + aoff + m * 2048 + k * 1024); } while (0)
; #define PG8_MMA(ai, bj, At, Bt) do { __builtin_amdgcn_s_setprio(1); _Pragma("unroll") for (int m = 0; m < 4; ++m) _Pragma("unroll") for (int n = 0; n < 2; ++n) _Pragma("unroll") for (int k = 0; k < 2; ++k) \
;         acc[ai][bj][m][n] = __builtin_amdgcn_mfma_f32_16x16x32_bf16(Bt[n][k], At[m][k], acc[ai][bj][m][n], 0, 0, 0); __builtin_amdgcn_s_setprio(0); } while (0)
; #define PG8_WAIT_V(n) asm volatile("s_waitcnt vmcnt(" #n ")" ::: "memory")
; #define PG8_WAIT_L(n) asm volatile("s_waitcnt lgkmcnt(" #n ")" ::: "memory")
; #define PG8_BAR __builtin_amdgcn_s_barrier()
; #define PG8_SCHED __builtin_amdgcn_sched_barrier(0)
; template <class Epi, class Sched, bool ALIGN_EPI = false, bool SP2 = false>
; __device__ __forceinline__ void gemm_phase(PG8_LAS unsigned char* lds, const Gemm g, const Sched& S, const Epi& E) {
;     ...
;         for (int t = 0; t < nt; t += 2) {
;             const bool last = (t == nt - 2);
;             const char* a1 = cA + (size_t)(t + 1) * kstep;
;             const char* a2 = last ? nA : cA + (size_t)(t + 2) * kstep; const char* b2 = last ? nB : cB + (size_t)(t + 2) * kstep;
;             const char* a3 = a2 + kstep; const char* b3 = b2 + kstep;
;             if (last && has_next) S.a_ready(nxt);
;     ...
;             PG8_LDA(At, 1, 1); PG8_STAGE(PG8_SB(1, 0), b3, voffB); PG8_STAGE(PG8_SB(1, 1), b3 + hstep, voffB); PG8_STAGE(PG8_SA(1, 0), a3, voffA);
;             PG8_WAIT_V(8); PG8_WAIT_L(0); PG8_BAR; PG8_MMA(1, 0, At, B0); PG8_MMA(1, 1, At, B1); PG8_BAR; PG8_SCHED;
	s_add_i32 s4, s4, s42
	v_lshl_add_u64 v[188:189], v[188:189], 0, s[62:63]
	s_mov_b32 m0, s4
	ds_read_b128 v[214:217], v204 offset:49152
	ds_read_b128 v[218:221], v204 offset:50176
	ds_read_b128 v[222:225], v204 offset:51200
	ds_read_b128 v[226:229], v204 offset:52224
	ds_read_b128 v[230:233], v204 offset:53248
	ds_read_b128 v[234:237], v204 offset:54272
	ds_read_b128 v[238:241], v204 offset:55296
	ds_read_b128 v[242:245], v204 offset:56320
	global_load_lds_dwordx4 v[188:189], off
	s_add_i32 m0, s4, 0x2000
	s_add_u32 s12, s12, 0x40080
	v_lshl_add_u64 v[188:189], v[246:247], 0, s[62:63]
	s_addc_u32 s13, s13, 0
	s_add_i32 s4, s5, s42
	global_load_lds_dwordx4 v[188:189], off
	v_lshl_add_u64 v[188:189], s[12:13], 0, v[154:155]
	s_mov_b32 m0, s4
	s_nop 0
	global_load_lds_dwordx4 v[188:189], off
	v_lshl_add_u64 v[188:189], s[12:13], 0, v[150:151]
	s_add_i32 m0, s4, 0x2000
	s_nop 0
	global_load_lds_dwordx4 v[188:189], off
	v_lshl_add_u64 v[188:189], v[248:249], 0, s[62:63]
	s_mov_b32 m0, s48
	s_nop 0
	global_load_lds_dwordx4 v[188:189], off
	v_lshl_add_u64 v[188:189], v[250:251], 0, s[62:63]
	s_mov_b32 m0, s49
	s_nop 0
	global_load_lds_dwordx4 v[188:189], off
	s_waitcnt vmcnt(8)
	s_waitcnt lgkmcnt(0)
	s_barrier
	s_setprio 1
	s_waitcnt lgkmcnt(0)
	v_mfma_f32_16x16x32_bf16 v[62:65], v[164:167], v[214:217], v[62:65]
	v_mfma_f32_16x16x32_bf16 v[58:61], v[172:175], v[214:217], v[58:61]
	v_mfma_f32_16x16x32_bf16 v[46:49], v[164:167], v[222:225], v[46:49]
	v_mfma_f32_16x16x32_bf16 v[42:45], v[172:175], v[222:225], v[42:45]
	v_mfma_f32_16x16x32_bf16 v[30:33], v[164:167], v[230:233], v[30:33]
	v_mfma_f32_16x16x32_bf16 v[26:29], v[172:175], v[230:233], v[26:29]
	v_mfma_f32_16x16x32_bf16 v[14:17], v[164:167], v[238:241], v[14:17]
	v_mfma_f32_16x16x32_bf16 v[10:13], v[172:175], v[238:241], v[10:13]
	v_mfma_f32_16x16x32_bf16 v[62:65], v[168:171], v[218:221], v[62:65]
	v_mfma_f32_16x16x32_bf16 v[58:61], v[176:179], v[218:221], v[58:61]
	v_mfma_f32_16x16x32_bf16 v[46:49], v[168:171], v[226:229], v[46:49]
	v_mfma_f32_16x16x32_bf16 v[42:45], v[176:179], v[226:229], v[42:45]
	v_mfma_f32_16x16x32_bf16 v[30:33], v[168:171], v[234:237], v[30:33]
	v_mfma_f32_16x16x32_bf16 v[26:29], v[176:179], v[234:237], v[26:29]
	v_mfma_f32_16x16x32_bf16 v[14:17], v[168:171], v[242:245], v[14:17]
	v_mfma_f32_16x16x32_bf16 v[10:13], v[176:179], v[242:245], v[10:13]
	v_mfma_f32_16x16x32_bf16 v[54:57], v[180:183], v[214:217], v[54:57]
	v_mfma_f32_16x16x32_bf16 v[50:53], v[206:209], v[214:217], v[50:53]
	v_mfma_f32_16x16x32_bf16 v[38:41], v[180:183], v[222:225], v[38:41]
	v_mfma_f32_16x16x32_bf16 v[34:37], v[206:209], v[222:225], v[34:37]
	v_mfma_f32_16x16x32_bf16 v[22:25], v[180:183], v[230:233], v[22:25]
	v_mfma_f32_16x16x32_bf16 v[18:21], v[206:209], v[230:233], v[18:21]
	v_mfma_f32_16x16x32_bf16 v[6:9], v[180:183], v[238:241], v[6:9]
	v_mfma_f32_16x16x32_bf16 v[2:5], v[206:209], v[238:241], v[2:5]
	v_mfma_f32_16x16x32_bf16 v[54:57], v[184:187], v[218:221], v[54:57]
	v_mfma_f32_16x16x32_bf16 v[50:53], v[210:213], v[218:221], v[50:53]
	v_mfma_f32_16x16x32_bf16 v[38:41], v[184:187], v[226:229], v[38:41]
	v_mfma_f32_16x16x32_bf16 v[34:37], v[210:213], v[226:229], v[34:37]
	v_mfma_f32_16x16x32_bf16 v[22:25], v[184:187], v[234:237], v[22:25]
	v_mfma_f32_16x16x32_bf16 v[18:21], v[210:213], v[234:237], v[18:21]
	v_mfma_f32_16x16x32_bf16 v[6:9], v[184:187], v[242:245], v[6:9]
	v_mfma_f32_16x16x32_bf16 v[2:5], v[210:213], v[242:245], v[2:5]
	s_setprio 0
	s_barrier
	s_add_i32 s64, s64, 2
	s_add_u32 s10, s10, 0x100
	s_addc_u32 s11, s11, 0
	s_add_u32 s54, s54, 0x100
	s_addc_u32 s55, s55, 0
	s_cmp_gt_u32 s64, 13
	s_cbranch_scc0 .LBB0_592
	s_and_b64 vcc, exec, s[24:25]
	s_cbranch_vccz .LBB0_595
	s_barrier

; #define PG8_STAGE(bufoff, gbase, voff) do { _Pragma("unroll") for (int _i = 0; _i < 2; ++_i) \
;         __builtin_amdgcn_global_load_lds((const unsigned*)((const char*)(gbase) + (voff)[_i]), (PG8_LAS unsigned*)(lds + (bufoff) + ldsw + _i * 8192), 16, 0, 0); } while (0)
; #define PG8_LDA(dst, b, h) do { _Pragma("unroll") for (int m = 0; m < 4; ++m) _Pragma("unroll") for (int k = 0; k < 2; ++k) dst[m][k] = *(const PG8_LAS bf16x8*)(lds + PG8_SA(b, h) + aoff + m * 2048 + k * 1024); } while (0)
; #define PG8_LDB(dst, b, h) do { _Pragma("unroll") for (int n = 0; n < 2; ++n) _Pragma("unroll") for (int k = 0; k < 2; ++k) dst[n][k] = *(const PG8_LAS bf16x8*)(lds + PG8_SB(b, h) + boff + n * 2048 + k * 1024); } while (0)
; #define PG8_MMA(ai, bj, At, Bt) do { __builtin_amdgcn_s_setprio(1); _Pragma("unroll") for (int m = 0; m < 4; ++m) _Pragma("unroll") for (int n = 0; n < 2; ++n) _Pragma("unroll") for (int k = 0; k < 2; ++k) \
;         acc[ai][bj][m][n] = __builtin_amdgcn_mfma_f32_16x16x32_bf16(Bt[n][k], At[m][k], acc[ai][bj][m][n], 0, 0, 0); __builtin_amdgcn_s_setprio(0); } while (0)
; #define PG8_WAIT_V(n) asm volatile("s_waitcnt vmcnt(" #n ")" ::: "memory")
; #define PG8_WAIT_L(n) asm volatile("s_waitcnt lgkmcnt(" #n ")" ::: "memory")
; #define PG8_BAR __builtin_amdgcn_s_barrier()
; #define PG8_SCHED __builtin_amdgcn_sched_barrier(0)
; template <class Epi, class Sched, bool ALIGN_EPI = false, bool SP2 = false>
; __device__ __forceinline__ void gemm_phase(PG8_LAS unsigned char* lds, const Gemm g, const Sched& S, const Epi& E) {
;     ...
;             PG8_LDB(B0, 0, 0); PG8_LDB(B1, 0, 1); PG8_SCHED; PG8_LDA(At, 0, 0); PG8_STAGE(PG8_SA(1, 1), a1 + hstep, voffA);
;             PG8_WAIT_V(8); PG8_WAIT_L(0); PG8_BAR; PG8_MMA(0, 0, At, B0); PG8_MMA(0, 1, At, B1); PG8_BAR; PG8_SCHED;
;             PG8_LDA(At, 0, 1); PG8_STAGE(PG8_SB(0, 0), b2, voffB); PG8_STAGE(PG8_SB(0, 1), b2 + hstep, voffB); PG8_STAGE(PG8_SA(0, 0), a2, voffA);
;             PG8_WAIT_V(8); PG8_WAIT_L(0); PG8_BAR; PG8_MMA(1, 0, At, B0); PG8_MMA(1, 1, At, B1); PG8_BAR; PG8_SCHED;
.LBB0_878:
	s_add_u32 s4, s14, s8
	s_addc_u32 s5, s15, s9
	s_add_u32 s4, s4, 0xc000100
	s_addc_u32 s5, s5, 0
	s_add_u32 s10, s35, s8
	s_addc_u32 s11, s49, s9
	s_add_i32 s18, 0, 0x10000
	s_cmpk_eq_i32 s8, 0x700
	s_cselect_b32 s13, s21, s5
	s_cselect_b32 s12, s20, s4
	s_cselect_b32 s11, s31, s11
	s_cselect_b32 s10, s34, s10
	s_add_i32 s4, 0, 0x14000
	v_add_u32_e32 v176, s18, v202
	v_add_u32_e32 v188, s4, v202
	ds_read_b128 v[164:167], v176
	ds_read_b128 v[168:171], v176 offset:1024
	ds_read_b128 v[172:175], v176 offset:2048
	ds_read_b128 v[176:179], v176 offset:3072
	ds_read_b128 v[180:183], v188
	ds_read_b128 v[184:187], v188 offset:1024
	ds_read_b128 v[206:209], v188 offset:2048
	ds_read_b128 v[210:213], v188 offset:3072
	v_lshl_add_u64 v[188:189], v[160:161], 0, s[8:9]
	s_add_i32 m0, s38, 0xc000
	ds_read_b128 v[214:217], v204
	ds_read_b128 v[218:221], v204 offset:1024
	ds_read_b128 v[222:225], v204 offset:2048
	ds_read_b128 v[226:229], v204 offset:3072
	ds_read_b128 v[230:233], v204 offset:4096
	ds_read_b128 v[234:237], v204 offset:5120
	ds_read_b128 v[238:241], v204 offset:6144
	ds_read_b128 v[242:245], v204 offset:7168
	global_load_lds_dwordx4 v[188:189], off
	v_lshl_add_u64 v[188:189], v[162:163], 0, s[8:9]
	s_add_i32 m0, s38, 0xe000
	s_nop 0
	global_load_lds_dwordx4 v[188:189], off
	s_waitcnt vmcnt(8)
	s_waitcnt lgkmcnt(0)
	s_barrier
	s_setprio 1
	s_waitcnt lgkmcnt(0)
	v_mfma_f32_16x16x32_bf16 v[126:129], v[164:167], v[214:217], v[126:129]
	v_mfma_f32_16x16x32_bf16 v[122:125], v[172:175], v[214:217], v[122:125]
	v_mfma_f32_16x16x32_bf16 v[110:113], v[164:167], v[222:225], v[110:113]
	v_mfma_f32_16x16x32_bf16 v[106:109], v[172:175], v[222:225], v[106:109]
	v_mfma_f32_16x16x32_bf16 v[94:97], v[164:167], v[230:233], v[94:97]
	v_mfma_f32_16x16x32_bf16 v[90:93], v[172:175], v[230:233], v[90:93]
	v_mfma_f32_16x16x32_bf16 v[78:81], v[164:167], v[238:241], v[78:81]
	v_mfma_f32_16x16x32_bf16 v[74:77], v[172:175], v[238:241], v[74:77]
	v_mfma_f32_16x16x32_bf16 v[126:129], v[168:171], v[218:221], v[126:129]
	v_mfma_f32_16x16x32_bf16 v[122:125], v[176:179], v[218:221], v[122:125]
	v_mfma_f32_16x16x32_bf16 v[110:113], v[168:171], v[226:229], v[110:113]
	v_mfma_f32_16x16x32_bf16 v[106:109], v[176:179], v[226:229], v[106:109]
	v_mfma_f32_16x16x32_bf16 v[94:97], v[168:171], v[234:237], v[94:97]
	v_mfma_f32_16x16x32_bf16 v[90:93], v[176:179], v[234:237], v[90:93]
	v_mfma_f32_16x16x32_bf16 v[78:81], v[168:171], v[242:245], v[78:81]
	v_mfma_f32_16x16x32_bf16 v[74:77], v[176:179], v[242:245], v[74:77]
	v_mfma_f32_16x16x32_bf16 v[118:121], v[180:183], v[214:217], v[118:121]
	v_mfma_f32_16x16x32_bf16 v[114:117], v[206:209], v[214:217], v[114:117]
	v_mfma_f32_16x16x32_bf16 v[102:105], v[180:183], v[222:225], v[102:105]
	v_mfma_f32_16x16x32_bf16 v[98:101], v[206:209], v[222:225], v[98:101]
	v_mfma_f32_16x16x32_bf16 v[86:89], v[180:183], v[230:233], v[86:89]
	v_mfma_f32_16x16x32_bf16 v[82:85], v[206:209], v[230:233], v[82:85]
	v_mfma_f32_16x16x32_bf16 v[70:73], v[180:183], v[238:241], v[70:73]
	v_mfma_f32_16x16x32_bf16 v[66:69], v[206:209], v[238:241], v[66:69]
	v_mfma_f32_16x16x32_bf16 v[118:121], v[184:187], v[218:221], v[118:121]
	v_mfma_f32_16x16x32_bf16 v[114:117], v[210:213], v[218:221], v[114:117]
	v_mfma_f32_16x16x32_bf16 v[102:105], v[184:187], v[226:229], v[102:105]
	v_mfma_f32_16x16x32_bf16 v[98:101], v[210:213], v[226:229], v[98:101]
	v_mfma_f32_16x16x32_bf16 v[86:89], v[184:187], v[234:237], v[86:89]
	v_mfma_f32_16x16x32_bf16 v[82:85], v[210:213], v[234:237], v[82:85]
	v_mfma_f32_16x16x32_bf16 v[70:73], v[184:187], v[242:245], v[70:73]
	v_mfma_f32_16x16x32_bf16 v[66:69], v[210:213], v[242:245], v[66:69]
	s_setprio 0
	s_barrier
	s_add_i32 s5, s18, s37
	v_lshl_add_u64 v[188:189], s[10:11], 0, v[154:155]
	s_mov_b32 m0, s5
	ds_read_b128 v[214:217], v204 offset:16384
	ds_read_b128 v[218:221], v204 offset:17408
	ds_read_b128 v[222:225], v204 offset:18432
	ds_read_b128 v[226:229], v204 offset:19456
	ds_read_b128 v[230:233], v204 offset:20480
	ds_read_b128 v[234:237], v204 offset:21504
	ds_read_b128 v[238:241], v204 offset:22528
	ds_read_b128 v[242:245], v204 offset:23552
	global_load_lds_dwordx4 v[188:189], off
	s_add_i32 m0, s5, 0x2000
	s_add_u32 s52, s10, 0x40000
	v_lshl_add_u64 v[246:247], s[10:11], 0, v[150:151]
	s_addc_u32 s53, s11, 0
	s_add_i32 s4, s4, s37
	global_load_lds_dwordx4 v[246:247], off
	v_lshl_add_u64 v[248:249], s[52:53], 0, v[154:155]
	s_mov_b32 m0, s4
	v_lshl_add_u64 v[250:251], s[12:13], 0, v[152:153]
	global_load_lds_dwordx4 v[248:249], off
	v_lshl_add_u64 v[248:249], s[52:53], 0, v[150:151]
	s_add_i32 m0, s4, 0x2000
	s_nop 0
	global_load_lds_dwordx4 v[248:249], off
	v_lshl_add_u64 v[248:249], s[12:13], 0, v[156:157]
	s_mov_b32 m0, s38
	s_nop 0
	global_load_lds_dwordx4 v[248:249], off
	s_mov_b32 m0, s39
	s_nop 0
	global_load_lds_dwordx4 v[250:251], off
	s_waitcnt vmcnt(8)
	s_waitcnt lgkmcnt(0)
	s_barrier
; #define PG8_STAGE(bufoff, gbase, voff) do { _Pragma("unroll") for (int _i = 0; _i < 2; ++_i) \
;         __builtin_amdgcn_global_load_lds((const unsigned*)((const char*)(gbase) + (voff)[_i]), (PG8_LAS unsigned*)(lds + (bufoff) + ldsw + _i * 8192), 16, 0, 0); } while (0)
; #define PG8_LDA(dst, b, h) do { _Pragma("unroll") for (int m = 0; m < 4; ++m) _Pragma("unroll") for (int k = 0; k < 2; ++k) dst[m][k] = *(const PG8_LAS bf16x8*)(lds + PG8_SA(b, h) + aoff + m * 2048 + k * 1024); } while (0)
; #define PG8_LDB(dst, b, h) do { _Pragma("unroll") for (int n = 0; n < 2; ++n) _Pragma("unroll") for (int k = 0; k < 2; ++k) dst[n][k] = *(const PG8_LAS bf16x8*)(lds + PG8_SB(b, h) + boff + n * 2048 + k * 1024); } while (0)
; #define PG8_MMA(ai, bj, At, Bt) do { __builtin_amdgcn_s_setprio(1); _Pragma("unroll") for (int m = 0; m < 4; ++m) _Pragma("unroll") for (int n = 0; n < 2; ++n) _Pragma("unroll") for (int k = 0; k < 2; ++k) \
;         acc[ai][bj][m][n] = __builtin_amdgcn_mfma_f32_16x16x32_bf16(Bt[n][k], At[m][k], acc[ai][bj][m][n], 0, 0, 0); __builtin_amdgcn_s_setprio(0); } while (0)
; #define PG8_WAIT_V(n) asm volatile("s_waitcnt vmcnt(" #n ")" ::: "memory")
; #define PG8_WAIT_L(n) asm volatile("s_waitcnt lgkmcnt(" #n ")" ::: "memory")
; #define PG8_BAR __builtin_amdgcn_s_barrier()
; #define PG8_SCHED __builtin_amdgcn_sched_barrier(0)
; template <class Epi, class Sched, bool ALIGN_EPI = false, bool SP2 = false>
; __device__ __forceinline__ void gemm_phase(PG8_LAS unsigned char* lds, const Gemm g, const Sched& S, const Epi& E) {
;     ...
;             PG8_WAIT_V(8); PG8_WAIT_L(0); PG8_BAR; PG8_MMA(1, 0, At, B0); PG8_MMA(1, 1, At, B1); PG8_BAR; PG8_SCHED;
;             PG8_LDB(B0, 1, 0); PG8_LDB(B1, 1, 1); PG8_SCHED; PG8_LDA(At, 1, 0); PG8_STAGE(PG8_SA(0, 1), a2 + hstep, voffA);
;             PG8_WAIT_V(8); PG8_WAIT_L(0); PG8_BAR; PG8_MMA(0, 0, At, B0); PG8_MMA(0, 1, At, B1); PG8_BAR; PG8_SCHED;
	s_setprio 1
	s_waitcnt lgkmcnt(0)
	v_mfma_f32_16x16x32_bf16 v[62:65], v[164:167], v[214:217], v[62:65]
	v_mfma_f32_16x16x32_bf16 v[58:61], v[172:175], v[214:217], v[58:61]
	v_mfma_f32_16x16x32_bf16 v[46:49], v[164:167], v[222:225], v[46:49]
	v_mfma_f32_16x16x32_bf16 v[42:45], v[172:175], v[222:225], v[42:45]
	v_mfma_f32_16x16x32_bf16 v[30:33], v[164:167], v[230:233], v[30:33]
	v_mfma_f32_16x16x32_bf16 v[26:29], v[172:175], v[230:233], v[26:29]
	v_mfma_f32_16x16x32_bf16 v[14:17], v[164:167], v[238:241], v[14:17]
	v_mfma_f32_16x16x32_bf16 v[10:13], v[172:175], v[238:241], v[10:13]
	v_mfma_f32_16x16x32_bf16 v[62:65], v[168:171], v[218:221], v[62:65]
	v_mfma_f32_16x16x32_bf16 v[58:61], v[176:179], v[218:221], v[58:61]
	v_mfma_f32_16x16x32_bf16 v[46:49], v[168:171], v[226:229], v[46:49]
	v_mfma_f32_16x16x32_bf16 v[42:45], v[176:179], v[226:229], v[42:45]
	v_mfma_f32_16x16x32_bf16 v[30:33], v[168:171], v[234:237], v[30:33]
	v_mfma_f32_16x16x32_bf16 v[26:29], v[176:179], v[234:237], v[26:29]
	v_mfma_f32_16x16x32_bf16 v[14:17], v[168:171], v[242:245], v[14:17]
	v_mfma_f32_16x16x32_bf16 v[10:13], v[176:179], v[242:245], v[10:13]
	v_mfma_f32_16x16x32_bf16 v[54:57], v[180:183], v[214:217], v[54:57]
	v_mfma_f32_16x16x32_bf16 v[50:53], v[206:209], v[214:217], v[50:53]
	v_mfma_f32_16x16x32_bf16 v[38:41], v[180:183], v[222:225], v[38:41]
	v_mfma_f32_16x16x32_bf16 v[34:37], v[206:209], v[222:225], v[34:37]
	v_mfma_f32_16x16x32_bf16 v[22:25], v[180:183], v[230:233], v[22:25]
	v_mfma_f32_16x16x32_bf16 v[18:21], v[206:209], v[230:233], v[18:21]
	v_mfma_f32_16x16x32_bf16 v[6:9], v[180:183], v[238:241], v[6:9]
	v_mfma_f32_16x16x32_bf16 v[2:5], v[206:209], v[238:241], v[2:5]
	v_mfma_f32_16x16x32_bf16 v[54:57], v[184:187], v[218:221], v[54:57]
	v_mfma_f32_16x16x32_bf16 v[50:53], v[210:213], v[218:221], v[50:53]
	v_mfma_f32_16x16x32_bf16 v[38:41], v[184:187], v[226:229], v[38:41]
	v_mfma_f32_16x16x32_bf16 v[34:37], v[210:213], v[226:229], v[34:37]
	v_mfma_f32_16x16x32_bf16 v[22:25], v[184:187], v[234:237], v[22:25]
	v_mfma_f32_16x16x32_bf16 v[18:21], v[210:213], v[234:237], v[18:21]
	v_mfma_f32_16x16x32_bf16 v[6:9], v[184:187], v[242:245], v[6:9]
	v_mfma_f32_16x16x32_bf16 v[2:5], v[210:213], v[242:245], v[2:5]
	s_setprio 0
	s_barrier
	s_add_i32 s4, 0, 0x18000
	s_add_i32 s5, 0, 0x1c000
	v_add_u32_e32 v176, s4, v202
	v_add_u32_e32 v205, s5, v202
	ds_read_b128 v[164:167], v176
	ds_read_b128 v[168:171], v176 offset:1024
	ds_read_b128 v[172:175], v176 offset:2048
	ds_read_b128 v[176:179], v176 offset:3072
	ds_read_b128 v[180:183], v205
	ds_read_b128 v[184:187], v205 offset:1024
	ds_read_b128 v[206:209], v205 offset:2048
	ds_read_b128 v[210:213], v205 offset:3072
	s_add_u32 s12, s12, 0x40000
	s_addc_u32 s13, s13, 0
	s_mov_b32 m0, s40
	v_lshl_add_u64 v[252:253], s[12:13], 0, v[156:157]
	ds_read_b128 v[214:217], v204 offset:32768
	ds_read_b128 v[218:221], v204 offset:33792
	ds_read_b128 v[222:225], v204 offset:34816
	ds_read_b128 v[226:229], v204 offset:35840
	ds_read_b128 v[230:233], v204 offset:36864
	ds_read_b128 v[234:237], v204 offset:37888
	ds_read_b128 v[238:241], v204 offset:38912
	ds_read_b128 v[242:245], v204 offset:39936
	global_load_lds_dwordx4 v[252:253], off
	v_lshl_add_u64 v[252:253], s[12:13], 0, v[152:153]
	s_mov_b32 m0, s41
	s_nop 0
	global_load_lds_dwordx4 v[252:253], off
	s_waitcnt vmcnt(8)
	s_waitcnt lgkmcnt(0)
	s_barrier
	s_setprio 1
	s_waitcnt lgkmcnt(0)
	v_mfma_f32_16x16x32_bf16 v[126:129], v[164:167], v[214:217], v[126:129]
	v_mfma_f32_16x16x32_bf16 v[122:125], v[172:175], v[214:217], v[122:125]
	v_mfma_f32_16x16x32_bf16 v[110:113], v[164:167], v[222:225], v[110:113]
	v_mfma_f32_16x16x32_bf16 v[106:109], v[172:175], v[222:225], v[106:109]
	v_mfma_f32_16x16x32_bf16 v[94:97], v[164:167], v[230:233], v[94:97]
	v_mfma_f32_16x16x32_bf16 v[90:93], v[172:175], v[230:233], v[90:93]
	v_mfma_f32_16x16x32_bf16 v[78:81], v[164:167], v[238:241], v[78:81]
	v_mfma_f32_16x16x32_bf16 v[74:77], v[172:175], v[238:241], v[74:77]
	v_mfma_f32_16x16x32_bf16 v[126:129], v[168:171], v[218:221], v[126:129]
	v_mfma_f32_16x16x32_bf16 v[122:125], v[176:179], v[218:221], v[122:125]
	v_mfma_f32_16x16x32_bf16 v[110:113], v[168:171], v[226:229], v[110:113]
	v_mfma_f32_16x16x32_bf16 v[106:109], v[176:179], v[226:229], v[106:109]
	v_mfma_f32_16x16x32_bf16 v[94:97], v[168:171], v[234:237], v[94:97]
	v_mfma_f32_16x16x32_bf16 v[90:93], v[176:179], v[234:237], v[90:93]
	v_mfma_f32_16x16x32_bf16 v[78:81], v[168:171], v[242:245], v[78:81]
	v_mfma_f32_16x16x32_bf16 v[74:77], v[176:179], v[242:245], v[74:77]
	v_mfma_f32_16x16x32_bf16 v[118:121], v[180:183], v[214:217], v[118:121]
	v_mfma_f32_16x16x32_bf16 v[114:117], v[206:209], v[214:217], v[114:117]
	v_mfma_f32_16x16x32_bf16 v[102:105], v[180:183], v[222:225], v[102:105]
	v_mfma_f32_16x16x32_bf16 v[98:101], v[206:209], v[222:225], v[98:101]
	v_mfma_f32_16x16x32_bf16 v[86:89], v[180:183], v[230:233], v[86:89]
	v_mfma_f32_16x16x32_bf16 v[82:85], v[206:209], v[230:233], v[82:85]
	v_mfma_f32_16x16x32_bf16 v[70:73], v[180:183], v[238:241], v[70:73]
	v_mfma_f32_16x16x32_bf16 v[66:69], v[206:209], v[238:241], v[66:69]
	v_mfma_f32_16x16x32_bf16 v[118:121], v[184:187], v[218:221], v[118:121]
	v_mfma_f32_16x16x32_bf16 v[114:117], v[210:213], v[218:221], v[114:117]
	v_mfma_f32_16x16x32_bf16 v[102:105], v[184:187], v[226:229], v[102:105]
	v_mfma_f32_16x16x32_bf16 v[98:101], v[210:213], v[226:229], v[98:101]
	v_mfma_f32_16x16x32_bf16 v[86:89], v[184:187], v[234:237], v[86:89]
	v_mfma_f32_16x16x32_bf16 v[82:85], v[210:213], v[234:237], v[82:85]
	v_mfma_f32_16x16x32_bf16 v[70:73], v[184:187], v[242:245], v[70:73]
	v_mfma_f32_16x16x32_bf16 v[66:69], v[210:213], v[242:245], v[66:69]
	s_setprio 0
	s_barrier
; #define PG8_STAGE(bufoff, gbase, voff) do { _Pragma("unroll") for (int _i = 0; _i < 2; ++_i) \
;         __builtin_amdgcn_global_load_lds((const unsigned*)((const char*)(gbase) + (voff)[_i]), (PG8_LAS unsigned*)(lds + (bufoff) + ldsw + _i * 8192), 16, 0, 0); } while (0)
; #define PG8_LDA(dst, b, h) do { _Pragma("unroll") for (int m = 0; m < 4; ++m) _Pragma("unroll") for (int k = 0; k < 2; ++k) dst[m][k] = *(const PG8_LAS bf16x8*)(lds + PG8_SA(b, h) + aoff + m * 2048 + k * 1024); } while (0)
; #define PG8_MMA(ai, bj, At, Bt) do { __builtin_amdgcn_s_setprio(1); _Pragma("unroll") for (int m = 0; m < 4; ++m) _Pragma("unroll") for (int n = 0; n < 2; ++n) _Pragma("unroll") for (int k = 0; k < 2; ++k) \
;         acc[ai][bj][m][n] = __builtin_amdgcn_mfma_f32_16x16x32_bf16(Bt[n][k], At[m][k], acc[ai][bj][m][n], 0, 0, 0); __builtin_amdgcn_s_setprio(0); } while (0)
; #define PG8_WAIT_V(n) asm volatile("s_waitcnt vmcnt(" #n ")" ::: "memory")
; #define PG8_WAIT_L(n) asm volatile("s_waitcnt lgkmcnt(" #n ")" ::: "memory")
; #define PG8_BAR __builtin_amdgcn_s_barrier()
; #define PG8_SCHED __builtin_amdgcn_sched_barrier(0)
; template <class Epi, class Sched, bool ALIGN_EPI = false, bool SP2 = false>
; __device__ __forceinline__ void gemm_phase(PG8_LAS unsigned char* lds, const Gemm g, const Sched& S, const Epi& E) {
;     ...
;         for (int t = 0; t < nt; t += 2) {
;             const bool last = (t == nt - 2);
;             const char* a1 = cA + (size_t)(t + 1) * kstep;
;             const char* a2 = last ? nA : cA + (size_t)(t + 2) * kstep; const char* b2 = last ? nB : cB + (size_t)(t + 2) * kstep;
;             const char* a3 = a2 + kstep; const char* b3 = b2 + kstep;
;             if (last && has_next) S.a_ready(nxt);
;     ...
;             PG8_LDA(At, 1, 1); PG8_STAGE(PG8_SB(1, 0), b3, voffB); PG8_STAGE(PG8_SB(1, 1), b3 + hstep, voffB); PG8_STAGE(PG8_SA(1, 0), a3, voffA);
;             PG8_WAIT_V(8); PG8_WAIT_L(0); PG8_BAR; PG8_MMA(1, 0, At, B0); PG8_MMA(1, 1, At, B1); PG8_BAR; PG8_SCHED;
	s_add_i32 s4, s4, s37
	v_lshl_add_u64 v[188:189], v[188:189], 0, s[62:63]
	s_mov_b32 m0, s4
	ds_read_b128 v[214:217], v204 offset:49152
	ds_read_b128 v[218:221], v204 offset:50176
	ds_read_b128 v[222:225], v204 offset:51200
	ds_read_b128 v[226:229], v204 offset:52224
	ds_read_b128 v[230:233], v204 offset:53248
	ds_read_b128 v[234:237], v204 offset:54272
	ds_read_b128 v[238:241], v204 offset:55296
	ds_read_b128 v[242:245], v204 offset:56320
	global_load_lds_dwordx4 v[188:189], off
	s_add_i32 m0, s4, 0x2000
	s_add_u32 s10, s10, 0x40080
	v_lshl_add_u64 v[188:189], v[246:247], 0, s[62:63]
	s_addc_u32 s11, s11, 0
	s_add_i32 s4, s5, s37
	global_load_lds_dwordx4 v[188:189], off
	v_lshl_add_u64 v[188:189], s[10:11], 0, v[154:155]
	s_mov_b32 m0, s4
	s_nop 0
	global_load_lds_dwordx4 v[188:189], off
	v_lshl_add_u64 v[188:189], s[10:11], 0, v[150:151]
	s_add_i32 m0, s4, 0x2000
	s_nop 0
	global_load_lds_dwordx4 v[188:189], off
	v_lshl_add_u64 v[188:189], v[248:249], 0, s[62:63]
	s_mov_b32 m0, s42
	s_nop 0
	global_load_lds_dwordx4 v[188:189], off
	v_lshl_add_u64 v[188:189], v[250:251], 0, s[62:63]
	s_mov_b32 m0, s43
	s_nop 0
	global_load_lds_dwordx4 v[188:189], off
	s_waitcnt vmcnt(8)
	s_waitcnt lgkmcnt(0)
	s_barrier
	s_setprio 1
	s_waitcnt lgkmcnt(0)
	v_mfma_f32_16x16x32_bf16 v[62:65], v[164:167], v[214:217], v[62:65]
	v_mfma_f32_16x16x32_bf16 v[58:61], v[172:175], v[214:217], v[58:61]
	v_mfma_f32_16x16x32_bf16 v[46:49], v[164:167], v[222:225], v[46:49]
	v_mfma_f32_16x16x32_bf16 v[42:45], v[172:175], v[222:225], v[42:45]
	v_mfma_f32_16x16x32_bf16 v[30:33], v[164:167], v[230:233], v[30:33]
	v_mfma_f32_16x16x32_bf16 v[26:29], v[172:175], v[230:233], v[26:29]
	v_mfma_f32_16x16x32_bf16 v[14:17], v[164:167], v[238:241], v[14:17]
	v_mfma_f32_16x16x32_bf16 v[10:13], v[172:175], v[238:241], v[10:13]
	v_mfma_f32_16x16x32_bf16 v[62:65], v[168:171], v[218:221], v[62:65]
	v_mfma_f32_16x16x32_bf16 v[58:61], v[176:179], v[218:221], v[58:61]
	v_mfma_f32_16x16x32_bf16 v[46:49], v[168:171], v[226:229], v[46:49]
	v_mfma_f32_16x16x32_bf16 v[42:45], v[176:179], v[226:229], v[42:45]
	v_mfma_f32_16x16x32_bf16 v[30:33], v[168:171], v[234:237], v[30:33]
	v_mfma_f32_16x16x32_bf16 v[26:29], v[176:179], v[234:237], v[26:29]
	v_mfma_f32_16x16x32_bf16 v[14:17], v[168:171], v[242:245], v[14:17]
	v_mfma_f32_16x16x32_bf16 v[10:13], v[176:179], v[242:245], v[10:13]
	v_mfma_f32_16x16x32_bf16 v[54:57], v[180:183], v[214:217], v[54:57]
	v_mfma_f32_16x16x32_bf16 v[50:53], v[206:209], v[214:217], v[50:53]
	v_mfma_f32_16x16x32_bf16 v[38:41], v[180:183], v[222:225], v[38:41]
	v_mfma_f32_16x16x32_bf16 v[34:37], v[206:209], v[222:225], v[34:37]
	v_mfma_f32_16x16x32_bf16 v[22:25], v[180:183], v[230:233], v[22:25]
	v_mfma_f32_16x16x32_bf16 v[18:21], v[206:209], v[230:233], v[18:21]
	v_mfma_f32_16x16x32_bf16 v[6:9], v[180:183], v[238:241], v[6:9]
	v_mfma_f32_16x16x32_bf16 v[2:5], v[206:209], v[238:241], v[2:5]
	v_mfma_f32_16x16x32_bf16 v[54:57], v[184:187], v[218:221], v[54:57]
	v_mfma_f32_16x16x32_bf16 v[50:53], v[210:213], v[218:221], v[50:53]
	v_mfma_f32_16x16x32_bf16 v[38:41], v[184:187], v[226:229], v[38:41]
	v_mfma_f32_16x16x32_bf16 v[34:37], v[210:213], v[226:229], v[34:37]
	v_mfma_f32_16x16x32_bf16 v[22:25], v[184:187], v[234:237], v[22:25]
	v_mfma_f32_16x16x32_bf16 v[18:21], v[210:213], v[234:237], v[18:21]
	v_mfma_f32_16x16x32_bf16 v[6:9], v[184:187], v[242:245], v[6:9]
	v_mfma_f32_16x16x32_bf16 v[2:5], v[210:213], v[242:245], v[2:5]
	s_setprio 0
	s_barrier
	s_add_i32 s50, s50, 2
	s_add_u32 s8, s8, 0x100
	s_addc_u32 s9, s9, 0
	s_cmp_gt_u32 s50, 13
	s_cbranch_scc0 .LBB0_878
	s_and_b64 vcc, exec, s[26:27]
	s_cbranch_vccz .LBB0_881
	s_barrier

; #define PG8_STAGE(bufoff, gbase, voff) do { _Pragma("unroll") for (int _i = 0; _i < 2; ++_i) \
;         __builtin_amdgcn_global_load_lds((const unsigned*)((const char*)(gbase) + (voff)[_i]), (PG8_LAS unsigned*)(lds + (bufoff) + ldsw + _i * 8192), 16, 0, 0); } while (0)
; #define PG8_LDA(dst, b, h) do { _Pragma("unroll") for (int m = 0; m < 4; ++m) _Pragma("unroll") for (int k = 0; k < 2; ++k) dst[m][k] = *(const PG8_LAS bf16x8*)(lds + PG8_SA(b, h) + aoff + m * 2048 + k * 1024); } while (0)
; #define PG8_LDB(dst, b, h) do { _Pragma("unroll") for (int n = 0; n < 2; ++n) _Pragma("unroll") for (int k = 0; k < 2; ++k) dst[n][k] = *(const PG8_LAS bf16x8*)(lds + PG8_SB(b, h) + boff + n * 2048 + k * 1024); } while (0)
; #define PG8_MMA(ai, bj, At, Bt) do { __builtin_amdgcn_s_setprio(1); _Pragma("unroll") for (int m = 0; m < 4; ++m) _Pragma("unroll") for (int n = 0; n < 2; ++n) _Pragma("unroll") for (int k = 0; k < 2; ++k) \
;         acc[ai][bj][m][n] = __builtin_amdgcn_mfma_f32_16x16x32_bf16(Bt[n][k], At[m][k], acc[ai][bj][m][n], 0, 0, 0); __builtin_amdgcn_s_setprio(0); } while (0)
; #define PG8_WAIT_V(n) asm volatile("s_waitcnt vmcnt(" #n ")" ::: "memory")
; #define PG8_WAIT_L(n) asm volatile("s_waitcnt lgkmcnt(" #n ")" ::: "memory")
; #define PG8_BAR __builtin_amdgcn_s_barrier()
; #define PG8_SCHED __builtin_amdgcn_sched_barrier(0)
; template <class Epi, class Sched, bool ALIGN_EPI = false, bool SP2 = false>
; __device__ __forceinline__ void gemm_phase(PG8_LAS unsigned char* lds, const Gemm g, const Sched& S, const Epi& E) {
;     ...
;             PG8_LDB(B0, 0, 0); PG8_LDB(B1, 0, 1); PG8_SCHED; PG8_LDA(At, 0, 0); PG8_STAGE(PG8_SA(1, 1), a1 + hstep, voffA);
;             PG8_WAIT_V(8); PG8_WAIT_L(0); PG8_BAR; PG8_MMA(0, 0, At, B0); PG8_MMA(0, 1, At, B1); PG8_BAR; PG8_SCHED;
;             PG8_LDA(At, 0, 1); PG8_STAGE(PG8_SB(0, 0), b2, voffB); PG8_STAGE(PG8_SB(0, 1), b2 + hstep, voffB); PG8_STAGE(PG8_SA(0, 0), a2, voffA);
;             PG8_WAIT_V(8); PG8_WAIT_L(0); PG8_BAR; PG8_MMA(1, 0, At, B0); PG8_MMA(1, 1, At, B1); PG8_BAR; PG8_SCHED;
.LBB0_1341:
	s_add_u32 s4, s1, s24
	s_addc_u32 s5, s30, s25
	s_add_u32 s4, s4, 0x34300100
	s_addc_u32 s5, s5, 0
	s_add_u32 s18, s49, s24
	s_addc_u32 s19, s50, s25
	s_add_i32 s52, 0, 0x10000
	s_cmpk_eq_i32 s24, 0x700
	s_cselect_b32 s29, s11, s5
	s_cselect_b32 s28, s10, s4
	v_add_u32_e32 v165, s52, v162
	s_cselect_b32 s27, s47, s19
	s_cselect_b32 s26, s48, s18
	s_add_i32 s18, 0, 0x14000
	ds_read_b128 v[158:161], v165
	ds_read_b128 v[166:169], v165 offset:1024
	ds_read_b128 v[170:173], v165 offset:2048
	ds_read_b128 v[174:177], v165 offset:3072
	v_add_u32_e32 v165, s18, v162
	ds_read_b128 v[178:181], v165
	ds_read_b128 v[182:185], v165 offset:1024
	ds_read_b128 v[186:189], v165 offset:2048
	ds_read_b128 v[202:205], v165 offset:3072
	v_lshl_add_u64 v[238:239], v[154:155], 0, s[24:25]
	s_add_i32 m0, s36, 0xc000
	ds_read_b128 v[206:209], v164
	ds_read_b128 v[210:213], v164 offset:1024
	ds_read_b128 v[214:217], v164 offset:2048
	ds_read_b128 v[218:221], v164 offset:3072
	ds_read_b128 v[222:225], v164 offset:4096
	ds_read_b128 v[226:229], v164 offset:5120
	ds_read_b128 v[230:233], v164 offset:6144
	ds_read_b128 v[234:237], v164 offset:7168
	global_load_lds_dwordx4 v[238:239], off
	v_lshl_add_u64 v[238:239], v[156:157], 0, s[24:25]
	s_add_i32 m0, s36, 0xe000
	s_nop 0
	global_load_lds_dwordx4 v[238:239], off
	s_waitcnt vmcnt(8)
	s_waitcnt lgkmcnt(0)
	s_barrier
	s_setprio 1
	s_waitcnt lgkmcnt(0)
	v_mfma_f32_16x16x32_bf16 v[126:129], v[158:161], v[206:209], v[126:129]
	v_mfma_f32_16x16x32_bf16 v[122:125], v[170:173], v[206:209], v[122:125]
	v_mfma_f32_16x16x32_bf16 v[110:113], v[158:161], v[214:217], v[110:113]
	v_mfma_f32_16x16x32_bf16 v[106:109], v[170:173], v[214:217], v[106:109]
	v_mfma_f32_16x16x32_bf16 v[94:97], v[158:161], v[222:225], v[94:97]
	v_mfma_f32_16x16x32_bf16 v[90:93], v[170:173], v[222:225], v[90:93]
	v_mfma_f32_16x16x32_bf16 v[78:81], v[158:161], v[230:233], v[78:81]
	v_mfma_f32_16x16x32_bf16 v[74:77], v[170:173], v[230:233], v[74:77]
	v_mfma_f32_16x16x32_bf16 v[126:129], v[166:169], v[210:213], v[126:129]
	v_mfma_f32_16x16x32_bf16 v[122:125], v[174:177], v[210:213], v[122:125]
	v_mfma_f32_16x16x32_bf16 v[110:113], v[166:169], v[218:221], v[110:113]
	v_mfma_f32_16x16x32_bf16 v[106:109], v[174:177], v[218:221], v[106:109]
	v_mfma_f32_16x16x32_bf16 v[94:97], v[166:169], v[226:229], v[94:97]
	v_mfma_f32_16x16x32_bf16 v[90:93], v[174:177], v[226:229], v[90:93]
	v_mfma_f32_16x16x32_bf16 v[78:81], v[166:169], v[234:237], v[78:81]
	v_mfma_f32_16x16x32_bf16 v[74:77], v[174:177], v[234:237], v[74:77]
	v_mfma_f32_16x16x32_bf16 v[118:121], v[178:181], v[206:209], v[118:121]
	v_mfma_f32_16x16x32_bf16 v[114:117], v[186:189], v[206:209], v[114:117]
	v_mfma_f32_16x16x32_bf16 v[102:105], v[178:181], v[214:217], v[102:105]
	v_mfma_f32_16x16x32_bf16 v[98:101], v[186:189], v[214:217], v[98:101]
	v_mfma_f32_16x16x32_bf16 v[86:89], v[178:181], v[222:225], v[86:89]
	v_mfma_f32_16x16x32_bf16 v[82:85], v[186:189], v[222:225], v[82:85]
	v_mfma_f32_16x16x32_bf16 v[70:73], v[178:181], v[230:233], v[70:73]
	v_mfma_f32_16x16x32_bf16 v[66:69], v[186:189], v[230:233], v[66:69]
	v_mfma_f32_16x16x32_bf16 v[118:121], v[182:185], v[210:213], v[118:121]
	v_mfma_f32_16x16x32_bf16 v[114:117], v[202:205], v[210:213], v[114:117]
	v_mfma_f32_16x16x32_bf16 v[102:105], v[182:185], v[218:221], v[102:105]
	v_mfma_f32_16x16x32_bf16 v[98:101], v[202:205], v[218:221], v[98:101]
	v_mfma_f32_16x16x32_bf16 v[86:89], v[182:185], v[226:229], v[86:89]
	v_mfma_f32_16x16x32_bf16 v[82:85], v[202:205], v[226:229], v[82:85]
	v_mfma_f32_16x16x32_bf16 v[70:73], v[182:185], v[234:237], v[70:73]
	v_mfma_f32_16x16x32_bf16 v[66:69], v[202:205], v[234:237], v[66:69]
	s_setprio 0
	s_barrier
	s_add_i32 s4, s52, s35
	v_lshl_add_u64 v[238:239], s[26:27], 0, v[152:153]
	s_mov_b32 m0, s4
	ds_read_b128 v[206:209], v164 offset:16384
	ds_read_b128 v[210:213], v164 offset:17408
	ds_read_b128 v[214:217], v164 offset:18432
	ds_read_b128 v[218:221], v164 offset:19456
	ds_read_b128 v[222:225], v164 offset:20480
	ds_read_b128 v[226:229], v164 offset:21504
	ds_read_b128 v[230:233], v164 offset:22528
	ds_read_b128 v[234:237], v164 offset:23552
	global_load_lds_dwordx4 v[238:239], off
	s_add_i32 m0, s4, 0x2000
	s_add_u32 s4, s26, 0x40000
	v_lshl_add_u64 v[240:241], s[26:27], 0, v[150:151]
	s_addc_u32 s5, s27, 0
	s_add_i32 s18, s18, s35
	global_load_lds_dwordx4 v[240:241], off
	v_lshl_add_u64 v[242:243], s[4:5], 0, v[152:153]
	s_mov_b32 m0, s18
	v_lshl_add_u64 v[244:245], s[28:29], 0, v[150:151]
	global_load_lds_dwordx4 v[242:243], off
	v_lshl_add_u64 v[242:243], s[4:5], 0, v[150:151]
	s_add_i32 m0, s18, 0x2000
	s_nop 0
	global_load_lds_dwordx4 v[242:243], off
	v_lshl_add_u64 v[242:243], s[28:29], 0, v[152:153]
	s_mov_b32 m0, s36
	s_nop 0
	global_load_lds_dwordx4 v[242:243], off
	s_mov_b32 m0, s37
	s_nop 0
	global_load_lds_dwordx4 v[244:245], off
	s_waitcnt vmcnt(8)
	s_waitcnt lgkmcnt(0)
	s_barrier
; #define PG8_STAGE(bufoff, gbase, voff) do { _Pragma("unroll") for (int _i = 0; _i < 2; ++_i) \
;         __builtin_amdgcn_global_load_lds((const unsigned*)((const char*)(gbase) + (voff)[_i]), (PG8_LAS unsigned*)(lds + (bufoff) + ldsw + _i * 8192), 16, 0, 0); } while (0)
; #define PG8_LDA(dst, b, h) do { _Pragma("unroll") for (int m = 0; m < 4; ++m) _Pragma("unroll") for (int k = 0; k < 2; ++k) dst[m][k] = *(const PG8_LAS bf16x8*)(lds + PG8_SA(b, h) + aoff + m * 2048 + k * 1024); } while (0)
; #define PG8_LDB(dst, b, h) do { _Pragma("unroll") for (int n = 0; n < 2; ++n) _Pragma("unroll") for (int k = 0; k < 2; ++k) dst[n][k] = *(const PG8_LAS bf16x8*)(lds + PG8_SB(b, h) + boff + n * 2048 + k * 1024); } while (0)
; #define PG8_MMA(ai, bj, At, Bt) do { __builtin_amdgcn_s_setprio(1); _Pragma("unroll") for (int m = 0; m < 4; ++m) _Pragma("unroll") for (int n = 0; n < 2; ++n) _Pragma("unroll") for (int k = 0; k < 2; ++k) \
;         acc[ai][bj][m][n] = __builtin_amdgcn_mfma_f32_16x16x32_bf16(Bt[n][k], At[m][k], acc[ai][bj][m][n], 0, 0, 0); __builtin_amdgcn_s_setprio(0); } while (0)
; #define PG8_WAIT_V(n) asm volatile("s_waitcnt vmcnt(" #n ")" ::: "memory")
; #define PG8_WAIT_L(n) asm volatile("s_waitcnt lgkmcnt(" #n ")" ::: "memory")
; #define PG8_BAR __builtin_amdgcn_s_barrier()
; #define PG8_SCHED __builtin_amdgcn_sched_barrier(0)
; template <class Epi, class Sched, bool ALIGN_EPI = false, bool SP2 = false>
; __device__ __forceinline__ void gemm_phase(PG8_LAS unsigned char* lds, const Gemm g, const Sched& S, const Epi& E) {
;     ...
;             PG8_WAIT_V(8); PG8_WAIT_L(0); PG8_BAR; PG8_MMA(1, 0, At, B0); PG8_MMA(1, 1, At, B1); PG8_BAR; PG8_SCHED;
;             PG8_LDB(B0, 1, 0); PG8_LDB(B1, 1, 1); PG8_SCHED; PG8_LDA(At, 1, 0); PG8_STAGE(PG8_SA(0, 1), a2 + hstep, voffA);
;             PG8_WAIT_V(8); PG8_WAIT_L(0); PG8_BAR; PG8_MMA(0, 0, At, B0); PG8_MMA(0, 1, At, B1); PG8_BAR; PG8_SCHED;
	s_setprio 1
	s_waitcnt lgkmcnt(0)
	v_mfma_f32_16x16x32_bf16 v[62:65], v[158:161], v[206:209], v[62:65]
	v_mfma_f32_16x16x32_bf16 v[58:61], v[170:173], v[206:209], v[58:61]
	v_mfma_f32_16x16x32_bf16 v[46:49], v[158:161], v[214:217], v[46:49]
	v_mfma_f32_16x16x32_bf16 v[42:45], v[170:173], v[214:217], v[42:45]
	v_mfma_f32_16x16x32_bf16 v[30:33], v[158:161], v[222:225], v[30:33]
	v_mfma_f32_16x16x32_bf16 v[26:29], v[170:173], v[222:225], v[26:29]
	v_mfma_f32_16x16x32_bf16 v[14:17], v[158:161], v[230:233], v[14:17]
	v_mfma_f32_16x16x32_bf16 v[10:13], v[170:173], v[230:233], v[10:13]
	v_mfma_f32_16x16x32_bf16 v[62:65], v[166:169], v[210:213], v[62:65]
	v_mfma_f32_16x16x32_bf16 v[58:61], v[174:177], v[210:213], v[58:61]
	v_mfma_f32_16x16x32_bf16 v[46:49], v[166:169], v[218:221], v[46:49]
	v_mfma_f32_16x16x32_bf16 v[42:45], v[174:177], v[218:221], v[42:45]
	v_mfma_f32_16x16x32_bf16 v[30:33], v[166:169], v[226:229], v[30:33]
	v_mfma_f32_16x16x32_bf16 v[26:29], v[174:177], v[226:229], v[26:29]
	v_mfma_f32_16x16x32_bf16 v[14:17], v[166:169], v[234:237], v[14:17]
	v_mfma_f32_16x16x32_bf16 v[10:13], v[174:177], v[234:237], v[10:13]
	v_mfma_f32_16x16x32_bf16 v[54:57], v[178:181], v[206:209], v[54:57]
	v_mfma_f32_16x16x32_bf16 v[50:53], v[186:189], v[206:209], v[50:53]
	v_mfma_f32_16x16x32_bf16 v[38:41], v[178:181], v[214:217], v[38:41]
	v_mfma_f32_16x16x32_bf16 v[34:37], v[186:189], v[214:217], v[34:37]
	v_mfma_f32_16x16x32_bf16 v[22:25], v[178:181], v[222:225], v[22:25]
	v_mfma_f32_16x16x32_bf16 v[18:21], v[186:189], v[222:225], v[18:21]
	v_mfma_f32_16x16x32_bf16 v[6:9], v[178:181], v[230:233], v[6:9]
	v_mfma_f32_16x16x32_bf16 v[2:5], v[186:189], v[230:233], v[2:5]
	v_mfma_f32_16x16x32_bf16 v[54:57], v[182:185], v[210:213], v[54:57]
	v_mfma_f32_16x16x32_bf16 v[50:53], v[202:205], v[210:213], v[50:53]
	v_mfma_f32_16x16x32_bf16 v[38:41], v[182:185], v[218:221], v[38:41]
	v_mfma_f32_16x16x32_bf16 v[34:37], v[202:205], v[218:221], v[34:37]
	v_mfma_f32_16x16x32_bf16 v[22:25], v[182:185], v[226:229], v[22:25]
	v_mfma_f32_16x16x32_bf16 v[18:21], v[202:205], v[226:229], v[18:21]
	v_mfma_f32_16x16x32_bf16 v[6:9], v[182:185], v[234:237], v[6:9]
	v_mfma_f32_16x16x32_bf16 v[2:5], v[202:205], v[234:237], v[2:5]
	s_setprio 0
	s_barrier
	s_add_i32 s18, 0, 0x18000
	v_add_u32_e32 v165, s18, v162
	s_add_i32 s19, 0, 0x1c000
	ds_read_b128 v[158:161], v165
	ds_read_b128 v[166:169], v165 offset:1024
	ds_read_b128 v[170:173], v165 offset:2048
	ds_read_b128 v[174:177], v165 offset:3072
	v_add_u32_e32 v165, s19, v162
	ds_read_b128 v[178:181], v165
	ds_read_b128 v[182:185], v165 offset:1024
	ds_read_b128 v[186:189], v165 offset:2048
	ds_read_b128 v[202:205], v165 offset:3072
	s_add_u32 s4, s28, 0x40000
	s_addc_u32 s5, s29, 0
	s_mov_b32 m0, s38
	v_lshl_add_u64 v[246:247], s[4:5], 0, v[152:153]
	ds_read_b128 v[206:209], v164 offset:32768
	ds_read_b128 v[210:213], v164 offset:33792
	ds_read_b128 v[214:217], v164 offset:34816
	ds_read_b128 v[218:221], v164 offset:35840
	ds_read_b128 v[222:225], v164 offset:36864
	ds_read_b128 v[226:229], v164 offset:37888
	ds_read_b128 v[230:233], v164 offset:38912
	ds_read_b128 v[234:237], v164 offset:39936
	global_load_lds_dwordx4 v[246:247], off
	v_lshl_add_u64 v[246:247], s[4:5], 0, v[150:151]
	s_mov_b32 m0, s39
	s_nop 0
	global_load_lds_dwordx4 v[246:247], off
	s_waitcnt vmcnt(8)
	s_waitcnt lgkmcnt(0)
	s_barrier
	s_setprio 1
	s_waitcnt lgkmcnt(0)
	v_mfma_f32_16x16x32_bf16 v[126:129], v[158:161], v[206:209], v[126:129]
	v_mfma_f32_16x16x32_bf16 v[122:125], v[170:173], v[206:209], v[122:125]
	v_mfma_f32_16x16x32_bf16 v[110:113], v[158:161], v[214:217], v[110:113]
	v_mfma_f32_16x16x32_bf16 v[106:109], v[170:173], v[214:217], v[106:109]
	v_mfma_f32_16x16x32_bf16 v[94:97], v[158:161], v[222:225], v[94:97]
	v_mfma_f32_16x16x32_bf16 v[90:93], v[170:173], v[222:225], v[90:93]
	v_mfma_f32_16x16x32_bf16 v[78:81], v[158:161], v[230:233], v[78:81]
	v_mfma_f32_16x16x32_bf16 v[74:77], v[170:173], v[230:233], v[74:77]
	v_mfma_f32_16x16x32_bf16 v[126:129], v[166:169], v[210:213], v[126:129]
	v_mfma_f32_16x16x32_bf16 v[122:125], v[174:177], v[210:213], v[122:125]
	v_mfma_f32_16x16x32_bf16 v[110:113], v[166:169], v[218:221], v[110:113]
	v_mfma_f32_16x16x32_bf16 v[106:109], v[174:177], v[218:221], v[106:109]
	v_mfma_f32_16x16x32_bf16 v[94:97], v[166:169], v[226:229], v[94:97]
	v_mfma_f32_16x16x32_bf16 v[90:93], v[174:177], v[226:229], v[90:93]
	v_mfma_f32_16x16x32_bf16 v[78:81], v[166:169], v[234:237], v[78:81]
	v_mfma_f32_16x16x32_bf16 v[74:77], v[174:177], v[234:237], v[74:77]
	v_mfma_f32_16x16x32_bf16 v[118:121], v[178:181], v[206:209], v[118:121]
	v_mfma_f32_16x16x32_bf16 v[114:117], v[186:189], v[206:209], v[114:117]
	v_mfma_f32_16x16x32_bf16 v[102:105], v[178:181], v[214:217], v[102:105]
	v_mfma_f32_16x16x32_bf16 v[98:101], v[186:189], v[214:217], v[98:101]
	v_mfma_f32_16x16x32_bf16 v[86:89], v[178:181], v[222:225], v[86:89]
	v_mfma_f32_16x16x32_bf16 v[82:85], v[186:189], v[222:225], v[82:85]
	v_mfma_f32_16x16x32_bf16 v[70:73], v[178:181], v[230:233], v[70:73]
	v_mfma_f32_16x16x32_bf16 v[66:69], v[186:189], v[230:233], v[66:69]
	v_mfma_f32_16x16x32_bf16 v[118:121], v[182:185], v[210:213], v[118:121]
	v_mfma_f32_16x16x32_bf16 v[114:117], v[202:205], v[210:213], v[114:117]
	v_mfma_f32_16x16x32_bf16 v[102:105], v[182:185], v[218:221], v[102:105]
	v_mfma_f32_16x16x32_bf16 v[98:101], v[202:205], v[218:221], v[98:101]
	v_mfma_f32_16x16x32_bf16 v[86:89], v[182:185], v[226:229], v[86:89]
	v_mfma_f32_16x16x32_bf16 v[82:85], v[202:205], v[226:229], v[82:85]
	v_mfma_f32_16x16x32_bf16 v[70:73], v[182:185], v[234:237], v[70:73]
	v_mfma_f32_16x16x32_bf16 v[66:69], v[202:205], v[234:237], v[66:69]
	s_setprio 0
	s_barrier
; #define PG8_STAGE(bufoff, gbase, voff) do { _Pragma("unroll") for (int _i = 0; _i < 2; ++_i) \
;         __builtin_amdgcn_global_load_lds((const unsigned*)((const char*)(gbase) + (voff)[_i]), (PG8_LAS unsigned*)(lds + (bufoff) + ldsw + _i * 8192), 16, 0, 0); } while (0)
; #define PG8_LDA(dst, b, h) do { _Pragma("unroll") for (int m = 0; m < 4; ++m) _Pragma("unroll") for (int k = 0; k < 2; ++k) dst[m][k] = *(const PG8_LAS bf16x8*)(lds + PG8_SA(b, h) + aoff + m * 2048 + k * 1024); } while (0)
; #define PG8_MMA(ai, bj, At, Bt) do { __builtin_amdgcn_s_setprio(1); _Pragma("unroll") for (int m = 0; m < 4; ++m) _Pragma("unroll") for (int n = 0; n < 2; ++n) _Pragma("unroll") for (int k = 0; k < 2; ++k) \
;         acc[ai][bj][m][n] = __builtin_amdgcn_mfma_f32_16x16x32_bf16(Bt[n][k], At[m][k], acc[ai][bj][m][n], 0, 0, 0); __builtin_amdgcn_s_setprio(0); } while (0)
; #define PG8_WAIT_V(n) asm volatile("s_waitcnt vmcnt(" #n ")" ::: "memory")
; #define PG8_WAIT_L(n) asm volatile("s_waitcnt lgkmcnt(" #n ")" ::: "memory")
; #define PG8_BAR __builtin_amdgcn_s_barrier()
; #define PG8_SCHED __builtin_amdgcn_sched_barrier(0)
; template <class Epi, class Sched, bool ALIGN_EPI = false, bool SP2 = false>
; __device__ __forceinline__ void gemm_phase(PG8_LAS unsigned char* lds, const Gemm g, const Sched& S, const Epi& E) {
;     ...
;         for (int t = 0; t < nt; t += 2) {
;             const bool last = (t == nt - 2);
;             const char* a1 = cA + (size_t)(t + 1) * kstep;
;             const char* a2 = last ? nA : cA + (size_t)(t + 2) * kstep; const char* b2 = last ? nB : cB + (size_t)(t + 2) * kstep;
;             const char* a3 = a2 + kstep; const char* b3 = b2 + kstep;
;             if (last && has_next) S.a_ready(nxt);
;     ...
;             PG8_LDA(At, 1, 1); PG8_STAGE(PG8_SB(1, 0), b3, voffB); PG8_STAGE(PG8_SB(1, 1), b3 + hstep, voffB); PG8_STAGE(PG8_SA(1, 0), a3, voffA);
;             PG8_WAIT_V(8); PG8_WAIT_L(0); PG8_BAR; PG8_MMA(1, 0, At, B0); PG8_MMA(1, 1, At, B1); PG8_BAR; PG8_SCHED;
	s_add_i32 s4, s18, s35
	v_lshl_add_u64 v[238:239], v[238:239], 0, s[62:63]
	s_mov_b32 m0, s4
	ds_read_b128 v[206:209], v164 offset:49152
	ds_read_b128 v[210:213], v164 offset:50176
	ds_read_b128 v[214:217], v164 offset:51200
	ds_read_b128 v[218:221], v164 offset:52224
	ds_read_b128 v[222:225], v164 offset:53248
	ds_read_b128 v[226:229], v164 offset:54272
	ds_read_b128 v[230:233], v164 offset:55296
	ds_read_b128 v[234:237], v164 offset:56320
	global_load_lds_dwordx4 v[238:239], off
	s_add_i32 m0, s4, 0x2000
	s_add_u32 s4, s26, 0x40080
	v_lshl_add_u64 v[238:239], v[240:241], 0, s[62:63]
	s_addc_u32 s5, s27, 0
	s_add_i32 s18, s19, s35
	global_load_lds_dwordx4 v[238:239], off
	v_lshl_add_u64 v[238:239], s[4:5], 0, v[152:153]
	s_mov_b32 m0, s18
	s_nop 0
	global_load_lds_dwordx4 v[238:239], off
	v_lshl_add_u64 v[238:239], s[4:5], 0, v[150:151]
	s_add_i32 m0, s18, 0x2000
	s_nop 0
	global_load_lds_dwordx4 v[238:239], off
	v_lshl_add_u64 v[238:239], v[242:243], 0, s[62:63]
	s_mov_b32 m0, s41
	s_nop 0
	global_load_lds_dwordx4 v[238:239], off
	v_lshl_add_u64 v[238:239], v[244:245], 0, s[62:63]
	s_mov_b32 m0, s42
	s_nop 0
	global_load_lds_dwordx4 v[238:239], off
	s_waitcnt vmcnt(8)
	s_waitcnt lgkmcnt(0)
	s_barrier
	s_setprio 1
	s_waitcnt lgkmcnt(0)
	v_mfma_f32_16x16x32_bf16 v[62:65], v[158:161], v[206:209], v[62:65]
	v_mfma_f32_16x16x32_bf16 v[58:61], v[170:173], v[206:209], v[58:61]
	v_mfma_f32_16x16x32_bf16 v[46:49], v[158:161], v[214:217], v[46:49]
	v_mfma_f32_16x16x32_bf16 v[42:45], v[170:173], v[214:217], v[42:45]
	v_mfma_f32_16x16x32_bf16 v[30:33], v[158:161], v[222:225], v[30:33]
	v_mfma_f32_16x16x32_bf16 v[26:29], v[170:173], v[222:225], v[26:29]
	v_mfma_f32_16x16x32_bf16 v[14:17], v[158:161], v[230:233], v[14:17]
	v_mfma_f32_16x16x32_bf16 v[10:13], v[170:173], v[230:233], v[10:13]
	v_mfma_f32_16x16x32_bf16 v[62:65], v[166:169], v[210:213], v[62:65]
	v_mfma_f32_16x16x32_bf16 v[58:61], v[174:177], v[210:213], v[58:61]
	v_mfma_f32_16x16x32_bf16 v[46:49], v[166:169], v[218:221], v[46:49]
	v_mfma_f32_16x16x32_bf16 v[42:45], v[174:177], v[218:221], v[42:45]
	v_mfma_f32_16x16x32_bf16 v[30:33], v[166:169], v[226:229], v[30:33]
	v_mfma_f32_16x16x32_bf16 v[26:29], v[174:177], v[226:229], v[26:29]
	v_mfma_f32_16x16x32_bf16 v[14:17], v[166:169], v[234:237], v[14:17]
	v_mfma_f32_16x16x32_bf16 v[10:13], v[174:177], v[234:237], v[10:13]
	v_mfma_f32_16x16x32_bf16 v[54:57], v[178:181], v[206:209], v[54:57]
	v_mfma_f32_16x16x32_bf16 v[50:53], v[186:189], v[206:209], v[50:53]
	v_mfma_f32_16x16x32_bf16 v[38:41], v[178:181], v[214:217], v[38:41]
	v_mfma_f32_16x16x32_bf16 v[34:37], v[186:189], v[214:217], v[34:37]
	v_mfma_f32_16x16x32_bf16 v[22:25], v[178:181], v[222:225], v[22:25]
	v_mfma_f32_16x16x32_bf16 v[18:21], v[186:189], v[222:225], v[18:21]
	v_mfma_f32_16x16x32_bf16 v[6:9], v[178:181], v[230:233], v[6:9]
	v_mfma_f32_16x16x32_bf16 v[2:5], v[186:189], v[230:233], v[2:5]
	v_mfma_f32_16x16x32_bf16 v[54:57], v[182:185], v[210:213], v[54:57]
	v_mfma_f32_16x16x32_bf16 v[50:53], v[202:205], v[210:213], v[50:53]
	v_mfma_f32_16x16x32_bf16 v[38:41], v[182:185], v[218:221], v[38:41]
	v_mfma_f32_16x16x32_bf16 v[34:37], v[202:205], v[218:221], v[34:37]
	v_mfma_f32_16x16x32_bf16 v[22:25], v[182:185], v[226:229], v[22:25]
	v_mfma_f32_16x16x32_bf16 v[18:21], v[202:205], v[226:229], v[18:21]
	v_mfma_f32_16x16x32_bf16 v[6:9], v[182:185], v[234:237], v[6:9]
	v_mfma_f32_16x16x32_bf16 v[2:5], v[202:205], v[234:237], v[2:5]
	s_setprio 0
	s_barrier
	s_add_i32 s51, s51, 2
	s_add_u32 s24, s24, 0x100
	s_addc_u32 s25, s25, 0
	s_cmp_gt_u32 s51, 13
	s_cbranch_scc0 .LBB0_1341
	s_and_b64 vcc, exec, s[20:21]
	s_cbranch_vccz .LBB0_1344
	s_barrier

; #define PG8_STAGE(bufoff, gbase, voff) do { _Pragma("unroll") for (int _i = 0; _i < 2; ++_i) \
;         __builtin_amdgcn_global_load_lds((const unsigned*)((const char*)(gbase) + (voff)[_i]), (PG8_LAS unsigned*)(lds + (bufoff) + ldsw + _i * 8192), 16, 0, 0); } while (0)
; #define PG8_LDA(dst, b, h) do { _Pragma("unroll") for (int m = 0; m < 4; ++m) _Pragma("unroll") for (int k = 0; k < 2; ++k) dst[m][k] = *(const PG8_LAS bf16x8*)(lds + PG8_SA(b, h) + aoff + m * 2048 + k * 1024); } while (0)
; #define PG8_LDB(dst, b, h) do { _Pragma("unroll") for (int n = 0; n < 2; ++n) _Pragma("unroll") for (int k = 0; k < 2; ++k) dst[n][k] = *(const PG8_LAS bf16x8*)(lds + PG8_SB(b, h) + boff + n * 2048 + k * 1024); } while (0)
; #define PG8_MMA(ai, bj, At, Bt) do { __builtin_amdgcn_s_setprio(1); _Pragma("unroll") for (int m = 0; m < 4; ++m) _Pragma("unroll") for (int n = 0; n < 2; ++n) _Pragma("unroll") for (int k = 0; k < 2; ++k) \
;         acc[ai][bj][m][n] = __builtin_amdgcn_mfma_f32_16x16x32_bf16(Bt[n][k], At[m][k], acc[ai][bj][m][n], 0, 0, 0); __builtin_amdgcn_s_setprio(0); } while (0)
; #define PG8_WAIT_V(n) asm volatile("s_waitcnt vmcnt(" #n ")" ::: "memory")
; #define PG8_WAIT_L(n) asm volatile("s_waitcnt lgkmcnt(" #n ")" ::: "memory")
; #define PG8_BAR __builtin_amdgcn_s_barrier()
; #define PG8_SCHED __builtin_amdgcn_sched_barrier(0)
; template <class Epi, class Sched, bool ALIGN_EPI = false, bool SP2 = false>
; __device__ __forceinline__ void gemm_phase(PG8_LAS unsigned char* lds, const Gemm g, const Sched& S, const Epi& E) {
;     ...
;             PG8_LDB(B0, 0, 0); PG8_LDB(B1, 0, 1); PG8_SCHED; PG8_LDA(At, 0, 0); PG8_STAGE(PG8_SA(1, 1), a1 + hstep, voffA);
;             PG8_WAIT_V(8); PG8_WAIT_L(0); PG8_BAR; PG8_MMA(0, 0, At, B0); PG8_MMA(0, 1, At, B1); PG8_BAR; PG8_SCHED;
;             PG8_LDA(At, 0, 1); PG8_STAGE(PG8_SB(0, 0), b2, voffB); PG8_STAGE(PG8_SB(0, 1), b2 + hstep, voffB); PG8_STAGE(PG8_SA(0, 0), a2, voffA);
;             PG8_WAIT_V(8); PG8_WAIT_L(0); PG8_BAR; PG8_MMA(1, 0, At, B0); PG8_MMA(1, 1, At, B1); PG8_BAR; PG8_SCHED;
.LBB0_1387:
	s_add_u32 s1, s6, s20
	s_addc_u32 s4, s7, s21
	s_add_u32 s5, s1, 0xc000100
	s_addc_u32 s4, s4, 0
	s_add_u32 s18, s48, s20
	s_addc_u32 s19, s49, s21
	s_add_i32 s1, 0, 0x10000
	s_cmpk_eq_i32 s20, 0x700
	s_cselect_b32 s25, s11, s4
	s_cselect_b32 s24, s10, s5
	v_add_u32_e32 v164, s1, v166
	s_cselect_b32 s23, s46, s19
	s_cselect_b32 s22, s47, s18
	s_add_i32 s26, 0, 0x14000
	ds_read_b128 v[170:173], v164
	ds_read_b128 v[174:177], v164 offset:1024
	ds_read_b128 v[178:181], v164 offset:2048
	ds_read_b128 v[182:185], v164 offset:3072
	v_add_u32_e32 v164, s26, v166
	ds_read_b128 v[186:189], v164
	ds_read_b128 v[202:205], v164 offset:1024
	ds_read_b128 v[206:209], v164 offset:2048
	ds_read_b128 v[210:213], v164 offset:3072
	v_lshl_add_u64 v[164:165], v[160:161], 0, s[20:21]
	s_add_i32 m0, s34, 0xc000
	ds_read_b128 v[214:217], v168
	ds_read_b128 v[218:221], v168 offset:1024
	ds_read_b128 v[222:225], v168 offset:2048
	ds_read_b128 v[226:229], v168 offset:3072
	ds_read_b128 v[230:233], v168 offset:4096
	ds_read_b128 v[234:237], v168 offset:5120
	ds_read_b128 v[238:241], v168 offset:6144
	ds_read_b128 v[242:245], v168 offset:7168
	global_load_lds_dwordx4 v[164:165], off
	v_lshl_add_u64 v[164:165], v[162:163], 0, s[20:21]
	s_add_i32 m0, s34, 0xe000
	s_nop 0
	global_load_lds_dwordx4 v[164:165], off
	s_waitcnt vmcnt(8)
	s_waitcnt lgkmcnt(0)
	s_barrier
	s_setprio 1
	s_waitcnt lgkmcnt(0)
	v_mfma_f32_16x16x32_bf16 v[126:129], v[170:173], v[214:217], v[126:129]
	v_mfma_f32_16x16x32_bf16 v[118:121], v[178:181], v[214:217], v[118:121]
	v_mfma_f32_16x16x32_bf16 v[110:113], v[170:173], v[222:225], v[110:113]
	v_mfma_f32_16x16x32_bf16 v[102:105], v[178:181], v[222:225], v[102:105]
	v_mfma_f32_16x16x32_bf16 v[94:97], v[170:173], v[230:233], v[94:97]
	v_mfma_f32_16x16x32_bf16 v[86:89], v[178:181], v[230:233], v[86:89]
	v_mfma_f32_16x16x32_bf16 v[78:81], v[170:173], v[238:241], v[78:81]
	v_mfma_f32_16x16x32_bf16 v[70:73], v[178:181], v[238:241], v[70:73]
	v_mfma_f32_16x16x32_bf16 v[126:129], v[174:177], v[218:221], v[126:129]
	v_mfma_f32_16x16x32_bf16 v[118:121], v[182:185], v[218:221], v[118:121]
	v_mfma_f32_16x16x32_bf16 v[110:113], v[174:177], v[226:229], v[110:113]
	v_mfma_f32_16x16x32_bf16 v[102:105], v[182:185], v[226:229], v[102:105]
	v_mfma_f32_16x16x32_bf16 v[94:97], v[174:177], v[234:237], v[94:97]
	v_mfma_f32_16x16x32_bf16 v[86:89], v[182:185], v[234:237], v[86:89]
	v_mfma_f32_16x16x32_bf16 v[78:81], v[174:177], v[242:245], v[78:81]
	v_mfma_f32_16x16x32_bf16 v[70:73], v[182:185], v[242:245], v[70:73]
	v_mfma_f32_16x16x32_bf16 v[122:125], v[186:189], v[214:217], v[122:125]
	v_mfma_f32_16x16x32_bf16 v[114:117], v[206:209], v[214:217], v[114:117]
	v_mfma_f32_16x16x32_bf16 v[106:109], v[186:189], v[222:225], v[106:109]
	v_mfma_f32_16x16x32_bf16 v[98:101], v[206:209], v[222:225], v[98:101]
	v_mfma_f32_16x16x32_bf16 v[90:93], v[186:189], v[230:233], v[90:93]
	v_mfma_f32_16x16x32_bf16 v[82:85], v[206:209], v[230:233], v[82:85]
	v_mfma_f32_16x16x32_bf16 v[74:77], v[186:189], v[238:241], v[74:77]
	v_mfma_f32_16x16x32_bf16 v[66:69], v[206:209], v[238:241], v[66:69]
	v_mfma_f32_16x16x32_bf16 v[122:125], v[202:205], v[218:221], v[122:125]
	v_mfma_f32_16x16x32_bf16 v[114:117], v[210:213], v[218:221], v[114:117]
	v_mfma_f32_16x16x32_bf16 v[106:109], v[202:205], v[226:229], v[106:109]
	v_mfma_f32_16x16x32_bf16 v[98:101], v[210:213], v[226:229], v[98:101]
	v_mfma_f32_16x16x32_bf16 v[90:93], v[202:205], v[234:237], v[90:93]
	v_mfma_f32_16x16x32_bf16 v[82:85], v[210:213], v[234:237], v[82:85]
	v_mfma_f32_16x16x32_bf16 v[74:77], v[202:205], v[242:245], v[74:77]
	v_mfma_f32_16x16x32_bf16 v[66:69], v[210:213], v[242:245], v[66:69]
	s_setprio 0
	s_barrier
	s_add_i32 s4, s1, s31
	v_lshl_add_u64 v[164:165], s[22:23], 0, v[154:155]
	s_mov_b32 m0, s4
	ds_read_b128 v[214:217], v168 offset:16384
	ds_read_b128 v[218:221], v168 offset:17408
	ds_read_b128 v[222:225], v168 offset:18432
	ds_read_b128 v[226:229], v168 offset:19456
	ds_read_b128 v[230:233], v168 offset:20480
	ds_read_b128 v[234:237], v168 offset:21504
	ds_read_b128 v[238:241], v168 offset:22528
	ds_read_b128 v[242:245], v168 offset:23552
	global_load_lds_dwordx4 v[164:165], off
	s_add_i32 m0, s4, 0x2000
	s_add_u32 s4, s22, 0x40000
	v_lshl_add_u64 v[246:247], s[22:23], 0, v[150:151]
	s_addc_u32 s5, s23, 0
	s_add_i32 s18, s26, s31
	global_load_lds_dwordx4 v[246:247], off
	v_lshl_add_u64 v[248:249], s[4:5], 0, v[154:155]
	s_mov_b32 m0, s18
	v_lshl_add_u64 v[250:251], s[24:25], 0, v[152:153]
	global_load_lds_dwordx4 v[248:249], off
	v_lshl_add_u64 v[248:249], s[4:5], 0, v[150:151]
	s_add_i32 m0, s18, 0x2000
	s_nop 0
	global_load_lds_dwordx4 v[248:249], off
	v_lshl_add_u64 v[248:249], s[24:25], 0, v[156:157]
	s_mov_b32 m0, s34
	s_nop 0
	global_load_lds_dwordx4 v[248:249], off
	s_mov_b32 m0, s35
	s_nop 0
	global_load_lds_dwordx4 v[250:251], off
	s_waitcnt vmcnt(8)
	s_waitcnt lgkmcnt(0)
	s_barrier
; #define PG8_STAGE(bufoff, gbase, voff) do { _Pragma("unroll") for (int _i = 0; _i < 2; ++_i) \
;         __builtin_amdgcn_global_load_lds((const unsigned*)((const char*)(gbase) + (voff)[_i]), (PG8_LAS unsigned*)(lds + (bufoff) + ldsw + _i * 8192), 16, 0, 0); } while (0)
; #define PG8_LDA(dst, b, h) do { _Pragma("unroll") for (int m = 0; m < 4; ++m) _Pragma("unroll") for (int k = 0; k < 2; ++k) dst[m][k] = *(const PG8_LAS bf16x8*)(lds + PG8_SA(b, h) + aoff + m * 2048 + k * 1024); } while (0)
; #define PG8_LDB(dst, b, h) do { _Pragma("unroll") for (int n = 0; n < 2; ++n) _Pragma("unroll") for (int k = 0; k < 2; ++k) dst[n][k] = *(const PG8_LAS bf16x8*)(lds + PG8_SB(b, h) + boff + n * 2048 + k * 1024); } while (0)
; #define PG8_MMA(ai, bj, At, Bt) do { __builtin_amdgcn_s_setprio(1); _Pragma("unroll") for (int m = 0; m < 4; ++m) _Pragma("unroll") for (int n = 0; n < 2; ++n) _Pragma("unroll") for (int k = 0; k < 2; ++k) \
;         acc[ai][bj][m][n] = __builtin_amdgcn_mfma_f32_16x16x32_bf16(Bt[n][k], At[m][k], acc[ai][bj][m][n], 0, 0, 0); __builtin_amdgcn_s_setprio(0); } while (0)
; #define PG8_WAIT_V(n) asm volatile("s_waitcnt vmcnt(" #n ")" ::: "memory")
; #define PG8_WAIT_L(n) asm volatile("s_waitcnt lgkmcnt(" #n ")" ::: "memory")
; #define PG8_BAR __builtin_amdgcn_s_barrier()
; #define PG8_SCHED __builtin_amdgcn_sched_barrier(0)
; template <class Epi, class Sched, bool ALIGN_EPI = false, bool SP2 = false>
; __device__ __forceinline__ void gemm_phase(PG8_LAS unsigned char* lds, const Gemm g, const Sched& S, const Epi& E) {
;     ...
;             PG8_WAIT_V(8); PG8_WAIT_L(0); PG8_BAR; PG8_MMA(1, 0, At, B0); PG8_MMA(1, 1, At, B1); PG8_BAR; PG8_SCHED;
;             PG8_LDB(B0, 1, 0); PG8_LDB(B1, 1, 1); PG8_SCHED; PG8_LDA(At, 1, 0); PG8_STAGE(PG8_SA(0, 1), a2 + hstep, voffA);
;             PG8_WAIT_V(8); PG8_WAIT_L(0); PG8_BAR; PG8_MMA(0, 0, At, B0); PG8_MMA(0, 1, At, B1); PG8_BAR; PG8_SCHED;
	s_setprio 1
	s_waitcnt lgkmcnt(0)
	v_mfma_f32_16x16x32_bf16 v[62:65], v[170:173], v[214:217], v[62:65]
	v_mfma_f32_16x16x32_bf16 v[54:57], v[178:181], v[214:217], v[54:57]
	v_mfma_f32_16x16x32_bf16 v[46:49], v[170:173], v[222:225], v[46:49]
	v_mfma_f32_16x16x32_bf16 v[38:41], v[178:181], v[222:225], v[38:41]
	v_mfma_f32_16x16x32_bf16 v[30:33], v[170:173], v[230:233], v[30:33]
	v_mfma_f32_16x16x32_bf16 v[22:25], v[178:181], v[230:233], v[22:25]
	v_mfma_f32_16x16x32_bf16 v[14:17], v[170:173], v[238:241], v[14:17]
	v_mfma_f32_16x16x32_bf16 v[6:9], v[178:181], v[238:241], v[6:9]
	v_mfma_f32_16x16x32_bf16 v[62:65], v[174:177], v[218:221], v[62:65]
	v_mfma_f32_16x16x32_bf16 v[54:57], v[182:185], v[218:221], v[54:57]
	v_mfma_f32_16x16x32_bf16 v[46:49], v[174:177], v[226:229], v[46:49]
	v_mfma_f32_16x16x32_bf16 v[38:41], v[182:185], v[226:229], v[38:41]
	v_mfma_f32_16x16x32_bf16 v[30:33], v[174:177], v[234:237], v[30:33]
	v_mfma_f32_16x16x32_bf16 v[22:25], v[182:185], v[234:237], v[22:25]
	v_mfma_f32_16x16x32_bf16 v[14:17], v[174:177], v[242:245], v[14:17]
	v_mfma_f32_16x16x32_bf16 v[6:9], v[182:185], v[242:245], v[6:9]
	v_mfma_f32_16x16x32_bf16 v[58:61], v[186:189], v[214:217], v[58:61]
	v_mfma_f32_16x16x32_bf16 v[50:53], v[206:209], v[214:217], v[50:53]
	v_mfma_f32_16x16x32_bf16 v[42:45], v[186:189], v[222:225], v[42:45]
	v_mfma_f32_16x16x32_bf16 v[34:37], v[206:209], v[222:225], v[34:37]
	v_mfma_f32_16x16x32_bf16 v[26:29], v[186:189], v[230:233], v[26:29]
	v_mfma_f32_16x16x32_bf16 v[18:21], v[206:209], v[230:233], v[18:21]
	v_mfma_f32_16x16x32_bf16 v[10:13], v[186:189], v[238:241], v[10:13]
	v_mfma_f32_16x16x32_bf16 v[2:5], v[206:209], v[238:241], v[2:5]
	v_mfma_f32_16x16x32_bf16 v[58:61], v[202:205], v[218:221], v[58:61]
	v_mfma_f32_16x16x32_bf16 v[50:53], v[210:213], v[218:221], v[50:53]
	v_mfma_f32_16x16x32_bf16 v[42:45], v[202:205], v[226:229], v[42:45]
	v_mfma_f32_16x16x32_bf16 v[34:37], v[210:213], v[226:229], v[34:37]
	v_mfma_f32_16x16x32_bf16 v[26:29], v[202:205], v[234:237], v[26:29]
	v_mfma_f32_16x16x32_bf16 v[18:21], v[210:213], v[234:237], v[18:21]
	v_mfma_f32_16x16x32_bf16 v[10:13], v[202:205], v[242:245], v[10:13]
	v_mfma_f32_16x16x32_bf16 v[2:5], v[210:213], v[242:245], v[2:5]
	s_setprio 0
	s_barrier
	s_add_i32 s27, 0, 0x18000
	v_add_u32_e32 v169, s27, v166
	s_add_i32 s28, 0, 0x1c000
	ds_read_b128 v[170:173], v169
	ds_read_b128 v[174:177], v169 offset:1024
	ds_read_b128 v[178:181], v169 offset:2048
	ds_read_b128 v[182:185], v169 offset:3072
	v_add_u32_e32 v169, s28, v166
	ds_read_b128 v[186:189], v169
	ds_read_b128 v[202:205], v169 offset:1024
	ds_read_b128 v[206:209], v169 offset:2048
	ds_read_b128 v[210:213], v169 offset:3072
	s_add_u32 s4, s24, 0x40000
	s_addc_u32 s5, s25, 0
	s_mov_b32 m0, s36
	v_lshl_add_u64 v[252:253], s[4:5], 0, v[156:157]
	ds_read_b128 v[214:217], v168 offset:32768
	ds_read_b128 v[218:221], v168 offset:33792
	ds_read_b128 v[222:225], v168 offset:34816
	ds_read_b128 v[226:229], v168 offset:35840
	ds_read_b128 v[230:233], v168 offset:36864
	ds_read_b128 v[234:237], v168 offset:37888
	ds_read_b128 v[238:241], v168 offset:38912
	ds_read_b128 v[242:245], v168 offset:39936
	global_load_lds_dwordx4 v[252:253], off
	v_lshl_add_u64 v[252:253], s[4:5], 0, v[152:153]
	s_mov_b32 m0, s37
	s_nop 0
	global_load_lds_dwordx4 v[252:253], off
	s_waitcnt vmcnt(8)
	s_waitcnt lgkmcnt(0)
	s_barrier
	s_setprio 1
	s_waitcnt lgkmcnt(0)
	v_mfma_f32_16x16x32_bf16 v[126:129], v[170:173], v[214:217], v[126:129]
	v_mfma_f32_16x16x32_bf16 v[118:121], v[178:181], v[214:217], v[118:121]
	v_mfma_f32_16x16x32_bf16 v[110:113], v[170:173], v[222:225], v[110:113]
	v_mfma_f32_16x16x32_bf16 v[102:105], v[178:181], v[222:225], v[102:105]
	v_mfma_f32_16x16x32_bf16 v[94:97], v[170:173], v[230:233], v[94:97]
	v_mfma_f32_16x16x32_bf16 v[86:89], v[178:181], v[230:233], v[86:89]
	v_mfma_f32_16x16x32_bf16 v[78:81], v[170:173], v[238:241], v[78:81]
	v_mfma_f32_16x16x32_bf16 v[70:73], v[178:181], v[238:241], v[70:73]
	v_mfma_f32_16x16x32_bf16 v[126:129], v[174:177], v[218:221], v[126:129]
	v_mfma_f32_16x16x32_bf16 v[118:121], v[182:185], v[218:221], v[118:121]
	v_mfma_f32_16x16x32_bf16 v[110:113], v[174:177], v[226:229], v[110:113]
	v_mfma_f32_16x16x32_bf16 v[102:105], v[182:185], v[226:229], v[102:105]
	v_mfma_f32_16x16x32_bf16 v[94:97], v[174:177], v[234:237], v[94:97]
	v_mfma_f32_16x16x32_bf16 v[86:89], v[182:185], v[234:237], v[86:89]
	v_mfma_f32_16x16x32_bf16 v[78:81], v[174:177], v[242:245], v[78:81]
	v_mfma_f32_16x16x32_bf16 v[70:73], v[182:185], v[242:245], v[70:73]
	v_mfma_f32_16x16x32_bf16 v[122:125], v[186:189], v[214:217], v[122:125]
	v_mfma_f32_16x16x32_bf16 v[114:117], v[206:209], v[214:217], v[114:117]
	v_mfma_f32_16x16x32_bf16 v[106:109], v[186:189], v[222:225], v[106:109]
	v_mfma_f32_16x16x32_bf16 v[98:101], v[206:209], v[222:225], v[98:101]
	v_mfma_f32_16x16x32_bf16 v[90:93], v[186:189], v[230:233], v[90:93]
	v_mfma_f32_16x16x32_bf16 v[82:85], v[206:209], v[230:233], v[82:85]
	v_mfma_f32_16x16x32_bf16 v[74:77], v[186:189], v[238:241], v[74:77]
	v_mfma_f32_16x16x32_bf16 v[66:69], v[206:209], v[238:241], v[66:69]
	v_mfma_f32_16x16x32_bf16 v[122:125], v[202:205], v[218:221], v[122:125]
	v_mfma_f32_16x16x32_bf16 v[114:117], v[210:213], v[218:221], v[114:117]
	v_mfma_f32_16x16x32_bf16 v[106:109], v[202:205], v[226:229], v[106:109]
	v_mfma_f32_16x16x32_bf16 v[98:101], v[210:213], v[226:229], v[98:101]
	v_mfma_f32_16x16x32_bf16 v[90:93], v[202:205], v[234:237], v[90:93]
	v_mfma_f32_16x16x32_bf16 v[82:85], v[210:213], v[234:237], v[82:85]
	v_mfma_f32_16x16x32_bf16 v[74:77], v[202:205], v[242:245], v[74:77]
	v_mfma_f32_16x16x32_bf16 v[66:69], v[210:213], v[242:245], v[66:69]
	s_setprio 0
	s_barrier
; #define PG8_STAGE(bufoff, gbase, voff) do { _Pragma("unroll") for (int _i = 0; _i < 2; ++_i) \
;         __builtin_amdgcn_global_load_lds((const unsigned*)((const char*)(gbase) + (voff)[_i]), (PG8_LAS unsigned*)(lds + (bufoff) + ldsw + _i * 8192), 16, 0, 0); } while (0)
; #define PG8_LDA(dst, b, h) do { _Pragma("unroll") for (int m = 0; m < 4; ++m) _Pragma("unroll") for (int k = 0; k < 2; ++k) dst[m][k] = *(const PG8_LAS bf16x8*)(lds + PG8_SA(b, h) + aoff + m * 2048 + k * 1024); } while (0)
; #define PG8_MMA(ai, bj, At, Bt) do { __builtin_amdgcn_s_setprio(1); _Pragma("unroll") for (int m = 0; m < 4; ++m) _Pragma("unroll") for (int n = 0; n < 2; ++n) _Pragma("unroll") for (int k = 0; k < 2; ++k) \
;         acc[ai][bj][m][n] = __builtin_amdgcn_mfma_f32_16x16x32_bf16(Bt[n][k], At[m][k], acc[ai][bj][m][n], 0, 0, 0); __builtin_amdgcn_s_setprio(0); } while (0)
; #define PG8_WAIT_V(n) asm volatile("s_waitcnt vmcnt(" #n ")" ::: "memory")
; #define PG8_WAIT_L(n) asm volatile("s_waitcnt lgkmcnt(" #n ")" ::: "memory")
; #define PG8_BAR __builtin_amdgcn_s_barrier()
; #define PG8_SCHED __builtin_amdgcn_sched_barrier(0)
; template <class Epi, class Sched, bool ALIGN_EPI = false, bool SP2 = false>
; __device__ __forceinline__ void gemm_phase(PG8_LAS unsigned char* lds, const Gemm g, const Sched& S, const Epi& E) {
;     ...
;             PG8_LDA(At, 1, 1); PG8_STAGE(PG8_SB(1, 0), b3, voffB); PG8_STAGE(PG8_SB(1, 1), b3 + hstep, voffB); PG8_STAGE(PG8_SA(1, 0), a3, voffA);
;             PG8_WAIT_V(8); PG8_WAIT_L(0); PG8_BAR; PG8_MMA(1, 0, At, B0); PG8_MMA(1, 1, At, B1); PG8_BAR; PG8_SCHED;
;     ...
;         }
;         if constexpr (ALIGN_EPI) { if (wr == 0) PG8_BAR; }
	s_add_i32 s4, s27, s31
	v_lshl_add_u64 v[164:165], v[164:165], 0, s[62:63]
	s_mov_b32 m0, s4
	ds_read_b128 v[214:217], v168 offset:49152
	ds_read_b128 v[218:221], v168 offset:50176
	ds_read_b128 v[222:225], v168 offset:51200
	ds_read_b128 v[226:229], v168 offset:52224
	ds_read_b128 v[230:233], v168 offset:53248
	ds_read_b128 v[234:237], v168 offset:54272
	ds_read_b128 v[238:241], v168 offset:55296
	ds_read_b128 v[242:245], v168 offset:56320
	global_load_lds_dwordx4 v[164:165], off
	s_add_i32 m0, s4, 0x2000
	s_add_u32 s4, s22, 0x40080
	v_lshl_add_u64 v[164:165], v[246:247], 0, s[62:63]
	s_addc_u32 s5, s23, 0
	s_add_i32 s18, s28, s31
	global_load_lds_dwordx4 v[164:165], off
	v_lshl_add_u64 v[164:165], s[4:5], 0, v[154:155]
	s_mov_b32 m0, s18
	s_nop 0
	global_load_lds_dwordx4 v[164:165], off
	v_lshl_add_u64 v[164:165], s[4:5], 0, v[150:151]
	s_add_i32 m0, s18, 0x2000
	s_nop 0
	global_load_lds_dwordx4 v[164:165], off
	v_lshl_add_u64 v[164:165], v[248:249], 0, s[62:63]
	s_mov_b32 m0, s41
	s_nop 0
	global_load_lds_dwordx4 v[164:165], off
	v_lshl_add_u64 v[164:165], v[250:251], 0, s[62:63]
	s_mov_b32 m0, s42
	s_nop 0
	global_load_lds_dwordx4 v[164:165], off
	s_waitcnt vmcnt(8)
	s_waitcnt lgkmcnt(0)
	s_barrier
	s_setprio 1
	s_waitcnt lgkmcnt(0)
	v_mfma_f32_16x16x32_bf16 v[62:65], v[170:173], v[214:217], v[62:65]
	v_mfma_f32_16x16x32_bf16 v[54:57], v[178:181], v[214:217], v[54:57]
	v_mfma_f32_16x16x32_bf16 v[46:49], v[170:173], v[222:225], v[46:49]
	v_mfma_f32_16x16x32_bf16 v[38:41], v[178:181], v[222:225], v[38:41]
	v_mfma_f32_16x16x32_bf16 v[30:33], v[170:173], v[230:233], v[30:33]
	v_mfma_f32_16x16x32_bf16 v[22:25], v[178:181], v[230:233], v[22:25]
	v_mfma_f32_16x16x32_bf16 v[14:17], v[170:173], v[238:241], v[14:17]
	v_mfma_f32_16x16x32_bf16 v[6:9], v[178:181], v[238:241], v[6:9]
	v_mfma_f32_16x16x32_bf16 v[62:65], v[174:177], v[218:221], v[62:65]
	v_mfma_f32_16x16x32_bf16 v[54:57], v[182:185], v[218:221], v[54:57]
	v_mfma_f32_16x16x32_bf16 v[46:49], v[174:177], v[226:229], v[46:49]
	v_mfma_f32_16x16x32_bf16 v[38:41], v[182:185], v[226:229], v[38:41]
	v_mfma_f32_16x16x32_bf16 v[30:33], v[174:177], v[234:237], v[30:33]
	v_mfma_f32_16x16x32_bf16 v[22:25], v[182:185], v[234:237], v[22:25]
	v_mfma_f32_16x16x32_bf16 v[14:17], v[174:177], v[242:245], v[14:17]
	v_mfma_f32_16x16x32_bf16 v[6:9], v[182:185], v[242:245], v[6:9]
	v_mfma_f32_16x16x32_bf16 v[58:61], v[186:189], v[214:217], v[58:61]
	v_mfma_f32_16x16x32_bf16 v[50:53], v[206:209], v[214:217], v[50:53]
	v_mfma_f32_16x16x32_bf16 v[42:45], v[186:189], v[222:225], v[42:45]
	v_mfma_f32_16x16x32_bf16 v[34:37], v[206:209], v[222:225], v[34:37]
	v_mfma_f32_16x16x32_bf16 v[26:29], v[186:189], v[230:233], v[26:29]
	v_mfma_f32_16x16x32_bf16 v[18:21], v[206:209], v[230:233], v[18:21]
	v_mfma_f32_16x16x32_bf16 v[10:13], v[186:189], v[238:241], v[10:13]
	v_mfma_f32_16x16x32_bf16 v[2:5], v[206:209], v[238:241], v[2:5]
	v_mfma_f32_16x16x32_bf16 v[58:61], v[202:205], v[218:221], v[58:61]
	v_mfma_f32_16x16x32_bf16 v[50:53], v[210:213], v[218:221], v[50:53]
	v_mfma_f32_16x16x32_bf16 v[42:45], v[202:205], v[226:229], v[42:45]
	v_mfma_f32_16x16x32_bf16 v[34:37], v[210:213], v[226:229], v[34:37]
	v_mfma_f32_16x16x32_bf16 v[26:29], v[202:205], v[234:237], v[26:29]
	v_mfma_f32_16x16x32_bf16 v[18:21], v[210:213], v[234:237], v[18:21]
	v_mfma_f32_16x16x32_bf16 v[10:13], v[202:205], v[242:245], v[10:13]
	v_mfma_f32_16x16x32_bf16 v[2:5], v[210:213], v[242:245], v[2:5]
	s_setprio 0
	s_barrier
	s_add_i32 s50, s50, 2
	s_add_u32 s20, s20, 0x100
	s_addc_u32 s21, s21, 0
	s_cmp_gt_u32 s50, 13
	s_cbranch_scc0 .LBB0_1387
	s_and_b64 vcc, exec, s[14:15]
	s_cbranch_vccz .LBB0_1390
	s_barrier

; #define PG8_STAGE(bufoff, gbase, voff) do { _Pragma("unroll") for (int _i = 0; _i < 2; ++_i) \
;         __builtin_amdgcn_global_load_lds((const unsigned*)((const char*)(gbase) + (voff)[_i]), (PG8_LAS unsigned*)(lds + (bufoff) + ldsw + _i * 8192), 16, 0, 0); } while (0)
; #define PG8_LDA(dst, b, h) do { _Pragma("unroll") for (int m = 0; m < 4; ++m) _Pragma("unroll") for (int k = 0; k < 2; ++k) dst[m][k] = *(const PG8_LAS bf16x8*)(lds + PG8_SA(b, h) + aoff + m * 2048 + k * 1024); } while (0)
; #define PG8_LDB(dst, b, h) do { _Pragma("unroll") for (int n = 0; n < 2; ++n) _Pragma("unroll") for (int k = 0; k < 2; ++k) dst[n][k] = *(const PG8_LAS bf16x8*)(lds + PG8_SB(b, h) + boff + n * 2048 + k * 1024); } while (0)
; #define PG8_MMA(ai, bj, At, Bt) do { __builtin_amdgcn_s_setprio(1); _Pragma("unroll") for (int m = 0; m < 4; ++m) _Pragma("unroll") for (int n = 0; n < 2; ++n) _Pragma("unroll") for (int k = 0; k < 2; ++k) \
;         acc[ai][bj][m][n] = __builtin_amdgcn_mfma_f32_16x16x32_bf16(Bt[n][k], At[m][k], acc[ai][bj][m][n], 0, 0, 0); __builtin_amdgcn_s_setprio(0); } while (0)
; #define PG8_WAIT_V(n) asm volatile("s_waitcnt vmcnt(" #n ")" ::: "memory")
; #define PG8_WAIT_L(n) asm volatile("s_waitcnt lgkmcnt(" #n ")" ::: "memory")
; template <class Epi, class Sched, bool ALIGN_EPI = false, bool SP2 = false>
; __device__ __forceinline__ void gemm_phase(PG8_LAS unsigned char* lds, const Gemm g, const Sched& S, const Epi& E) {
;     ...
;             const bool last = (t == nt - 2);
;             const char* a1 = cA + (size_t)(t + 1) * kstep;
;             const char* a2 = last ? nA : cA + (size_t)(t + 2) * kstep; const char* b2 = last ? nB : cB + (size_t)(t + 2) * kstep;
;             const char* a3 = a2 + kstep; const char* b3 = b2 + kstep;
;             if (last && has_next) S.a_ready(nxt);
;             if constexpr (SP2) {
;             PG8_LDB(B0, 0, 0); PG8_LDB(B1, 0, 1); PG8_SCHED; PG8_LDA(At, 0, 0); PG8_STAGE(PG8_SA(1, 1), a1 + hstep, voffA);
;             PG8_WAIT_V(8); PG8_WAIT_L(0); PG8_BAR; PG8_MMA(0, 0, At, B0); PG8_MMA(0, 1, At, B1); PG8_BAR; PG8_SCHED;
;             PG8_LDA(At, 0, 1); PG8_STAGE(PG8_SB(0, 0), b2, voffB); PG8_STAGE(PG8_SB(0, 1), b2 + hstep, voffB); PG8_STAGE(PG8_SA(0, 0), a2, voffA);
;             PG8_WAIT_V(8); PG8_WAIT_L(0); PG8_BAR; PG8_MMA(1, 0, At, B0); PG8_MMA(1, 1, At, B1); PG8_BAR; PG8_SCHED;
.LBB0_1415:
	v_add_u32_e32 v161, s1, v159
	ds_read_b128 v[162:165], v161
	ds_read_b128 v[166:169], v161 offset:1024
	ds_read_b128 v[170:173], v161 offset:2048
	ds_read_b128 v[174:177], v161 offset:3072
	v_add_u32_e32 v161, s26, v159
	s_add_u32 s4, s31, s10
	ds_read_b128 v[178:181], v161
	ds_read_b128 v[182:185], v161 offset:1024
	ds_read_b128 v[186:189], v161 offset:2048
	ds_read_b128 v[202:205], v161 offset:3072
	s_addc_u32 s5, s34, s11
	s_add_u32 s4, s4, 0x3d00100
	s_addc_u32 s5, s5, 0
	s_add_u32 s12, s35, s10
	s_addc_u32 s13, s36, s11
	s_cmpk_eq_i32 s10, 0xa00
	s_cselect_b32 s15, s7, s5
	s_cselect_b32 s14, s6, s4
	s_cselect_b32 s13, s9, s13
	s_cselect_b32 s12, s8, s12
	v_lshl_add_u64 v[238:239], v[154:155], 0, s[10:11]
	s_add_i32 m0, s20, 0xc000
	ds_read_b128 v[206:209], v160
	ds_read_b128 v[210:213], v160 offset:1024
	ds_read_b128 v[214:217], v160 offset:2048
	ds_read_b128 v[218:221], v160 offset:3072
	ds_read_b128 v[222:225], v160 offset:4096
	ds_read_b128 v[226:229], v160 offset:5120
	ds_read_b128 v[230:233], v160 offset:6144
	ds_read_b128 v[234:237], v160 offset:7168
	global_load_lds_dwordx4 v[238:239], off
	v_lshl_add_u64 v[238:239], v[156:157], 0, s[10:11]
	s_add_i32 m0, s20, 0xe000
	s_nop 0
	global_load_lds_dwordx4 v[238:239], off
	s_waitcnt vmcnt(8)
	s_waitcnt lgkmcnt(0)
	s_barrier
	s_setprio 1
	s_waitcnt lgkmcnt(0)
	v_mfma_f32_16x16x32_bf16 v[126:129], v[162:165], v[206:209], v[126:129]
	v_mfma_f32_16x16x32_bf16 v[122:125], v[170:173], v[206:209], v[122:125]
	v_mfma_f32_16x16x32_bf16 v[118:121], v[162:165], v[214:217], v[118:121]
	v_mfma_f32_16x16x32_bf16 v[114:117], v[170:173], v[214:217], v[114:117]
	v_mfma_f32_16x16x32_bf16 v[102:105], v[162:165], v[222:225], v[102:105]
	v_mfma_f32_16x16x32_bf16 v[98:101], v[170:173], v[222:225], v[98:101]
	v_mfma_f32_16x16x32_bf16 v[86:89], v[162:165], v[230:233], v[86:89]
	v_mfma_f32_16x16x32_bf16 v[82:85], v[170:173], v[230:233], v[82:85]
	v_mfma_f32_16x16x32_bf16 v[126:129], v[166:169], v[210:213], v[126:129]
	v_mfma_f32_16x16x32_bf16 v[122:125], v[174:177], v[210:213], v[122:125]
	v_mfma_f32_16x16x32_bf16 v[118:121], v[166:169], v[218:221], v[118:121]
	v_mfma_f32_16x16x32_bf16 v[114:117], v[174:177], v[218:221], v[114:117]
	v_mfma_f32_16x16x32_bf16 v[102:105], v[166:169], v[226:229], v[102:105]
	v_mfma_f32_16x16x32_bf16 v[98:101], v[174:177], v[226:229], v[98:101]
	v_mfma_f32_16x16x32_bf16 v[86:89], v[166:169], v[234:237], v[86:89]
	v_mfma_f32_16x16x32_bf16 v[82:85], v[174:177], v[234:237], v[82:85]
	v_mfma_f32_16x16x32_bf16 v[110:113], v[178:181], v[206:209], v[110:113]
	v_mfma_f32_16x16x32_bf16 v[106:109], v[186:189], v[206:209], v[106:109]
	v_mfma_f32_16x16x32_bf16 v[94:97], v[178:181], v[214:217], v[94:97]
	v_mfma_f32_16x16x32_bf16 v[90:93], v[186:189], v[214:217], v[90:93]
	v_mfma_f32_16x16x32_bf16 v[78:81], v[178:181], v[222:225], v[78:81]
	v_mfma_f32_16x16x32_bf16 v[74:77], v[186:189], v[222:225], v[74:77]
	v_mfma_f32_16x16x32_bf16 v[70:73], v[178:181], v[230:233], v[70:73]
	v_mfma_f32_16x16x32_bf16 v[66:69], v[186:189], v[230:233], v[66:69]
	v_mfma_f32_16x16x32_bf16 v[110:113], v[182:185], v[210:213], v[110:113]
	v_mfma_f32_16x16x32_bf16 v[106:109], v[202:205], v[210:213], v[106:109]
	v_mfma_f32_16x16x32_bf16 v[94:97], v[182:185], v[218:221], v[94:97]
	v_mfma_f32_16x16x32_bf16 v[90:93], v[202:205], v[218:221], v[90:93]
	v_mfma_f32_16x16x32_bf16 v[78:81], v[182:185], v[226:229], v[78:81]
	v_mfma_f32_16x16x32_bf16 v[74:77], v[202:205], v[226:229], v[74:77]
	v_mfma_f32_16x16x32_bf16 v[70:73], v[182:185], v[234:237], v[70:73]
	v_mfma_f32_16x16x32_bf16 v[66:69], v[202:205], v[234:237], v[66:69]
	s_setprio 0
	s_barrier
	s_add_i32 s4, s1, s19
	v_lshl_add_u64 v[238:239], s[12:13], 0, v[152:153]
	s_mov_b32 m0, s4
	ds_read_b128 v[206:209], v160 offset:16384
	ds_read_b128 v[210:213], v160 offset:17408
	ds_read_b128 v[214:217], v160 offset:18432
	ds_read_b128 v[218:221], v160 offset:19456
	ds_read_b128 v[222:225], v160 offset:20480
	ds_read_b128 v[226:229], v160 offset:21504
	ds_read_b128 v[230:233], v160 offset:22528
	ds_read_b128 v[234:237], v160 offset:23552
	global_load_lds_dwordx4 v[238:239], off
	s_add_i32 m0, s4, 0x2000
	s_add_u32 s4, s12, 0x58000
	v_lshl_add_u64 v[240:241], s[12:13], 0, v[150:151]
	s_addc_u32 s5, s13, 0
	s_add_i32 s38, s26, s19
	global_load_lds_dwordx4 v[240:241], off
	v_lshl_add_u64 v[242:243], s[4:5], 0, v[152:153]
	s_mov_b32 m0, s38
	v_lshl_add_u64 v[244:245], s[14:15], 0, v[150:151]
	global_load_lds_dwordx4 v[242:243], off
	v_lshl_add_u64 v[242:243], s[4:5], 0, v[150:151]
	s_add_i32 m0, s38, 0x2000
	s_nop 0
	global_load_lds_dwordx4 v[242:243], off
	v_lshl_add_u64 v[242:243], s[14:15], 0, v[152:153]
	s_mov_b32 m0, s20
	s_nop 0
	global_load_lds_dwordx4 v[242:243], off
	s_mov_b32 m0, s21
	s_nop 0
	global_load_lds_dwordx4 v[244:245], off
	s_waitcnt vmcnt(8)
	s_waitcnt lgkmcnt(0)
	s_barrier
; #define PG8_STAGE(bufoff, gbase, voff) do { _Pragma("unroll") for (int _i = 0; _i < 2; ++_i) \
;         __builtin_amdgcn_global_load_lds((const unsigned*)((const char*)(gbase) + (voff)[_i]), (PG8_LAS unsigned*)(lds + (bufoff) + ldsw + _i * 8192), 16, 0, 0); } while (0)
; #define PG8_LDA(dst, b, h) do { _Pragma("unroll") for (int m = 0; m < 4; ++m) _Pragma("unroll") for (int k = 0; k < 2; ++k) dst[m][k] = *(const PG8_LAS bf16x8*)(lds + PG8_SA(b, h) + aoff + m * 2048 + k * 1024); } while (0)
; #define PG8_LDB(dst, b, h) do { _Pragma("unroll") for (int n = 0; n < 2; ++n) _Pragma("unroll") for (int k = 0; k < 2; ++k) dst[n][k] = *(const PG8_LAS bf16x8*)(lds + PG8_SB(b, h) + boff + n * 2048 + k * 1024); } while (0)
; #define PG8_MMA(ai, bj, At, Bt) do { __builtin_amdgcn_s_setprio(1); _Pragma("unroll") for (int m = 0; m < 4; ++m) _Pragma("unroll") for (int n = 0; n < 2; ++n) _Pragma("unroll") for (int k = 0; k < 2; ++k) \
;         acc[ai][bj][m][n] = __builtin_amdgcn_mfma_f32_16x16x32_bf16(Bt[n][k], At[m][k], acc[ai][bj][m][n], 0, 0, 0); __builtin_amdgcn_s_setprio(0); } while (0)
; #define PG8_WAIT_V(n) asm volatile("s_waitcnt vmcnt(" #n ")" ::: "memory")
; #define PG8_WAIT_L(n) asm volatile("s_waitcnt lgkmcnt(" #n ")" ::: "memory")
; #define PG8_BAR __builtin_amdgcn_s_barrier()
; #define PG8_SCHED __builtin_amdgcn_sched_barrier(0)
; template <class Epi, class Sched, bool ALIGN_EPI = false, bool SP2 = false>
; __device__ __forceinline__ void gemm_phase(PG8_LAS unsigned char* lds, const Gemm g, const Sched& S, const Epi& E) {
;     ...
;             PG8_WAIT_V(8); PG8_WAIT_L(0); PG8_BAR; PG8_MMA(1, 0, At, B0); PG8_MMA(1, 1, At, B1); PG8_BAR; PG8_SCHED;
;             PG8_LDB(B0, 1, 0); PG8_LDB(B1, 1, 1); PG8_SCHED; PG8_LDA(At, 1, 0); PG8_STAGE(PG8_SA(0, 1), a2 + hstep, voffA);
;             PG8_WAIT_V(8); PG8_WAIT_L(0); PG8_BAR; PG8_MMA(0, 0, At, B0); PG8_MMA(0, 1, At, B1); PG8_BAR; PG8_SCHED;
	s_setprio 1
	s_waitcnt lgkmcnt(0)
	v_mfma_f32_16x16x32_bf16 v[62:65], v[162:165], v[206:209], v[62:65]
	v_mfma_f32_16x16x32_bf16 v[58:61], v[170:173], v[206:209], v[58:61]
	v_mfma_f32_16x16x32_bf16 v[54:57], v[162:165], v[214:217], v[54:57]
	v_mfma_f32_16x16x32_bf16 v[50:53], v[170:173], v[214:217], v[50:53]
	v_mfma_f32_16x16x32_bf16 v[38:41], v[162:165], v[222:225], v[38:41]
	v_mfma_f32_16x16x32_bf16 v[34:37], v[170:173], v[222:225], v[34:37]
	v_mfma_f32_16x16x32_bf16 v[22:25], v[162:165], v[230:233], v[22:25]
	v_mfma_f32_16x16x32_bf16 v[18:21], v[170:173], v[230:233], v[18:21]
	v_mfma_f32_16x16x32_bf16 v[62:65], v[166:169], v[210:213], v[62:65]
	v_mfma_f32_16x16x32_bf16 v[58:61], v[174:177], v[210:213], v[58:61]
	v_mfma_f32_16x16x32_bf16 v[54:57], v[166:169], v[218:221], v[54:57]
	v_mfma_f32_16x16x32_bf16 v[50:53], v[174:177], v[218:221], v[50:53]
	v_mfma_f32_16x16x32_bf16 v[38:41], v[166:169], v[226:229], v[38:41]
	v_mfma_f32_16x16x32_bf16 v[34:37], v[174:177], v[226:229], v[34:37]
	v_mfma_f32_16x16x32_bf16 v[22:25], v[166:169], v[234:237], v[22:25]
	v_mfma_f32_16x16x32_bf16 v[18:21], v[174:177], v[234:237], v[18:21]
	v_mfma_f32_16x16x32_bf16 v[46:49], v[178:181], v[206:209], v[46:49]
	v_mfma_f32_16x16x32_bf16 v[42:45], v[186:189], v[206:209], v[42:45]
	v_mfma_f32_16x16x32_bf16 v[30:33], v[178:181], v[214:217], v[30:33]
	v_mfma_f32_16x16x32_bf16 v[26:29], v[186:189], v[214:217], v[26:29]
	v_mfma_f32_16x16x32_bf16 v[14:17], v[178:181], v[222:225], v[14:17]
	v_mfma_f32_16x16x32_bf16 v[10:13], v[186:189], v[222:225], v[10:13]
	v_mfma_f32_16x16x32_bf16 v[6:9], v[178:181], v[230:233], v[6:9]
	v_mfma_f32_16x16x32_bf16 v[2:5], v[186:189], v[230:233], v[2:5]
	v_mfma_f32_16x16x32_bf16 v[46:49], v[182:185], v[210:213], v[46:49]
	v_mfma_f32_16x16x32_bf16 v[42:45], v[202:205], v[210:213], v[42:45]
	v_mfma_f32_16x16x32_bf16 v[30:33], v[182:185], v[218:221], v[30:33]
	v_mfma_f32_16x16x32_bf16 v[26:29], v[202:205], v[218:221], v[26:29]
	v_mfma_f32_16x16x32_bf16 v[14:17], v[182:185], v[226:229], v[14:17]
	v_mfma_f32_16x16x32_bf16 v[10:13], v[202:205], v[226:229], v[10:13]
	v_mfma_f32_16x16x32_bf16 v[6:9], v[182:185], v[234:237], v[6:9]
	v_mfma_f32_16x16x32_bf16 v[2:5], v[202:205], v[234:237], v[2:5]
	s_setprio 0
	s_barrier
	v_add_u32_e32 v161, s27, v159
	ds_read_b128 v[162:165], v161
	ds_read_b128 v[166:169], v161 offset:1024
	ds_read_b128 v[170:173], v161 offset:2048
	ds_read_b128 v[174:177], v161 offset:3072
	v_add_u32_e32 v161, s28, v159
	ds_read_b128 v[178:181], v161
	ds_read_b128 v[182:185], v161 offset:1024
	ds_read_b128 v[186:189], v161 offset:2048
	ds_read_b128 v[202:205], v161 offset:3072
	s_add_u32 s4, s14, 0x58000
	s_addc_u32 s5, s15, 0
	s_mov_b32 m0, s22
	v_lshl_add_u64 v[246:247], s[4:5], 0, v[152:153]
	ds_read_b128 v[206:209], v160 offset:32768
	ds_read_b128 v[210:213], v160 offset:33792
	ds_read_b128 v[214:217], v160 offset:34816
	ds_read_b128 v[218:221], v160 offset:35840
	ds_read_b128 v[222:225], v160 offset:36864
	ds_read_b128 v[226:229], v160 offset:37888
	ds_read_b128 v[230:233], v160 offset:38912
	ds_read_b128 v[234:237], v160 offset:39936
	global_load_lds_dwordx4 v[246:247], off
	v_lshl_add_u64 v[246:247], s[4:5], 0, v[150:151]
	s_mov_b32 m0, s23
	s_nop 0
	global_load_lds_dwordx4 v[246:247], off
	s_waitcnt vmcnt(8)
	s_waitcnt lgkmcnt(0)
	s_barrier
	s_setprio 1
	s_waitcnt lgkmcnt(0)
	v_mfma_f32_16x16x32_bf16 v[126:129], v[162:165], v[206:209], v[126:129]
	v_mfma_f32_16x16x32_bf16 v[122:125], v[170:173], v[206:209], v[122:125]
	v_mfma_f32_16x16x32_bf16 v[118:121], v[162:165], v[214:217], v[118:121]
	v_mfma_f32_16x16x32_bf16 v[114:117], v[170:173], v[214:217], v[114:117]
	v_mfma_f32_16x16x32_bf16 v[102:105], v[162:165], v[222:225], v[102:105]
	v_mfma_f32_16x16x32_bf16 v[98:101], v[170:173], v[222:225], v[98:101]
	v_mfma_f32_16x16x32_bf16 v[86:89], v[162:165], v[230:233], v[86:89]
	v_mfma_f32_16x16x32_bf16 v[82:85], v[170:173], v[230:233], v[82:85]
	v_mfma_f32_16x16x32_bf16 v[126:129], v[166:169], v[210:213], v[126:129]
	v_mfma_f32_16x16x32_bf16 v[122:125], v[174:177], v[210:213], v[122:125]
	v_mfma_f32_16x16x32_bf16 v[118:121], v[166:169], v[218:221], v[118:121]
	v_mfma_f32_16x16x32_bf16 v[114:117], v[174:177], v[218:221], v[114:117]
	v_mfma_f32_16x16x32_bf16 v[102:105], v[166:169], v[226:229], v[102:105]
	v_mfma_f32_16x16x32_bf16 v[98:101], v[174:177], v[226:229], v[98:101]
	v_mfma_f32_16x16x32_bf16 v[86:89], v[166:169], v[234:237], v[86:89]
	v_mfma_f32_16x16x32_bf16 v[82:85], v[174:177], v[234:237], v[82:85]
	v_mfma_f32_16x16x32_bf16 v[110:113], v[178:181], v[206:209], v[110:113]
	v_mfma_f32_16x16x32_bf16 v[106:109], v[186:189], v[206:209], v[106:109]
	v_mfma_f32_16x16x32_bf16 v[94:97], v[178:181], v[214:217], v[94:97]
	v_mfma_f32_16x16x32_bf16 v[90:93], v[186:189], v[214:217], v[90:93]
	v_mfma_f32_16x16x32_bf16 v[78:81], v[178:181], v[222:225], v[78:81]
	v_mfma_f32_16x16x32_bf16 v[74:77], v[186:189], v[222:225], v[74:77]
	v_mfma_f32_16x16x32_bf16 v[70:73], v[178:181], v[230:233], v[70:73]
	v_mfma_f32_16x16x32_bf16 v[66:69], v[186:189], v[230:233], v[66:69]
	v_mfma_f32_16x16x32_bf16 v[110:113], v[182:185], v[210:213], v[110:113]
	v_mfma_f32_16x16x32_bf16 v[106:109], v[202:205], v[210:213], v[106:109]
	v_mfma_f32_16x16x32_bf16 v[94:97], v[182:185], v[218:221], v[94:97]
	v_mfma_f32_16x16x32_bf16 v[90:93], v[202:205], v[218:221], v[90:93]
	v_mfma_f32_16x16x32_bf16 v[78:81], v[182:185], v[226:229], v[78:81]
	v_mfma_f32_16x16x32_bf16 v[74:77], v[202:205], v[226:229], v[74:77]
	v_mfma_f32_16x16x32_bf16 v[70:73], v[182:185], v[234:237], v[70:73]
	v_mfma_f32_16x16x32_bf16 v[66:69], v[202:205], v[234:237], v[66:69]
	s_setprio 0
	s_barrier
; #define PG8_STAGE(bufoff, gbase, voff) do { _Pragma("unroll") for (int _i = 0; _i < 2; ++_i) \
;         __builtin_amdgcn_global_load_lds((const unsigned*)((const char*)(gbase) + (voff)[_i]), (PG8_LAS unsigned*)(lds + (bufoff) + ldsw + _i * 8192), 16, 0, 0); } while (0)
; #define PG8_LDA(dst, b, h) do { _Pragma("unroll") for (int m = 0; m < 4; ++m) _Pragma("unroll") for (int k = 0; k < 2; ++k) dst[m][k] = *(const PG8_LAS bf16x8*)(lds + PG8_SA(b, h) + aoff + m * 2048 + k * 1024); } while (0)
; #define PG8_MMA(ai, bj, At, Bt) do { __builtin_amdgcn_s_setprio(1); _Pragma("unroll") for (int m = 0; m < 4; ++m) _Pragma("unroll") for (int n = 0; n < 2; ++n) _Pragma("unroll") for (int k = 0; k < 2; ++k) \
;         acc[ai][bj][m][n] = __builtin_amdgcn_mfma_f32_16x16x32_bf16(Bt[n][k], At[m][k], acc[ai][bj][m][n], 0, 0, 0); __builtin_amdgcn_s_setprio(0); } while (0)
; #define PG8_WAIT_V(n) asm volatile("s_waitcnt vmcnt(" #n ")" ::: "memory")
; #define PG8_WAIT_L(n) asm volatile("s_waitcnt lgkmcnt(" #n ")" ::: "memory")
; #define PG8_BAR __builtin_amdgcn_s_barrier()
; #define PG8_SCHED __builtin_amdgcn_sched_barrier(0)
; template <class Epi, class Sched, bool ALIGN_EPI = false, bool SP2 = false>
; __device__ __forceinline__ void gemm_phase(PG8_LAS unsigned char* lds, const Gemm g, const Sched& S, const Epi& E) {
;     ...
;             PG8_LDA(At, 1, 1); PG8_STAGE(PG8_SB(1, 0), b3, voffB); PG8_STAGE(PG8_SB(1, 1), b3 + hstep, voffB); PG8_STAGE(PG8_SA(1, 0), a3, voffA);
;             PG8_WAIT_V(8); PG8_WAIT_L(0); PG8_BAR; PG8_MMA(1, 0, At, B0); PG8_MMA(1, 1, At, B1); PG8_BAR; PG8_SCHED;
;     ...
;         }
;         if constexpr (ALIGN_EPI) { if (wr == 0) PG8_BAR; }
	s_add_i32 s4, s27, s19
	v_lshl_add_u64 v[238:239], v[238:239], 0, s[62:63]
	s_mov_b32 m0, s4
	ds_read_b128 v[206:209], v160 offset:49152
	ds_read_b128 v[210:213], v160 offset:50176
	ds_read_b128 v[214:217], v160 offset:51200
	ds_read_b128 v[218:221], v160 offset:52224
	ds_read_b128 v[222:225], v160 offset:53248
	ds_read_b128 v[226:229], v160 offset:54272
	ds_read_b128 v[230:233], v160 offset:55296
	ds_read_b128 v[234:237], v160 offset:56320
	global_load_lds_dwordx4 v[238:239], off
	s_add_i32 m0, s4, 0x2000
	s_add_u32 s4, s12, 0x58080
	v_lshl_add_u64 v[238:239], v[240:241], 0, s[62:63]
	s_addc_u32 s5, s13, 0
	s_add_i32 s12, s28, s19
	global_load_lds_dwordx4 v[238:239], off
	v_lshl_add_u64 v[238:239], s[4:5], 0, v[152:153]
	s_mov_b32 m0, s12
	s_nop 0
	global_load_lds_dwordx4 v[238:239], off
	v_lshl_add_u64 v[238:239], s[4:5], 0, v[150:151]
	s_add_i32 m0, s12, 0x2000
	s_nop 0
	global_load_lds_dwordx4 v[238:239], off
	v_lshl_add_u64 v[238:239], v[242:243], 0, s[62:63]
	s_mov_b32 m0, s29
	s_nop 0
	global_load_lds_dwordx4 v[238:239], off
	v_lshl_add_u64 v[238:239], v[244:245], 0, s[62:63]
	s_mov_b32 m0, s30
	s_nop 0
	global_load_lds_dwordx4 v[238:239], off
	s_waitcnt vmcnt(8)
	s_waitcnt lgkmcnt(0)
	s_barrier
	s_setprio 1
	s_waitcnt lgkmcnt(0)
	v_mfma_f32_16x16x32_bf16 v[62:65], v[162:165], v[206:209], v[62:65]
	v_mfma_f32_16x16x32_bf16 v[58:61], v[170:173], v[206:209], v[58:61]
	v_mfma_f32_16x16x32_bf16 v[54:57], v[162:165], v[214:217], v[54:57]
	v_mfma_f32_16x16x32_bf16 v[50:53], v[170:173], v[214:217], v[50:53]
	v_mfma_f32_16x16x32_bf16 v[38:41], v[162:165], v[222:225], v[38:41]
	v_mfma_f32_16x16x32_bf16 v[34:37], v[170:173], v[222:225], v[34:37]
	v_mfma_f32_16x16x32_bf16 v[22:25], v[162:165], v[230:233], v[22:25]
	v_mfma_f32_16x16x32_bf16 v[18:21], v[170:173], v[230:233], v[18:21]
	v_mfma_f32_16x16x32_bf16 v[62:65], v[166:169], v[210:213], v[62:65]
	v_mfma_f32_16x16x32_bf16 v[58:61], v[174:177], v[210:213], v[58:61]
	v_mfma_f32_16x16x32_bf16 v[54:57], v[166:169], v[218:221], v[54:57]
	v_mfma_f32_16x16x32_bf16 v[50:53], v[174:177], v[218:221], v[50:53]
	v_mfma_f32_16x16x32_bf16 v[38:41], v[166:169], v[226:229], v[38:41]
	v_mfma_f32_16x16x32_bf16 v[34:37], v[174:177], v[226:229], v[34:37]
	v_mfma_f32_16x16x32_bf16 v[22:25], v[166:169], v[234:237], v[22:25]
	v_mfma_f32_16x16x32_bf16 v[18:21], v[174:177], v[234:237], v[18:21]
	v_mfma_f32_16x16x32_bf16 v[46:49], v[178:181], v[206:209], v[46:49]
	v_mfma_f32_16x16x32_bf16 v[42:45], v[186:189], v[206:209], v[42:45]
	v_mfma_f32_16x16x32_bf16 v[30:33], v[178:181], v[214:217], v[30:33]
	v_mfma_f32_16x16x32_bf16 v[26:29], v[186:189], v[214:217], v[26:29]
	v_mfma_f32_16x16x32_bf16 v[14:17], v[178:181], v[222:225], v[14:17]
	v_mfma_f32_16x16x32_bf16 v[10:13], v[186:189], v[222:225], v[10:13]
	v_mfma_f32_16x16x32_bf16 v[6:9], v[178:181], v[230:233], v[6:9]
	v_mfma_f32_16x16x32_bf16 v[2:5], v[186:189], v[230:233], v[2:5]
	v_mfma_f32_16x16x32_bf16 v[46:49], v[182:185], v[210:213], v[46:49]
	v_mfma_f32_16x16x32_bf16 v[42:45], v[202:205], v[210:213], v[42:45]
	v_mfma_f32_16x16x32_bf16 v[30:33], v[182:185], v[218:221], v[30:33]
	v_mfma_f32_16x16x32_bf16 v[26:29], v[202:205], v[218:221], v[26:29]
	v_mfma_f32_16x16x32_bf16 v[14:17], v[182:185], v[226:229], v[14:17]
	v_mfma_f32_16x16x32_bf16 v[10:13], v[202:205], v[226:229], v[10:13]
	v_mfma_f32_16x16x32_bf16 v[6:9], v[182:185], v[234:237], v[6:9]
	v_mfma_f32_16x16x32_bf16 v[2:5], v[202:205], v[234:237], v[2:5]
	s_setprio 0
	s_barrier
	s_add_i32 s37, s37, 2
	s_add_u32 s10, s10, 0x100
	s_addc_u32 s11, s11, 0
	s_cmp_gt_u32 s37, 19
	s_cbranch_scc0 .LBB0_1415
	s_cmpk_lt_u32 s18, 0x100
	s_cbranch_scc0 .LBB0_1418
	s_barrier

; #define PG8_STAGE(bufoff, gbase, voff) do { _Pragma("unroll") for (int _i = 0; _i < 2; ++_i) \
;         __builtin_amdgcn_global_load_lds((const unsigned*)((const char*)(gbase) + (voff)[_i]), (PG8_LAS unsigned*)(lds + (bufoff) + ldsw + _i * 8192), 16, 0, 0); } while (0)
; #define PG8_LDA(dst, b, h) do { _Pragma("unroll") for (int m = 0; m < 4; ++m) _Pragma("unroll") for (int k = 0; k < 2; ++k) dst[m][k] = *(const PG8_LAS bf16x8*)(lds + PG8_SA(b, h) + aoff + m * 2048 + k * 1024); } while (0)
; #define PG8_LDB(dst, b, h) do { _Pragma("unroll") for (int n = 0; n < 2; ++n) _Pragma("unroll") for (int k = 0; k < 2; ++k) dst[n][k] = *(const PG8_LAS bf16x8*)(lds + PG8_SB(b, h) + boff + n * 2048 + k * 1024); } while (0)
; #define PG8_MMA(ai, bj, At, Bt) do { __builtin_amdgcn_s_setprio(1); _Pragma("unroll") for (int m = 0; m < 4; ++m) _Pragma("unroll") for (int n = 0; n < 2; ++n) _Pragma("unroll") for (int k = 0; k < 2; ++k) \
;         acc[ai][bj][m][n] = __builtin_amdgcn_mfma_f32_16x16x32_bf16(Bt[n][k], At[m][k], acc[ai][bj][m][n], 0, 0, 0); __builtin_amdgcn_s_setprio(0); } while (0)
; #define PG8_WAIT_V(n) asm volatile("s_waitcnt vmcnt(" #n ")" ::: "memory")
; #define PG8_WAIT_L(n) asm volatile("s_waitcnt lgkmcnt(" #n ")" ::: "memory")
; template <class Epi, class Sched, bool ALIGN_EPI = false, bool SP2 = false>
; __device__ __forceinline__ void gemm_phase(PG8_LAS unsigned char* lds, const Gemm g, const Sched& S, const Epi& E) {
;     ...
;             const bool last = (t == nt - 2);
;             const char* a1 = cA + (size_t)(t + 1) * kstep;
;             const char* a2 = last ? nA : cA + (size_t)(t + 2) * kstep; const char* b2 = last ? nB : cB + (size_t)(t + 2) * kstep;
;             const char* a3 = a2 + kstep; const char* b3 = b2 + kstep;
;             if (last && has_next) S.a_ready(nxt);
;             if constexpr (SP2) {
;             PG8_LDB(B0, 0, 0); PG8_LDB(B1, 0, 1); PG8_SCHED; PG8_LDA(At, 0, 0); PG8_STAGE(PG8_SA(1, 1), a1 + hstep, voffA);
;             PG8_WAIT_V(8); PG8_WAIT_L(0); PG8_BAR; PG8_MMA(0, 0, At, B0); PG8_MMA(0, 1, At, B1); PG8_BAR; PG8_SCHED;
;             PG8_LDA(At, 0, 1); PG8_STAGE(PG8_SB(0, 0), b2, voffB); PG8_STAGE(PG8_SB(0, 1), b2 + hstep, voffB); PG8_STAGE(PG8_SA(0, 0), a2, voffA);
;             PG8_WAIT_V(8); PG8_WAIT_L(0); PG8_BAR; PG8_MMA(1, 0, At, B0); PG8_MMA(1, 1, At, B1); PG8_BAR; PG8_SCHED;
.LBB0_1680:
	s_add_u32 s30, s28, 0x100
	s_addc_u32 s31, s29, 0
	s_add_i32 s4, 0, 0x10000
	s_cmp_eq_u32 s64, 12
	s_cselect_b32 s37, s23, s31
	s_cselect_b32 s36, s52, s30
	v_add_u32_e32 v165, s4, v162
	s_cselect_b32 s35, s21, s55
	s_cselect_b32 s34, s53, s54
	s_add_i32 s65, 0, 0x14000
	ds_read_b128 v[158:161], v165
	ds_read_b128 v[166:169], v165 offset:1024
	ds_read_b128 v[170:173], v165 offset:2048
	ds_read_b128 v[174:177], v165 offset:3072
	v_add_u32_e32 v165, s65, v162
	ds_read_b128 v[178:181], v165
	ds_read_b128 v[182:185], v165 offset:1024
	ds_read_b128 v[186:189], v165 offset:2048
	ds_read_b128 v[202:205], v165 offset:3072
	v_lshl_add_u64 v[238:239], s[28:29], 0, v[154:155]
	s_add_i32 m0, s41, 0xc000
	ds_read_b128 v[206:209], v164
	ds_read_b128 v[210:213], v164 offset:1024
	ds_read_b128 v[214:217], v164 offset:2048
	ds_read_b128 v[218:221], v164 offset:3072
	ds_read_b128 v[222:225], v164 offset:4096
	ds_read_b128 v[226:229], v164 offset:5120
	ds_read_b128 v[230:233], v164 offset:6144
	ds_read_b128 v[234:237], v164 offset:7168
	global_load_lds_dwordx4 v[238:239], off
	v_lshl_add_u64 v[238:239], s[28:29], 0, v[156:157]
	s_add_i32 m0, s41, 0xe000
	s_nop 0
	global_load_lds_dwordx4 v[238:239], off
	s_bfe_u32 s100, s64, 0x30001
	s_lshl_b32 s100, s100, 16
	v_add_u32_e32 v250, s100, v249
	global_load_dword v248, v250, s[14:15]
	s_waitcnt vmcnt(9)
	s_waitcnt lgkmcnt(0)
	s_barrier
	s_setprio 1
	s_waitcnt lgkmcnt(0)
	v_mfma_f32_16x16x32_bf16 v[126:129], v[158:161], v[206:209], v[126:129]
	v_mfma_f32_16x16x32_bf16 v[122:125], v[170:173], v[206:209], v[122:125]
	v_mfma_f32_16x16x32_bf16 v[110:113], v[158:161], v[214:217], v[110:113]
	v_mfma_f32_16x16x32_bf16 v[106:109], v[170:173], v[214:217], v[106:109]
	v_mfma_f32_16x16x32_bf16 v[94:97], v[158:161], v[222:225], v[94:97]
	v_mfma_f32_16x16x32_bf16 v[90:93], v[170:173], v[222:225], v[90:93]
	v_mfma_f32_16x16x32_bf16 v[78:81], v[158:161], v[230:233], v[78:81]
	v_mfma_f32_16x16x32_bf16 v[74:77], v[170:173], v[230:233], v[74:77]
	v_mfma_f32_16x16x32_bf16 v[126:129], v[166:169], v[210:213], v[126:129]
	v_mfma_f32_16x16x32_bf16 v[122:125], v[174:177], v[210:213], v[122:125]
	v_mfma_f32_16x16x32_bf16 v[110:113], v[166:169], v[218:221], v[110:113]
	v_mfma_f32_16x16x32_bf16 v[106:109], v[174:177], v[218:221], v[106:109]
	v_mfma_f32_16x16x32_bf16 v[94:97], v[166:169], v[226:229], v[94:97]
	v_mfma_f32_16x16x32_bf16 v[90:93], v[174:177], v[226:229], v[90:93]
	v_mfma_f32_16x16x32_bf16 v[78:81], v[166:169], v[234:237], v[78:81]
	v_mfma_f32_16x16x32_bf16 v[74:77], v[174:177], v[234:237], v[74:77]
	v_mfma_f32_16x16x32_bf16 v[118:121], v[178:181], v[206:209], v[118:121]
	v_mfma_f32_16x16x32_bf16 v[114:117], v[186:189], v[206:209], v[114:117]
	v_mfma_f32_16x16x32_bf16 v[102:105], v[178:181], v[214:217], v[102:105]
	v_mfma_f32_16x16x32_bf16 v[98:101], v[186:189], v[214:217], v[98:101]
	v_mfma_f32_16x16x32_bf16 v[86:89], v[178:181], v[222:225], v[86:89]
	v_mfma_f32_16x16x32_bf16 v[82:85], v[186:189], v[222:225], v[82:85]
	v_mfma_f32_16x16x32_bf16 v[70:73], v[178:181], v[230:233], v[70:73]
	v_mfma_f32_16x16x32_bf16 v[66:69], v[186:189], v[230:233], v[66:69]
	v_mfma_f32_16x16x32_bf16 v[118:121], v[182:185], v[210:213], v[118:121]
	v_mfma_f32_16x16x32_bf16 v[114:117], v[202:205], v[210:213], v[114:117]
	v_mfma_f32_16x16x32_bf16 v[102:105], v[182:185], v[218:221], v[102:105]
	v_mfma_f32_16x16x32_bf16 v[98:101], v[202:205], v[218:221], v[98:101]
	v_mfma_f32_16x16x32_bf16 v[86:89], v[182:185], v[226:229], v[86:89]
	v_mfma_f32_16x16x32_bf16 v[82:85], v[202:205], v[226:229], v[82:85]
	v_mfma_f32_16x16x32_bf16 v[70:73], v[182:185], v[234:237], v[70:73]
	v_mfma_f32_16x16x32_bf16 v[66:69], v[202:205], v[234:237], v[66:69]
	s_setprio 0
	s_barrier
	s_add_i32 s4, s4, s40
	v_lshl_add_u64 v[238:239], s[34:35], 0, v[152:153]
	s_mov_b32 m0, s4
	ds_read_b128 v[206:209], v164 offset:16384
	ds_read_b128 v[210:213], v164 offset:17408
	ds_read_b128 v[214:217], v164 offset:18432
	ds_read_b128 v[218:221], v164 offset:19456
	ds_read_b128 v[222:225], v164 offset:20480
	ds_read_b128 v[226:229], v164 offset:21504
	ds_read_b128 v[230:233], v164 offset:22528
	ds_read_b128 v[234:237], v164 offset:23552
	global_load_lds_dwordx4 v[238:239], off
	s_add_i32 m0, s4, 0x2000
	s_add_u32 s4, s34, 0x40000
	v_lshl_add_u64 v[240:241], s[34:35], 0, v[150:151]
	s_addc_u32 s5, s35, 0
	s_add_i32 s28, s65, s40
	global_load_lds_dwordx4 v[240:241], off
	v_lshl_add_u64 v[242:243], s[4:5], 0, v[152:153]
	s_mov_b32 m0, s28
	v_lshl_add_u64 v[244:245], s[36:37], 0, v[150:151]
	global_load_lds_dwordx4 v[242:243], off
	v_lshl_add_u64 v[242:243], s[4:5], 0, v[150:151]
	s_add_i32 m0, s28, 0x2000
	s_nop 0
	global_load_lds_dwordx4 v[242:243], off
	v_lshl_add_u64 v[242:243], s[36:37], 0, v[152:153]
	s_mov_b32 m0, s41
	s_nop 0
	global_load_lds_dwordx4 v[242:243], off
	s_mov_b32 m0, s42
	s_nop 0
	global_load_lds_dwordx4 v[244:245], off
	s_waitcnt vmcnt(9)
	s_waitcnt lgkmcnt(0)
	s_barrier
; #define PG8_STAGE(bufoff, gbase, voff) do { _Pragma("unroll") for (int _i = 0; _i < 2; ++_i) \
;         __builtin_amdgcn_global_load_lds((const unsigned*)((const char*)(gbase) + (voff)[_i]), (PG8_LAS unsigned*)(lds + (bufoff) + ldsw + _i * 8192), 16, 0, 0); } while (0)
; #define PG8_LDA(dst, b, h) do { _Pragma("unroll") for (int m = 0; m < 4; ++m) _Pragma("unroll") for (int k = 0; k < 2; ++k) dst[m][k] = *(const PG8_LAS bf16x8*)(lds + PG8_SA(b, h) + aoff + m * 2048 + k * 1024); } while (0)
; #define PG8_LDB(dst, b, h) do { _Pragma("unroll") for (int n = 0; n < 2; ++n) _Pragma("unroll") for (int k = 0; k < 2; ++k) dst[n][k] = *(const PG8_LAS bf16x8*)(lds + PG8_SB(b, h) + boff + n * 2048 + k * 1024); } while (0)
; #define PG8_MMA(ai, bj, At, Bt) do { __builtin_amdgcn_s_setprio(1); _Pragma("unroll") for (int m = 0; m < 4; ++m) _Pragma("unroll") for (int n = 0; n < 2; ++n) _Pragma("unroll") for (int k = 0; k < 2; ++k) \
;         acc[ai][bj][m][n] = __builtin_amdgcn_mfma_f32_16x16x32_bf16(Bt[n][k], At[m][k], acc[ai][bj][m][n], 0, 0, 0); __builtin_amdgcn_s_setprio(0); } while (0)
; #define PG8_WAIT_V(n) asm volatile("s_waitcnt vmcnt(" #n ")" ::: "memory")
; #define PG8_WAIT_L(n) asm volatile("s_waitcnt lgkmcnt(" #n ")" ::: "memory")
; #define PG8_BAR __builtin_amdgcn_s_barrier()
; #define PG8_SCHED __builtin_amdgcn_sched_barrier(0)
; template <class Epi, class Sched, bool ALIGN_EPI = false, bool SP2 = false>
; __device__ __forceinline__ void gemm_phase(PG8_LAS unsigned char* lds, const Gemm g, const Sched& S, const Epi& E) {
;     ...
;             PG8_WAIT_V(8); PG8_WAIT_L(0); PG8_BAR; PG8_MMA(1, 0, At, B0); PG8_MMA(1, 1, At, B1); PG8_BAR; PG8_SCHED;
;             PG8_LDB(B0, 1, 0); PG8_LDB(B1, 1, 1); PG8_SCHED; PG8_LDA(At, 1, 0); PG8_STAGE(PG8_SA(0, 1), a2 + hstep, voffA);
;             PG8_WAIT_V(8); PG8_WAIT_L(0); PG8_BAR; PG8_MMA(0, 0, At, B0); PG8_MMA(0, 1, At, B1); PG8_BAR; PG8_SCHED;
	s_setprio 1
	s_waitcnt lgkmcnt(0)
	v_mfma_f32_16x16x32_bf16 v[62:65], v[158:161], v[206:209], v[62:65]
	v_mfma_f32_16x16x32_bf16 v[58:61], v[170:173], v[206:209], v[58:61]
	v_mfma_f32_16x16x32_bf16 v[46:49], v[158:161], v[214:217], v[46:49]
	v_mfma_f32_16x16x32_bf16 v[42:45], v[170:173], v[214:217], v[42:45]
	v_mfma_f32_16x16x32_bf16 v[30:33], v[158:161], v[222:225], v[30:33]
	v_mfma_f32_16x16x32_bf16 v[26:29], v[170:173], v[222:225], v[26:29]
	v_mfma_f32_16x16x32_bf16 v[14:17], v[158:161], v[230:233], v[14:17]
	v_mfma_f32_16x16x32_bf16 v[10:13], v[170:173], v[230:233], v[10:13]
	v_mfma_f32_16x16x32_bf16 v[62:65], v[166:169], v[210:213], v[62:65]
	v_mfma_f32_16x16x32_bf16 v[58:61], v[174:177], v[210:213], v[58:61]
	v_mfma_f32_16x16x32_bf16 v[46:49], v[166:169], v[218:221], v[46:49]
	v_mfma_f32_16x16x32_bf16 v[42:45], v[174:177], v[218:221], v[42:45]
	v_mfma_f32_16x16x32_bf16 v[30:33], v[166:169], v[226:229], v[30:33]
	v_mfma_f32_16x16x32_bf16 v[26:29], v[174:177], v[226:229], v[26:29]
	v_mfma_f32_16x16x32_bf16 v[14:17], v[166:169], v[234:237], v[14:17]
	v_mfma_f32_16x16x32_bf16 v[10:13], v[174:177], v[234:237], v[10:13]
	v_mfma_f32_16x16x32_bf16 v[54:57], v[178:181], v[206:209], v[54:57]
	v_mfma_f32_16x16x32_bf16 v[50:53], v[186:189], v[206:209], v[50:53]
	v_mfma_f32_16x16x32_bf16 v[38:41], v[178:181], v[214:217], v[38:41]
	v_mfma_f32_16x16x32_bf16 v[34:37], v[186:189], v[214:217], v[34:37]
	v_mfma_f32_16x16x32_bf16 v[22:25], v[178:181], v[222:225], v[22:25]
	v_mfma_f32_16x16x32_bf16 v[18:21], v[186:189], v[222:225], v[18:21]
	v_mfma_f32_16x16x32_bf16 v[6:9], v[178:181], v[230:233], v[6:9]
	v_mfma_f32_16x16x32_bf16 v[2:5], v[186:189], v[230:233], v[2:5]
	v_mfma_f32_16x16x32_bf16 v[54:57], v[182:185], v[210:213], v[54:57]
	v_mfma_f32_16x16x32_bf16 v[50:53], v[202:205], v[210:213], v[50:53]
	v_mfma_f32_16x16x32_bf16 v[38:41], v[182:185], v[218:221], v[38:41]
	v_mfma_f32_16x16x32_bf16 v[34:37], v[202:205], v[218:221], v[34:37]
	v_mfma_f32_16x16x32_bf16 v[22:25], v[182:185], v[226:229], v[22:25]
	v_mfma_f32_16x16x32_bf16 v[18:21], v[202:205], v[226:229], v[18:21]
	v_mfma_f32_16x16x32_bf16 v[6:9], v[182:185], v[234:237], v[6:9]
	v_mfma_f32_16x16x32_bf16 v[2:5], v[202:205], v[234:237], v[2:5]
	s_setprio 0
	s_barrier
	s_add_i32 s28, 0, 0x18000
	v_add_u32_e32 v165, s28, v162
	s_add_i32 s29, 0, 0x1c000
	ds_read_b128 v[158:161], v165
	ds_read_b128 v[166:169], v165 offset:1024
	ds_read_b128 v[170:173], v165 offset:2048
	ds_read_b128 v[174:177], v165 offset:3072
	v_add_u32_e32 v165, s29, v162
	ds_read_b128 v[178:181], v165
	ds_read_b128 v[182:185], v165 offset:1024
	ds_read_b128 v[186:189], v165 offset:2048
	ds_read_b128 v[202:205], v165 offset:3072
	s_add_u32 s4, s36, 0x40000
	s_addc_u32 s5, s37, 0
	s_mov_b32 m0, s43
	v_lshl_add_u64 v[246:247], s[4:5], 0, v[152:153]
	ds_read_b128 v[206:209], v164 offset:32768
	ds_read_b128 v[210:213], v164 offset:33792
	ds_read_b128 v[214:217], v164 offset:34816
	ds_read_b128 v[218:221], v164 offset:35840
	ds_read_b128 v[222:225], v164 offset:36864
	ds_read_b128 v[226:229], v164 offset:37888
	ds_read_b128 v[230:233], v164 offset:38912
	ds_read_b128 v[234:237], v164 offset:39936
	global_load_lds_dwordx4 v[246:247], off
	v_lshl_add_u64 v[246:247], s[4:5], 0, v[150:151]
	s_mov_b32 m0, s44
	s_nop 0
	global_load_lds_dwordx4 v[246:247], off
	s_waitcnt vmcnt(9)
	s_waitcnt lgkmcnt(0)
	s_barrier
	s_setprio 1
	s_waitcnt lgkmcnt(0)
	v_mfma_f32_16x16x32_bf16 v[126:129], v[158:161], v[206:209], v[126:129]
	v_mfma_f32_16x16x32_bf16 v[122:125], v[170:173], v[206:209], v[122:125]
	v_mfma_f32_16x16x32_bf16 v[110:113], v[158:161], v[214:217], v[110:113]
	v_mfma_f32_16x16x32_bf16 v[106:109], v[170:173], v[214:217], v[106:109]
	v_mfma_f32_16x16x32_bf16 v[94:97], v[158:161], v[222:225], v[94:97]
	v_mfma_f32_16x16x32_bf16 v[90:93], v[170:173], v[222:225], v[90:93]
	v_mfma_f32_16x16x32_bf16 v[78:81], v[158:161], v[230:233], v[78:81]
	v_mfma_f32_16x16x32_bf16 v[74:77], v[170:173], v[230:233], v[74:77]
	v_mfma_f32_16x16x32_bf16 v[126:129], v[166:169], v[210:213], v[126:129]
	v_mfma_f32_16x16x32_bf16 v[122:125], v[174:177], v[210:213], v[122:125]
	v_mfma_f32_16x16x32_bf16 v[110:113], v[166:169], v[218:221], v[110:113]
	v_mfma_f32_16x16x32_bf16 v[106:109], v[174:177], v[218:221], v[106:109]
	v_mfma_f32_16x16x32_bf16 v[94:97], v[166:169], v[226:229], v[94:97]
	v_mfma_f32_16x16x32_bf16 v[90:93], v[174:177], v[226:229], v[90:93]
	v_mfma_f32_16x16x32_bf16 v[78:81], v[166:169], v[234:237], v[78:81]
	v_mfma_f32_16x16x32_bf16 v[74:77], v[174:177], v[234:237], v[74:77]
	v_mfma_f32_16x16x32_bf16 v[118:121], v[178:181], v[206:209], v[118:121]
	v_mfma_f32_16x16x32_bf16 v[114:117], v[186:189], v[206:209], v[114:117]
	v_mfma_f32_16x16x32_bf16 v[102:105], v[178:181], v[214:217], v[102:105]
	v_mfma_f32_16x16x32_bf16 v[98:101], v[186:189], v[214:217], v[98:101]
	v_mfma_f32_16x16x32_bf16 v[86:89], v[178:181], v[222:225], v[86:89]
	v_mfma_f32_16x16x32_bf16 v[82:85], v[186:189], v[222:225], v[82:85]
	v_mfma_f32_16x16x32_bf16 v[70:73], v[178:181], v[230:233], v[70:73]
	v_mfma_f32_16x16x32_bf16 v[66:69], v[186:189], v[230:233], v[66:69]
	v_mfma_f32_16x16x32_bf16 v[118:121], v[182:185], v[210:213], v[118:121]
	v_mfma_f32_16x16x32_bf16 v[114:117], v[202:205], v[210:213], v[114:117]
	v_mfma_f32_16x16x32_bf16 v[102:105], v[182:185], v[218:221], v[102:105]
	v_mfma_f32_16x16x32_bf16 v[98:101], v[202:205], v[218:221], v[98:101]
	v_mfma_f32_16x16x32_bf16 v[86:89], v[182:185], v[226:229], v[86:89]
	v_mfma_f32_16x16x32_bf16 v[82:85], v[202:205], v[226:229], v[82:85]
	v_mfma_f32_16x16x32_bf16 v[70:73], v[182:185], v[234:237], v[70:73]
	v_mfma_f32_16x16x32_bf16 v[66:69], v[202:205], v[234:237], v[66:69]
	s_setprio 0
	s_barrier
; #define PG8_STAGE(bufoff, gbase, voff) do { _Pragma("unroll") for (int _i = 0; _i < 2; ++_i) \
;         __builtin_amdgcn_global_load_lds((const unsigned*)((const char*)(gbase) + (voff)[_i]), (PG8_LAS unsigned*)(lds + (bufoff) + ldsw + _i * 8192), 16, 0, 0); } while (0)
; #define PG8_LDA(dst, b, h) do { _Pragma("unroll") for (int m = 0; m < 4; ++m) _Pragma("unroll") for (int k = 0; k < 2; ++k) dst[m][k] = *(const PG8_LAS bf16x8*)(lds + PG8_SA(b, h) + aoff + m * 2048 + k * 1024); } while (0)
; #define PG8_MMA(ai, bj, At, Bt) do { __builtin_amdgcn_s_setprio(1); _Pragma("unroll") for (int m = 0; m < 4; ++m) _Pragma("unroll") for (int n = 0; n < 2; ++n) _Pragma("unroll") for (int k = 0; k < 2; ++k) \
;         acc[ai][bj][m][n] = __builtin_amdgcn_mfma_f32_16x16x32_bf16(Bt[n][k], At[m][k], acc[ai][bj][m][n], 0, 0, 0); __builtin_amdgcn_s_setprio(0); } while (0)
; #define PG8_WAIT_V(n) asm volatile("s_waitcnt vmcnt(" #n ")" ::: "memory")
; #define PG8_WAIT_L(n) asm volatile("s_waitcnt lgkmcnt(" #n ")" ::: "memory")
; #define PG8_BAR __builtin_amdgcn_s_barrier()
; #define PG8_SCHED __builtin_amdgcn_sched_barrier(0)
; template <class Epi, class Sched, bool ALIGN_EPI = false, bool SP2 = false>
; __device__ __forceinline__ void gemm_phase(PG8_LAS unsigned char* lds, const Gemm g, const Sched& S, const Epi& E) {
;     ...
;             PG8_LDA(At, 1, 1); PG8_STAGE(PG8_SB(1, 0), b3, voffB); PG8_STAGE(PG8_SB(1, 1), b3 + hstep, voffB); PG8_STAGE(PG8_SA(1, 0), a3, voffA);
;             PG8_WAIT_V(8); PG8_WAIT_L(0); PG8_BAR; PG8_MMA(1, 0, At, B0); PG8_MMA(1, 1, At, B1); PG8_BAR; PG8_SCHED;
;     ...
;         }
;         if constexpr (ALIGN_EPI) { if (wr == 0) PG8_BAR; }
	s_add_i32 s4, s28, s40
	v_lshl_add_u64 v[238:239], v[238:239], 0, s[62:63]
	s_mov_b32 m0, s4
	ds_read_b128 v[206:209], v164 offset:49152
	ds_read_b128 v[210:213], v164 offset:50176
	ds_read_b128 v[214:217], v164 offset:51200
	ds_read_b128 v[218:221], v164 offset:52224
	ds_read_b128 v[222:225], v164 offset:53248
	ds_read_b128 v[226:229], v164 offset:54272
	ds_read_b128 v[230:233], v164 offset:55296
	ds_read_b128 v[234:237], v164 offset:56320
	global_load_lds_dwordx4 v[238:239], off
	s_add_i32 m0, s4, 0x2000
	s_add_u32 s4, s34, 0x40080
	v_lshl_add_u64 v[238:239], v[240:241], 0, s[62:63]
	s_addc_u32 s5, s35, 0
	s_add_i32 s28, s29, s40
	global_load_lds_dwordx4 v[238:239], off
	v_lshl_add_u64 v[238:239], s[4:5], 0, v[152:153]
	s_mov_b32 m0, s28
	s_nop 0
	global_load_lds_dwordx4 v[238:239], off
	v_lshl_add_u64 v[238:239], s[4:5], 0, v[150:151]
	s_add_i32 m0, s28, 0x2000
	s_nop 0
	global_load_lds_dwordx4 v[238:239], off
	v_lshl_add_u64 v[238:239], v[242:243], 0, s[62:63]
	s_mov_b32 m0, s47
	s_nop 0
	global_load_lds_dwordx4 v[238:239], off
	v_lshl_add_u64 v[238:239], v[244:245], 0, s[62:63]
	s_mov_b32 m0, s48
	s_nop 0
	global_load_lds_dwordx4 v[238:239], off
	s_waitcnt vmcnt(8)
	s_waitcnt lgkmcnt(0)
	s_barrier
	s_setprio 1
	s_waitcnt lgkmcnt(0)
	v_mfma_f32_16x16x32_bf16 v[62:65], v[158:161], v[206:209], v[62:65]
	v_mfma_f32_16x16x32_bf16 v[58:61], v[170:173], v[206:209], v[58:61]
	v_mfma_f32_16x16x32_bf16 v[46:49], v[158:161], v[214:217], v[46:49]
	v_mfma_f32_16x16x32_bf16 v[42:45], v[170:173], v[214:217], v[42:45]
	v_mfma_f32_16x16x32_bf16 v[30:33], v[158:161], v[222:225], v[30:33]
	v_mfma_f32_16x16x32_bf16 v[26:29], v[170:173], v[222:225], v[26:29]
	v_mfma_f32_16x16x32_bf16 v[14:17], v[158:161], v[230:233], v[14:17]
	v_mfma_f32_16x16x32_bf16 v[10:13], v[170:173], v[230:233], v[10:13]
	v_mfma_f32_16x16x32_bf16 v[62:65], v[166:169], v[210:213], v[62:65]
	v_mfma_f32_16x16x32_bf16 v[58:61], v[174:177], v[210:213], v[58:61]
	v_mfma_f32_16x16x32_bf16 v[46:49], v[166:169], v[218:221], v[46:49]
	v_mfma_f32_16x16x32_bf16 v[42:45], v[174:177], v[218:221], v[42:45]
	v_mfma_f32_16x16x32_bf16 v[30:33], v[166:169], v[226:229], v[30:33]
	v_mfma_f32_16x16x32_bf16 v[26:29], v[174:177], v[226:229], v[26:29]
	v_mfma_f32_16x16x32_bf16 v[14:17], v[166:169], v[234:237], v[14:17]
	v_mfma_f32_16x16x32_bf16 v[10:13], v[174:177], v[234:237], v[10:13]
	v_mfma_f32_16x16x32_bf16 v[54:57], v[178:181], v[206:209], v[54:57]
	v_mfma_f32_16x16x32_bf16 v[50:53], v[186:189], v[206:209], v[50:53]
	v_mfma_f32_16x16x32_bf16 v[38:41], v[178:181], v[214:217], v[38:41]
	v_mfma_f32_16x16x32_bf16 v[34:37], v[186:189], v[214:217], v[34:37]
	v_mfma_f32_16x16x32_bf16 v[22:25], v[178:181], v[222:225], v[22:25]
	v_mfma_f32_16x16x32_bf16 v[18:21], v[186:189], v[222:225], v[18:21]
	v_mfma_f32_16x16x32_bf16 v[6:9], v[178:181], v[230:233], v[6:9]
	v_mfma_f32_16x16x32_bf16 v[2:5], v[186:189], v[230:233], v[2:5]
	v_mfma_f32_16x16x32_bf16 v[54:57], v[182:185], v[210:213], v[54:57]
	v_mfma_f32_16x16x32_bf16 v[50:53], v[202:205], v[210:213], v[50:53]
	v_mfma_f32_16x16x32_bf16 v[38:41], v[182:185], v[218:221], v[38:41]
	v_mfma_f32_16x16x32_bf16 v[34:37], v[202:205], v[218:221], v[34:37]
	v_mfma_f32_16x16x32_bf16 v[22:25], v[182:185], v[226:229], v[22:25]
	v_mfma_f32_16x16x32_bf16 v[18:21], v[202:205], v[226:229], v[18:21]
	v_mfma_f32_16x16x32_bf16 v[6:9], v[182:185], v[234:237], v[6:9]
	v_mfma_f32_16x16x32_bf16 v[2:5], v[202:205], v[234:237], v[2:5]
	s_setprio 0
	s_barrier
	s_add_i32 s64, s64, 2
	s_add_u32 s54, s54, 0x100
	s_addc_u32 s55, s55, 0
	s_cmp_gt_u32 s64, 13
	s_mov_b64 s[28:29], s[30:31]
	s_cbranch_scc0 .LBB0_1680
	s_and_b64 vcc, exec, s[18:19]
	s_cbranch_vccz .LBB0_1683
	s_barrier

; #define PG8_STAGE(bufoff, gbase, voff) do { _Pragma("unroll") for (int _i = 0; _i < 2; ++_i) \
;         __builtin_amdgcn_global_load_lds((const unsigned*)((const char*)(gbase) + (voff)[_i]), (PG8_LAS unsigned*)(lds + (bufoff) + ldsw + _i * 8192), 16, 0, 0); } while (0)
; #define PG8_LDA(dst, b, h) do { _Pragma("unroll") for (int m = 0; m < 4; ++m) _Pragma("unroll") for (int k = 0; k < 2; ++k) dst[m][k] = *(const PG8_LAS bf16x8*)(lds + PG8_SA(b, h) + aoff + m * 2048 + k * 1024); } while (0)
; #define PG8_LDB(dst, b, h) do { _Pragma("unroll") for (int n = 0; n < 2; ++n) _Pragma("unroll") for (int k = 0; k < 2; ++k) dst[n][k] = *(const PG8_LAS bf16x8*)(lds + PG8_SB(b, h) + boff + n * 2048 + k * 1024); } while (0)
; #define PG8_MMA(ai, bj, At, Bt) do { __builtin_amdgcn_s_setprio(1); _Pragma("unroll") for (int m = 0; m < 4; ++m) _Pragma("unroll") for (int n = 0; n < 2; ++n) _Pragma("unroll") for (int k = 0; k < 2; ++k) \
;         acc[ai][bj][m][n] = __builtin_amdgcn_mfma_f32_16x16x32_bf16(Bt[n][k], At[m][k], acc[ai][bj][m][n], 0, 0, 0); __builtin_amdgcn_s_setprio(0); } while (0)
; #define PG8_WAIT_V(n) asm volatile("s_waitcnt vmcnt(" #n ")" ::: "memory")
; #define PG8_WAIT_L(n) asm volatile("s_waitcnt lgkmcnt(" #n ")" ::: "memory")
; template <class Epi, class Sched, bool ALIGN_EPI = false, bool SP2 = false>
; __device__ __forceinline__ void gemm_phase(PG8_LAS unsigned char* lds, const Gemm g, const Sched& S, const Epi& E) {
;     ...
;             const bool last = (t == nt - 2);
;             const char* a1 = cA + (size_t)(t + 1) * kstep;
;             const char* a2 = last ? nA : cA + (size_t)(t + 2) * kstep; const char* b2 = last ? nB : cB + (size_t)(t + 2) * kstep;
;             const char* a3 = a2 + kstep; const char* b3 = b2 + kstep;
;             if (last && has_next) S.a_ready(nxt);
;             if constexpr (SP2) {
;             PG8_LDB(B0, 0, 0); PG8_LDB(B1, 0, 1); PG8_SCHED; PG8_LDA(At, 0, 0); PG8_STAGE(PG8_SA(1, 1), a1 + hstep, voffA);
;             PG8_WAIT_V(8); PG8_WAIT_L(0); PG8_BAR; PG8_MMA(0, 0, At, B0); PG8_MMA(0, 1, At, B1); PG8_BAR; PG8_SCHED;
;             PG8_LDA(At, 0, 1); PG8_STAGE(PG8_SB(0, 0), b2, voffB); PG8_STAGE(PG8_SB(0, 1), b2 + hstep, voffB); PG8_STAGE(PG8_SA(0, 0), a2, voffA);
;             PG8_WAIT_V(8); PG8_WAIT_L(0); PG8_BAR; PG8_MMA(1, 0, At, B0); PG8_MMA(1, 1, At, B1); PG8_BAR; PG8_SCHED;
.LBB0_1764:
	s_add_u32 s4, s12, 0xfffc0080
	s_addc_u32 s5, s13, -1
	s_add_i32 s55, 0, 0x10000
	s_cmp_eq_u32 s54, 12
	s_cselect_b32 s31, s23, s5
	s_cselect_b32 s30, s50, s4
	v_add_u32_e32 v171, s55, v168
	s_cselect_b32 s29, s21, s53
	s_cselect_b32 s28, s51, s52
	s_add_i32 s64, 0, 0x14000
	ds_read_b128 v[164:167], v171
	ds_read_b128 v[172:175], v171 offset:1024
	ds_read_b128 v[176:179], v171 offset:2048
	ds_read_b128 v[180:183], v171 offset:3072
	v_add_u32_e32 v171, s64, v168
	ds_read_b128 v[184:187], v171
	ds_read_b128 v[202:205], v171 offset:1024
	ds_read_b128 v[206:209], v171 offset:2048
	ds_read_b128 v[210:213], v171 offset:3072
	v_lshl_add_u64 v[188:189], s[12:13], 0, v[160:161]
	s_add_i32 m0, s37, 0xc000
	ds_read_b128 v[214:217], v170
	ds_read_b128 v[218:221], v170 offset:1024
	ds_read_b128 v[222:225], v170 offset:2048
	ds_read_b128 v[226:229], v170 offset:3072
	ds_read_b128 v[230:233], v170 offset:4096
	ds_read_b128 v[234:237], v170 offset:5120
	ds_read_b128 v[238:241], v170 offset:6144
	ds_read_b128 v[242:245], v170 offset:7168
	global_load_lds_dwordx4 v[188:189], off
	v_lshl_add_u64 v[188:189], s[12:13], 0, v[162:163]
	s_add_i32 m0, s37, 0xe000
	s_nop 0
	global_load_lds_dwordx4 v[188:189], off
	s_waitcnt vmcnt(8)
	s_waitcnt lgkmcnt(0)
	s_barrier
	s_setprio 1
	s_waitcnt lgkmcnt(0)
	v_mfma_f32_16x16x32_bf16 v[126:129], v[164:167], v[214:217], v[126:129]
	v_mfma_f32_16x16x32_bf16 v[114:117], v[176:179], v[214:217], v[114:117]
	v_mfma_f32_16x16x32_bf16 v[110:113], v[164:167], v[222:225], v[110:113]
	v_mfma_f32_16x16x32_bf16 v[98:101], v[176:179], v[222:225], v[98:101]
	v_mfma_f32_16x16x32_bf16 v[94:97], v[164:167], v[230:233], v[94:97]
	v_mfma_f32_16x16x32_bf16 v[82:85], v[176:179], v[230:233], v[82:85]
	v_mfma_f32_16x16x32_bf16 v[78:81], v[164:167], v[238:241], v[78:81]
	v_mfma_f32_16x16x32_bf16 v[66:69], v[176:179], v[238:241], v[66:69]
	v_mfma_f32_16x16x32_bf16 v[126:129], v[172:175], v[218:221], v[126:129]
	v_mfma_f32_16x16x32_bf16 v[114:117], v[180:183], v[218:221], v[114:117]
	v_mfma_f32_16x16x32_bf16 v[110:113], v[172:175], v[226:229], v[110:113]
	v_mfma_f32_16x16x32_bf16 v[98:101], v[180:183], v[226:229], v[98:101]
	v_mfma_f32_16x16x32_bf16 v[94:97], v[172:175], v[234:237], v[94:97]
	v_mfma_f32_16x16x32_bf16 v[82:85], v[180:183], v[234:237], v[82:85]
	v_mfma_f32_16x16x32_bf16 v[78:81], v[172:175], v[242:245], v[78:81]
	v_mfma_f32_16x16x32_bf16 v[66:69], v[180:183], v[242:245], v[66:69]
	v_mfma_f32_16x16x32_bf16 v[122:125], v[184:187], v[214:217], v[122:125]
	v_mfma_f32_16x16x32_bf16 v[118:121], v[206:209], v[214:217], v[118:121]
	v_mfma_f32_16x16x32_bf16 v[106:109], v[184:187], v[222:225], v[106:109]
	v_mfma_f32_16x16x32_bf16 v[102:105], v[206:209], v[222:225], v[102:105]
	v_mfma_f32_16x16x32_bf16 v[90:93], v[184:187], v[230:233], v[90:93]
	v_mfma_f32_16x16x32_bf16 v[86:89], v[206:209], v[230:233], v[86:89]
	v_mfma_f32_16x16x32_bf16 v[74:77], v[184:187], v[238:241], v[74:77]
	v_mfma_f32_16x16x32_bf16 v[70:73], v[206:209], v[238:241], v[70:73]
	v_mfma_f32_16x16x32_bf16 v[122:125], v[202:205], v[218:221], v[122:125]
	v_mfma_f32_16x16x32_bf16 v[118:121], v[210:213], v[218:221], v[118:121]
	v_mfma_f32_16x16x32_bf16 v[106:109], v[202:205], v[226:229], v[106:109]
	v_mfma_f32_16x16x32_bf16 v[102:105], v[210:213], v[226:229], v[102:105]
	v_mfma_f32_16x16x32_bf16 v[90:93], v[202:205], v[234:237], v[90:93]
	v_mfma_f32_16x16x32_bf16 v[86:89], v[210:213], v[234:237], v[86:89]
	v_mfma_f32_16x16x32_bf16 v[74:77], v[202:205], v[242:245], v[74:77]
	v_mfma_f32_16x16x32_bf16 v[70:73], v[210:213], v[242:245], v[70:73]
	s_setprio 0
	s_barrier
	s_add_i32 s4, s55, s36
	v_lshl_add_u64 v[188:189], s[28:29], 0, v[154:155]
	s_mov_b32 m0, s4
	ds_read_b128 v[214:217], v170 offset:16384
	ds_read_b128 v[218:221], v170 offset:17408
	ds_read_b128 v[222:225], v170 offset:18432
	ds_read_b128 v[226:229], v170 offset:19456
	ds_read_b128 v[230:233], v170 offset:20480
	ds_read_b128 v[234:237], v170 offset:21504
	ds_read_b128 v[238:241], v170 offset:22528
	ds_read_b128 v[242:245], v170 offset:23552
	global_load_lds_dwordx4 v[188:189], off
	s_add_i32 m0, s4, 0x2000
	s_add_u32 s4, s28, 0x40000
	v_lshl_add_u64 v[246:247], s[28:29], 0, v[150:151]
	s_addc_u32 s5, s29, 0
	s_add_i32 s55, s64, s36
	global_load_lds_dwordx4 v[246:247], off
	v_lshl_add_u64 v[248:249], s[4:5], 0, v[154:155]
	s_mov_b32 m0, s55
	v_lshl_add_u64 v[250:251], s[30:31], 0, v[152:153]
	global_load_lds_dwordx4 v[248:249], off
	v_lshl_add_u64 v[248:249], s[4:5], 0, v[150:151]
	s_add_i32 m0, s55, 0x2000
	s_nop 0
	global_load_lds_dwordx4 v[248:249], off
	v_lshl_add_u64 v[248:249], s[30:31], 0, v[156:157]
	s_mov_b32 m0, s37
	s_nop 0
	global_load_lds_dwordx4 v[248:249], off
	s_mov_b32 m0, s38
	s_nop 0
	global_load_lds_dwordx4 v[250:251], off
	s_waitcnt vmcnt(8)
	s_waitcnt lgkmcnt(0)
	s_barrier
; #define PG8_STAGE(bufoff, gbase, voff) do { _Pragma("unroll") for (int _i = 0; _i < 2; ++_i) \
;         __builtin_amdgcn_global_load_lds((const unsigned*)((const char*)(gbase) + (voff)[_i]), (PG8_LAS unsigned*)(lds + (bufoff) + ldsw + _i * 8192), 16, 0, 0); } while (0)
; #define PG8_LDA(dst, b, h) do { _Pragma("unroll") for (int m = 0; m < 4; ++m) _Pragma("unroll") for (int k = 0; k < 2; ++k) dst[m][k] = *(const PG8_LAS bf16x8*)(lds + PG8_SA(b, h) + aoff + m * 2048 + k * 1024); } while (0)
; #define PG8_LDB(dst, b, h) do { _Pragma("unroll") for (int n = 0; n < 2; ++n) _Pragma("unroll") for (int k = 0; k < 2; ++k) dst[n][k] = *(const PG8_LAS bf16x8*)(lds + PG8_SB(b, h) + boff + n * 2048 + k * 1024); } while (0)
; #define PG8_MMA(ai, bj, At, Bt) do { __builtin_amdgcn_s_setprio(1); _Pragma("unroll") for (int m = 0; m < 4; ++m) _Pragma("unroll") for (int n = 0; n < 2; ++n) _Pragma("unroll") for (int k = 0; k < 2; ++k) \
;         acc[ai][bj][m][n] = __builtin_amdgcn_mfma_f32_16x16x32_bf16(Bt[n][k], At[m][k], acc[ai][bj][m][n], 0, 0, 0); __builtin_amdgcn_s_setprio(0); } while (0)
; #define PG8_WAIT_V(n) asm volatile("s_waitcnt vmcnt(" #n ")" ::: "memory")
; #define PG8_WAIT_L(n) asm volatile("s_waitcnt lgkmcnt(" #n ")" ::: "memory")
; #define PG8_BAR __builtin_amdgcn_s_barrier()
; #define PG8_SCHED __builtin_amdgcn_sched_barrier(0)
; template <class Epi, class Sched, bool ALIGN_EPI = false, bool SP2 = false>
; __device__ __forceinline__ void gemm_phase(PG8_LAS unsigned char* lds, const Gemm g, const Sched& S, const Epi& E) {
;     ...
;             PG8_WAIT_V(8); PG8_WAIT_L(0); PG8_BAR; PG8_MMA(1, 0, At, B0); PG8_MMA(1, 1, At, B1); PG8_BAR; PG8_SCHED;
;             PG8_LDB(B0, 1, 0); PG8_LDB(B1, 1, 1); PG8_SCHED; PG8_LDA(At, 1, 0); PG8_STAGE(PG8_SA(0, 1), a2 + hstep, voffA);
;             PG8_WAIT_V(8); PG8_WAIT_L(0); PG8_BAR; PG8_MMA(0, 0, At, B0); PG8_MMA(0, 1, At, B1); PG8_BAR; PG8_SCHED;
	s_setprio 1
	s_waitcnt lgkmcnt(0)
	v_mfma_f32_16x16x32_bf16 v[62:65], v[164:167], v[214:217], v[62:65]
	v_mfma_f32_16x16x32_bf16 v[50:53], v[176:179], v[214:217], v[50:53]
	v_mfma_f32_16x16x32_bf16 v[46:49], v[164:167], v[222:225], v[46:49]
	v_mfma_f32_16x16x32_bf16 v[34:37], v[176:179], v[222:225], v[34:37]
	v_mfma_f32_16x16x32_bf16 v[30:33], v[164:167], v[230:233], v[30:33]
	v_mfma_f32_16x16x32_bf16 v[18:21], v[176:179], v[230:233], v[18:21]
	v_mfma_f32_16x16x32_bf16 v[14:17], v[164:167], v[238:241], v[14:17]
	v_mfma_f32_16x16x32_bf16 v[6:9], v[176:179], v[238:241], v[6:9]
	v_mfma_f32_16x16x32_bf16 v[62:65], v[172:175], v[218:221], v[62:65]
	v_mfma_f32_16x16x32_bf16 v[50:53], v[180:183], v[218:221], v[50:53]
	v_mfma_f32_16x16x32_bf16 v[46:49], v[172:175], v[226:229], v[46:49]
	v_mfma_f32_16x16x32_bf16 v[34:37], v[180:183], v[226:229], v[34:37]
	v_mfma_f32_16x16x32_bf16 v[30:33], v[172:175], v[234:237], v[30:33]
	v_mfma_f32_16x16x32_bf16 v[18:21], v[180:183], v[234:237], v[18:21]
	v_mfma_f32_16x16x32_bf16 v[14:17], v[172:175], v[242:245], v[14:17]
	v_mfma_f32_16x16x32_bf16 v[6:9], v[180:183], v[242:245], v[6:9]
	v_mfma_f32_16x16x32_bf16 v[58:61], v[184:187], v[214:217], v[58:61]
	v_mfma_f32_16x16x32_bf16 v[54:57], v[206:209], v[214:217], v[54:57]
	v_mfma_f32_16x16x32_bf16 v[42:45], v[184:187], v[222:225], v[42:45]
	v_mfma_f32_16x16x32_bf16 v[38:41], v[206:209], v[222:225], v[38:41]
	v_mfma_f32_16x16x32_bf16 v[26:29], v[184:187], v[230:233], v[26:29]
	v_mfma_f32_16x16x32_bf16 v[22:25], v[206:209], v[230:233], v[22:25]
	v_mfma_f32_16x16x32_bf16 v[10:13], v[184:187], v[238:241], v[10:13]
	v_mfma_f32_16x16x32_bf16 v[2:5], v[206:209], v[238:241], v[2:5]
	v_mfma_f32_16x16x32_bf16 v[58:61], v[202:205], v[218:221], v[58:61]
	v_mfma_f32_16x16x32_bf16 v[54:57], v[210:213], v[218:221], v[54:57]
	v_mfma_f32_16x16x32_bf16 v[42:45], v[202:205], v[226:229], v[42:45]
	v_mfma_f32_16x16x32_bf16 v[38:41], v[210:213], v[226:229], v[38:41]
	v_mfma_f32_16x16x32_bf16 v[26:29], v[202:205], v[234:237], v[26:29]
	v_mfma_f32_16x16x32_bf16 v[22:25], v[210:213], v[234:237], v[22:25]
	v_mfma_f32_16x16x32_bf16 v[10:13], v[202:205], v[242:245], v[10:13]
	v_mfma_f32_16x16x32_bf16 v[2:5], v[210:213], v[242:245], v[2:5]
	s_setprio 0
	s_barrier
	s_add_i32 s55, 0, 0x18000
	v_add_u32_e32 v171, s55, v168
	s_add_i32 s64, 0, 0x1c000
	ds_read_b128 v[164:167], v171
	ds_read_b128 v[172:175], v171 offset:1024
	ds_read_b128 v[176:179], v171 offset:2048
	ds_read_b128 v[180:183], v171 offset:3072
	v_add_u32_e32 v171, s64, v168
	ds_read_b128 v[184:187], v171
	ds_read_b128 v[202:205], v171 offset:1024
	ds_read_b128 v[206:209], v171 offset:2048
	ds_read_b128 v[210:213], v171 offset:3072
	s_add_u32 s4, s30, 0x40000
	s_addc_u32 s5, s31, 0
	s_mov_b32 m0, s39
	v_lshl_add_u64 v[252:253], s[4:5], 0, v[156:157]
	ds_read_b128 v[214:217], v170 offset:32768
	ds_read_b128 v[218:221], v170 offset:33792
	ds_read_b128 v[222:225], v170 offset:34816
	ds_read_b128 v[226:229], v170 offset:35840
	ds_read_b128 v[230:233], v170 offset:36864
	ds_read_b128 v[234:237], v170 offset:37888
	ds_read_b128 v[238:241], v170 offset:38912
	ds_read_b128 v[242:245], v170 offset:39936
	global_load_lds_dwordx4 v[252:253], off
	v_lshl_add_u64 v[252:253], s[4:5], 0, v[152:153]
	s_mov_b32 m0, s40
	s_nop 0
	global_load_lds_dwordx4 v[252:253], off
	s_waitcnt vmcnt(8)
	s_waitcnt lgkmcnt(0)
	s_barrier
	s_setprio 1
	s_waitcnt lgkmcnt(0)
	v_mfma_f32_16x16x32_bf16 v[126:129], v[164:167], v[214:217], v[126:129]
	v_mfma_f32_16x16x32_bf16 v[114:117], v[176:179], v[214:217], v[114:117]
	v_mfma_f32_16x16x32_bf16 v[110:113], v[164:167], v[222:225], v[110:113]
	v_mfma_f32_16x16x32_bf16 v[98:101], v[176:179], v[222:225], v[98:101]
	v_mfma_f32_16x16x32_bf16 v[94:97], v[164:167], v[230:233], v[94:97]
	v_mfma_f32_16x16x32_bf16 v[82:85], v[176:179], v[230:233], v[82:85]
	v_mfma_f32_16x16x32_bf16 v[78:81], v[164:167], v[238:241], v[78:81]
	v_mfma_f32_16x16x32_bf16 v[66:69], v[176:179], v[238:241], v[66:69]
	v_mfma_f32_16x16x32_bf16 v[126:129], v[172:175], v[218:221], v[126:129]
	v_mfma_f32_16x16x32_bf16 v[114:117], v[180:183], v[218:221], v[114:117]
	v_mfma_f32_16x16x32_bf16 v[110:113], v[172:175], v[226:229], v[110:113]
	v_mfma_f32_16x16x32_bf16 v[98:101], v[180:183], v[226:229], v[98:101]
	v_mfma_f32_16x16x32_bf16 v[94:97], v[172:175], v[234:237], v[94:97]
	v_mfma_f32_16x16x32_bf16 v[82:85], v[180:183], v[234:237], v[82:85]
	v_mfma_f32_16x16x32_bf16 v[78:81], v[172:175], v[242:245], v[78:81]
	v_mfma_f32_16x16x32_bf16 v[66:69], v[180:183], v[242:245], v[66:69]
	v_mfma_f32_16x16x32_bf16 v[122:125], v[184:187], v[214:217], v[122:125]
	v_mfma_f32_16x16x32_bf16 v[118:121], v[206:209], v[214:217], v[118:121]
	v_mfma_f32_16x16x32_bf16 v[106:109], v[184:187], v[222:225], v[106:109]
	v_mfma_f32_16x16x32_bf16 v[102:105], v[206:209], v[222:225], v[102:105]
	v_mfma_f32_16x16x32_bf16 v[90:93], v[184:187], v[230:233], v[90:93]
	v_mfma_f32_16x16x32_bf16 v[86:89], v[206:209], v[230:233], v[86:89]
	v_mfma_f32_16x16x32_bf16 v[74:77], v[184:187], v[238:241], v[74:77]
	v_mfma_f32_16x16x32_bf16 v[70:73], v[206:209], v[238:241], v[70:73]
	v_mfma_f32_16x16x32_bf16 v[122:125], v[202:205], v[218:221], v[122:125]
	v_mfma_f32_16x16x32_bf16 v[118:121], v[210:213], v[218:221], v[118:121]
	v_mfma_f32_16x16x32_bf16 v[106:109], v[202:205], v[226:229], v[106:109]
	v_mfma_f32_16x16x32_bf16 v[102:105], v[210:213], v[226:229], v[102:105]
	v_mfma_f32_16x16x32_bf16 v[90:93], v[202:205], v[234:237], v[90:93]
	v_mfma_f32_16x16x32_bf16 v[86:89], v[210:213], v[234:237], v[86:89]
	v_mfma_f32_16x16x32_bf16 v[74:77], v[202:205], v[242:245], v[74:77]
	v_mfma_f32_16x16x32_bf16 v[70:73], v[210:213], v[242:245], v[70:73]
	s_setprio 0
	s_barrier
; #define PG8_STAGE(bufoff, gbase, voff) do { _Pragma("unroll") for (int _i = 0; _i < 2; ++_i) \
;         __builtin_amdgcn_global_load_lds((const unsigned*)((const char*)(gbase) + (voff)[_i]), (PG8_LAS unsigned*)(lds + (bufoff) + ldsw + _i * 8192), 16, 0, 0); } while (0)
; #define PG8_LDA(dst, b, h) do { _Pragma("unroll") for (int m = 0; m < 4; ++m) _Pragma("unroll") for (int k = 0; k < 2; ++k) dst[m][k] = *(const PG8_LAS bf16x8*)(lds + PG8_SA(b, h) + aoff + m * 2048 + k * 1024); } while (0)
; #define PG8_MMA(ai, bj, At, Bt) do { __builtin_amdgcn_s_setprio(1); _Pragma("unroll") for (int m = 0; m < 4; ++m) _Pragma("unroll") for (int n = 0; n < 2; ++n) _Pragma("unroll") for (int k = 0; k < 2; ++k) \
;         acc[ai][bj][m][n] = __builtin_amdgcn_mfma_f32_16x16x32_bf16(Bt[n][k], At[m][k], acc[ai][bj][m][n], 0, 0, 0); __builtin_amdgcn_s_setprio(0); } while (0)
; #define PG8_WAIT_V(n) asm volatile("s_waitcnt vmcnt(" #n ")" ::: "memory")
; #define PG8_WAIT_L(n) asm volatile("s_waitcnt lgkmcnt(" #n ")" ::: "memory")
; #define PG8_BAR __builtin_amdgcn_s_barrier()
; #define PG8_SCHED __builtin_amdgcn_sched_barrier(0)
; template <class Epi, class Sched, bool ALIGN_EPI = false, bool SP2 = false>
; __device__ __forceinline__ void gemm_phase(PG8_LAS unsigned char* lds, const Gemm g, const Sched& S, const Epi& E) {
;     ...
;             PG8_LDA(At, 1, 1); PG8_STAGE(PG8_SB(1, 0), b3, voffB); PG8_STAGE(PG8_SB(1, 1), b3 + hstep, voffB); PG8_STAGE(PG8_SA(1, 0), a3, voffA);
;             PG8_WAIT_V(8); PG8_WAIT_L(0); PG8_BAR; PG8_MMA(1, 0, At, B0); PG8_MMA(1, 1, At, B1); PG8_BAR; PG8_SCHED;
;     ...
;         }
;         if constexpr (ALIGN_EPI) { if (wr == 0) PG8_BAR; }
	s_add_i32 s4, s55, s36
	v_lshl_add_u64 v[188:189], v[188:189], 0, s[62:63]
	s_mov_b32 m0, s4
	ds_read_b128 v[214:217], v170 offset:49152
	ds_read_b128 v[218:221], v170 offset:50176
	ds_read_b128 v[222:225], v170 offset:51200
	ds_read_b128 v[226:229], v170 offset:52224
	ds_read_b128 v[230:233], v170 offset:53248
	ds_read_b128 v[234:237], v170 offset:54272
	ds_read_b128 v[238:241], v170 offset:55296
	ds_read_b128 v[242:245], v170 offset:56320
	global_load_lds_dwordx4 v[188:189], off
	s_add_i32 m0, s4, 0x2000
	s_add_u32 s4, s28, 0x40080
	v_lshl_add_u64 v[188:189], v[246:247], 0, s[62:63]
	s_addc_u32 s5, s29, 0
	s_add_i32 s28, s64, s36
	global_load_lds_dwordx4 v[188:189], off
	v_lshl_add_u64 v[188:189], s[4:5], 0, v[154:155]
	s_mov_b32 m0, s28
	s_nop 0
	global_load_lds_dwordx4 v[188:189], off
	v_lshl_add_u64 v[188:189], s[4:5], 0, v[150:151]
	s_add_i32 m0, s28, 0x2000
	s_nop 0
	global_load_lds_dwordx4 v[188:189], off
	v_lshl_add_u64 v[188:189], v[248:249], 0, s[62:63]
	s_mov_b32 m0, s42
	s_nop 0
	global_load_lds_dwordx4 v[188:189], off
	v_lshl_add_u64 v[188:189], v[250:251], 0, s[62:63]
	s_mov_b32 m0, s43
	s_nop 0
	global_load_lds_dwordx4 v[188:189], off
	s_waitcnt vmcnt(8)
	s_waitcnt lgkmcnt(0)
	s_barrier
	s_setprio 1
	s_waitcnt lgkmcnt(0)
	v_mfma_f32_16x16x32_bf16 v[62:65], v[164:167], v[214:217], v[62:65]
	v_mfma_f32_16x16x32_bf16 v[50:53], v[176:179], v[214:217], v[50:53]
	v_mfma_f32_16x16x32_bf16 v[46:49], v[164:167], v[222:225], v[46:49]
	v_mfma_f32_16x16x32_bf16 v[34:37], v[176:179], v[222:225], v[34:37]
	v_mfma_f32_16x16x32_bf16 v[30:33], v[164:167], v[230:233], v[30:33]
	v_mfma_f32_16x16x32_bf16 v[18:21], v[176:179], v[230:233], v[18:21]
	v_mfma_f32_16x16x32_bf16 v[14:17], v[164:167], v[238:241], v[14:17]
	v_mfma_f32_16x16x32_bf16 v[6:9], v[176:179], v[238:241], v[6:9]
	v_mfma_f32_16x16x32_bf16 v[62:65], v[172:175], v[218:221], v[62:65]
	v_mfma_f32_16x16x32_bf16 v[50:53], v[180:183], v[218:221], v[50:53]
	v_mfma_f32_16x16x32_bf16 v[46:49], v[172:175], v[226:229], v[46:49]
	v_mfma_f32_16x16x32_bf16 v[34:37], v[180:183], v[226:229], v[34:37]
	v_mfma_f32_16x16x32_bf16 v[30:33], v[172:175], v[234:237], v[30:33]
	v_mfma_f32_16x16x32_bf16 v[18:21], v[180:183], v[234:237], v[18:21]
	v_mfma_f32_16x16x32_bf16 v[14:17], v[172:175], v[242:245], v[14:17]
	v_mfma_f32_16x16x32_bf16 v[6:9], v[180:183], v[242:245], v[6:9]
	v_mfma_f32_16x16x32_bf16 v[58:61], v[184:187], v[214:217], v[58:61]
	v_mfma_f32_16x16x32_bf16 v[54:57], v[206:209], v[214:217], v[54:57]
	v_mfma_f32_16x16x32_bf16 v[42:45], v[184:187], v[222:225], v[42:45]
	v_mfma_f32_16x16x32_bf16 v[38:41], v[206:209], v[222:225], v[38:41]
	v_mfma_f32_16x16x32_bf16 v[26:29], v[184:187], v[230:233], v[26:29]
	v_mfma_f32_16x16x32_bf16 v[22:25], v[206:209], v[230:233], v[22:25]
	v_mfma_f32_16x16x32_bf16 v[10:13], v[184:187], v[238:241], v[10:13]
	v_mfma_f32_16x16x32_bf16 v[2:5], v[206:209], v[238:241], v[2:5]
	v_mfma_f32_16x16x32_bf16 v[58:61], v[202:205], v[218:221], v[58:61]
	v_mfma_f32_16x16x32_bf16 v[54:57], v[210:213], v[218:221], v[54:57]
	v_mfma_f32_16x16x32_bf16 v[42:45], v[202:205], v[226:229], v[42:45]
	v_mfma_f32_16x16x32_bf16 v[38:41], v[210:213], v[226:229], v[38:41]
	v_mfma_f32_16x16x32_bf16 v[26:29], v[202:205], v[234:237], v[26:29]
	v_mfma_f32_16x16x32_bf16 v[22:25], v[210:213], v[234:237], v[22:25]
	v_mfma_f32_16x16x32_bf16 v[10:13], v[202:205], v[242:245], v[10:13]
	v_mfma_f32_16x16x32_bf16 v[2:5], v[210:213], v[242:245], v[2:5]
	s_setprio 0
	s_barrier
	s_add_i32 s54, s54, 2
	s_add_u32 s12, s12, 0x100
	s_addc_u32 s13, s13, 0
	s_add_u32 s52, s52, 0x100
	s_addc_u32 s53, s53, 0
	s_cmp_gt_u32 s54, 13
	s_cbranch_scc0 .LBB0_1764
	s_and_b64 vcc, exec, s[18:19]
	s_cbranch_vccz .LBB0_1767
	s_barrier

; #define PG8_STAGE(bufoff, gbase, voff) do { _Pragma("unroll") for (int _i = 0; _i < 2; ++_i) \
;         __builtin_amdgcn_global_load_lds((const unsigned*)((const char*)(gbase) + (voff)[_i]), (PG8_LAS unsigned*)(lds + (bufoff) + ldsw + _i * 8192), 16, 0, 0); } while (0)
; #define PG8_LDA(dst, b, h) do { _Pragma("unroll") for (int m = 0; m < 4; ++m) _Pragma("unroll") for (int k = 0; k < 2; ++k) dst[m][k] = *(const PG8_LAS bf16x8*)(lds + PG8_SA(b, h) + aoff + m * 2048 + k * 1024); } while (0)
; #define PG8_LDB(dst, b, h) do { _Pragma("unroll") for (int n = 0; n < 2; ++n) _Pragma("unroll") for (int k = 0; k < 2; ++k) dst[n][k] = *(const PG8_LAS bf16x8*)(lds + PG8_SB(b, h) + boff + n * 2048 + k * 1024); } while (0)
; #define PG8_MMA(ai, bj, At, Bt) do { __builtin_amdgcn_s_setprio(1); _Pragma("unroll") for (int m = 0; m < 4; ++m) _Pragma("unroll") for (int n = 0; n < 2; ++n) _Pragma("unroll") for (int k = 0; k < 2; ++k) \
;         acc[ai][bj][m][n] = __builtin_amdgcn_mfma_f32_16x16x32_bf16(Bt[n][k], At[m][k], acc[ai][bj][m][n], 0, 0, 0); __builtin_amdgcn_s_setprio(0); } while (0)
; #define PG8_WAIT_V(n) asm volatile("s_waitcnt vmcnt(" #n ")" ::: "memory")
; #define PG8_WAIT_L(n) asm volatile("s_waitcnt lgkmcnt(" #n ")" ::: "memory")
; template <class Epi, class Sched, bool ALIGN_EPI = false, bool SP2 = false>
; __device__ __forceinline__ void gemm_phase(PG8_LAS unsigned char* lds, const Gemm g, const Sched& S, const Epi& E) {
;     ...
;             const bool last = (t == nt - 2);
;             const char* a1 = cA + (size_t)(t + 1) * kstep;
;             const char* a2 = last ? nA : cA + (size_t)(t + 2) * kstep; const char* b2 = last ? nB : cB + (size_t)(t + 2) * kstep;
;             const char* a3 = a2 + kstep; const char* b3 = b2 + kstep;
;             if (last && has_next) S.a_ready(nxt);
;             if constexpr (SP2) {
;             PG8_LDB(B0, 0, 0); PG8_LDB(B1, 0, 1); PG8_SCHED; PG8_LDA(At, 0, 0); PG8_STAGE(PG8_SA(1, 1), a1 + hstep, voffA);
;             PG8_WAIT_V(8); PG8_WAIT_L(0); PG8_BAR; PG8_MMA(0, 0, At, B0); PG8_MMA(0, 1, At, B1); PG8_BAR; PG8_SCHED;
;             PG8_LDA(At, 0, 1); PG8_STAGE(PG8_SB(0, 0), b2, voffB); PG8_STAGE(PG8_SB(0, 1), b2 + hstep, voffB); PG8_STAGE(PG8_SA(0, 0), a2, voffA);
;             PG8_WAIT_V(8); PG8_WAIT_L(0); PG8_BAR; PG8_MMA(1, 0, At, B0); PG8_MMA(1, 1, At, B1); PG8_BAR; PG8_SCHED;
.LBB0_1890:
	s_add_u32 s24, s22, 0x100
	s_addc_u32 s25, s23, 0
	s_add_i32 s4, 0, 0x10000
	s_cmp_eq_u32 s50, 40
	s_cselect_b32 s29, s11, s25
	s_cselect_b32 s28, s10, s24
	v_add_u32_e32 v165, s4, v162
	s_cselect_b32 s27, s21, s49
	s_cselect_b32 s26, s20, s48
	s_add_i32 s51, 0, 0x14000
	ds_read_b128 v[158:161], v165
	ds_read_b128 v[166:169], v165 offset:1024
	ds_read_b128 v[170:173], v165 offset:2048
	ds_read_b128 v[174:177], v165 offset:3072
	v_add_u32_e32 v165, s51, v162
	ds_read_b128 v[178:181], v165
	ds_read_b128 v[182:185], v165 offset:1024
	ds_read_b128 v[186:189], v165 offset:2048
	ds_read_b128 v[202:205], v165 offset:3072
	v_lshl_add_u64 v[238:239], s[22:23], 0, v[154:155]
	s_add_i32 m0, s35, 0xc000
	ds_read_b128 v[206:209], v164
	ds_read_b128 v[210:213], v164 offset:1024
	ds_read_b128 v[214:217], v164 offset:2048
	ds_read_b128 v[218:221], v164 offset:3072
	ds_read_b128 v[222:225], v164 offset:4096
	ds_read_b128 v[226:229], v164 offset:5120
	ds_read_b128 v[230:233], v164 offset:6144
	ds_read_b128 v[234:237], v164 offset:7168
	global_load_lds_dwordx4 v[238:239], off
	v_lshl_add_u64 v[238:239], s[22:23], 0, v[156:157]
	s_add_i32 m0, s35, 0xe000
	s_nop 0
	global_load_lds_dwordx4 v[238:239], off
	s_bfe_u32 s100, s50, 0x30001
	s_lshl_b32 s100, s100, 16
	v_add_u32_e32 v250, s100, v249
	global_load_dword v248, v250, s[14:15]
	s_waitcnt vmcnt(9)
	s_waitcnt lgkmcnt(0)
	s_barrier
	s_setprio 1
	s_waitcnt lgkmcnt(0)
	v_mfma_f32_16x16x32_bf16 v[126:129], v[158:161], v[206:209], v[126:129]
	v_mfma_f32_16x16x32_bf16 v[122:125], v[170:173], v[206:209], v[122:125]
	v_mfma_f32_16x16x32_bf16 v[110:113], v[158:161], v[214:217], v[110:113]
	v_mfma_f32_16x16x32_bf16 v[106:109], v[170:173], v[214:217], v[106:109]
	v_mfma_f32_16x16x32_bf16 v[94:97], v[158:161], v[222:225], v[94:97]
	v_mfma_f32_16x16x32_bf16 v[90:93], v[170:173], v[222:225], v[90:93]
	v_mfma_f32_16x16x32_bf16 v[78:81], v[158:161], v[230:233], v[78:81]
	v_mfma_f32_16x16x32_bf16 v[74:77], v[170:173], v[230:233], v[74:77]
	v_mfma_f32_16x16x32_bf16 v[126:129], v[166:169], v[210:213], v[126:129]
	v_mfma_f32_16x16x32_bf16 v[122:125], v[174:177], v[210:213], v[122:125]
	v_mfma_f32_16x16x32_bf16 v[110:113], v[166:169], v[218:221], v[110:113]
	v_mfma_f32_16x16x32_bf16 v[106:109], v[174:177], v[218:221], v[106:109]
	v_mfma_f32_16x16x32_bf16 v[94:97], v[166:169], v[226:229], v[94:97]
	v_mfma_f32_16x16x32_bf16 v[90:93], v[174:177], v[226:229], v[90:93]
	v_mfma_f32_16x16x32_bf16 v[78:81], v[166:169], v[234:237], v[78:81]
	v_mfma_f32_16x16x32_bf16 v[74:77], v[174:177], v[234:237], v[74:77]
	v_mfma_f32_16x16x32_bf16 v[118:121], v[178:181], v[206:209], v[118:121]
	v_mfma_f32_16x16x32_bf16 v[114:117], v[186:189], v[206:209], v[114:117]
	v_mfma_f32_16x16x32_bf16 v[102:105], v[178:181], v[214:217], v[102:105]
	v_mfma_f32_16x16x32_bf16 v[98:101], v[186:189], v[214:217], v[98:101]
	v_mfma_f32_16x16x32_bf16 v[86:89], v[178:181], v[222:225], v[86:89]
	v_mfma_f32_16x16x32_bf16 v[82:85], v[186:189], v[222:225], v[82:85]
	v_mfma_f32_16x16x32_bf16 v[70:73], v[178:181], v[230:233], v[70:73]
	v_mfma_f32_16x16x32_bf16 v[66:69], v[186:189], v[230:233], v[66:69]
	v_mfma_f32_16x16x32_bf16 v[118:121], v[182:185], v[210:213], v[118:121]
	v_mfma_f32_16x16x32_bf16 v[114:117], v[202:205], v[210:213], v[114:117]
	v_mfma_f32_16x16x32_bf16 v[102:105], v[182:185], v[218:221], v[102:105]
	v_mfma_f32_16x16x32_bf16 v[98:101], v[202:205], v[218:221], v[98:101]
	v_mfma_f32_16x16x32_bf16 v[86:89], v[182:185], v[226:229], v[86:89]
	v_mfma_f32_16x16x32_bf16 v[82:85], v[202:205], v[226:229], v[82:85]
	v_mfma_f32_16x16x32_bf16 v[70:73], v[182:185], v[234:237], v[70:73]
	v_mfma_f32_16x16x32_bf16 v[66:69], v[202:205], v[234:237], v[66:69]
	s_setprio 0
	s_barrier
	s_add_i32 s4, s4, s34
	v_lshl_add_u64 v[238:239], s[26:27], 0, v[152:153]
	s_mov_b32 m0, s4
	ds_read_b128 v[206:209], v164 offset:16384
	ds_read_b128 v[210:213], v164 offset:17408
	ds_read_b128 v[214:217], v164 offset:18432
	ds_read_b128 v[218:221], v164 offset:19456
	ds_read_b128 v[222:225], v164 offset:20480
	ds_read_b128 v[226:229], v164 offset:21504
	ds_read_b128 v[230:233], v164 offset:22528
	ds_read_b128 v[234:237], v164 offset:23552
	global_load_lds_dwordx4 v[238:239], off
	s_add_i32 m0, s4, 0x2000
	s_add_u32 s4, s26, 0xb0000
	v_lshl_add_u64 v[240:241], s[26:27], 0, v[150:151]
	s_addc_u32 s5, s27, 0
	s_add_i32 s22, s51, s34
	global_load_lds_dwordx4 v[240:241], off
	v_lshl_add_u64 v[242:243], s[4:5], 0, v[152:153]
	s_mov_b32 m0, s22
	v_lshl_add_u64 v[244:245], s[28:29], 0, v[150:151]
	global_load_lds_dwordx4 v[242:243], off
	v_lshl_add_u64 v[242:243], s[4:5], 0, v[150:151]
	s_add_i32 m0, s22, 0x2000
	s_nop 0
	global_load_lds_dwordx4 v[242:243], off
	v_lshl_add_u64 v[242:243], s[28:29], 0, v[152:153]
	s_mov_b32 m0, s35
	s_nop 0
	global_load_lds_dwordx4 v[242:243], off
	s_mov_b32 m0, s36
	s_nop 0
	global_load_lds_dwordx4 v[244:245], off
	s_waitcnt vmcnt(9)
	s_waitcnt lgkmcnt(0)
	s_barrier
; #define PG8_STAGE(bufoff, gbase, voff) do { _Pragma("unroll") for (int _i = 0; _i < 2; ++_i) \
;         __builtin_amdgcn_global_load_lds((const unsigned*)((const char*)(gbase) + (voff)[_i]), (PG8_LAS unsigned*)(lds + (bufoff) + ldsw + _i * 8192), 16, 0, 0); } while (0)
; #define PG8_LDA(dst, b, h) do { _Pragma("unroll") for (int m = 0; m < 4; ++m) _Pragma("unroll") for (int k = 0; k < 2; ++k) dst[m][k] = *(const PG8_LAS bf16x8*)(lds + PG8_SA(b, h) + aoff + m * 2048 + k * 1024); } while (0)
; #define PG8_LDB(dst, b, h) do { _Pragma("unroll") for (int n = 0; n < 2; ++n) _Pragma("unroll") for (int k = 0; k < 2; ++k) dst[n][k] = *(const PG8_LAS bf16x8*)(lds + PG8_SB(b, h) + boff + n * 2048 + k * 1024); } while (0)
; #define PG8_MMA(ai, bj, At, Bt) do { __builtin_amdgcn_s_setprio(1); _Pragma("unroll") for (int m = 0; m < 4; ++m) _Pragma("unroll") for (int n = 0; n < 2; ++n) _Pragma("unroll") for (int k = 0; k < 2; ++k) \
;         acc[ai][bj][m][n] = __builtin_amdgcn_mfma_f32_16x16x32_bf16(Bt[n][k], At[m][k], acc[ai][bj][m][n], 0, 0, 0); __builtin_amdgcn_s_setprio(0); } while (0)
; #define PG8_WAIT_V(n) asm volatile("s_waitcnt vmcnt(" #n ")" ::: "memory")
; #define PG8_WAIT_L(n) asm volatile("s_waitcnt lgkmcnt(" #n ")" ::: "memory")
; #define PG8_BAR __builtin_amdgcn_s_barrier()
; #define PG8_SCHED __builtin_amdgcn_sched_barrier(0)
; template <class Epi, class Sched, bool ALIGN_EPI = false, bool SP2 = false>
; __device__ __forceinline__ void gemm_phase(PG8_LAS unsigned char* lds, const Gemm g, const Sched& S, const Epi& E) {
;     ...
;             PG8_WAIT_V(8); PG8_WAIT_L(0); PG8_BAR; PG8_MMA(1, 0, At, B0); PG8_MMA(1, 1, At, B1); PG8_BAR; PG8_SCHED;
;             PG8_LDB(B0, 1, 0); PG8_LDB(B1, 1, 1); PG8_SCHED; PG8_LDA(At, 1, 0); PG8_STAGE(PG8_SA(0, 1), a2 + hstep, voffA);
;             PG8_WAIT_V(8); PG8_WAIT_L(0); PG8_BAR; PG8_MMA(0, 0, At, B0); PG8_MMA(0, 1, At, B1); PG8_BAR; PG8_SCHED;
	s_setprio 1
	s_waitcnt lgkmcnt(0)
	v_mfma_f32_16x16x32_bf16 v[62:65], v[158:161], v[206:209], v[62:65]
	v_mfma_f32_16x16x32_bf16 v[58:61], v[170:173], v[206:209], v[58:61]
	v_mfma_f32_16x16x32_bf16 v[46:49], v[158:161], v[214:217], v[46:49]
	v_mfma_f32_16x16x32_bf16 v[42:45], v[170:173], v[214:217], v[42:45]
	v_mfma_f32_16x16x32_bf16 v[30:33], v[158:161], v[222:225], v[30:33]
	v_mfma_f32_16x16x32_bf16 v[26:29], v[170:173], v[222:225], v[26:29]
	v_mfma_f32_16x16x32_bf16 v[14:17], v[158:161], v[230:233], v[14:17]
	v_mfma_f32_16x16x32_bf16 v[10:13], v[170:173], v[230:233], v[10:13]
	v_mfma_f32_16x16x32_bf16 v[62:65], v[166:169], v[210:213], v[62:65]
	v_mfma_f32_16x16x32_bf16 v[58:61], v[174:177], v[210:213], v[58:61]
	v_mfma_f32_16x16x32_bf16 v[46:49], v[166:169], v[218:221], v[46:49]
	v_mfma_f32_16x16x32_bf16 v[42:45], v[174:177], v[218:221], v[42:45]
	v_mfma_f32_16x16x32_bf16 v[30:33], v[166:169], v[226:229], v[30:33]
	v_mfma_f32_16x16x32_bf16 v[26:29], v[174:177], v[226:229], v[26:29]
	v_mfma_f32_16x16x32_bf16 v[14:17], v[166:169], v[234:237], v[14:17]
	v_mfma_f32_16x16x32_bf16 v[10:13], v[174:177], v[234:237], v[10:13]
	v_mfma_f32_16x16x32_bf16 v[54:57], v[178:181], v[206:209], v[54:57]
	v_mfma_f32_16x16x32_bf16 v[50:53], v[186:189], v[206:209], v[50:53]
	v_mfma_f32_16x16x32_bf16 v[38:41], v[178:181], v[214:217], v[38:41]
	v_mfma_f32_16x16x32_bf16 v[34:37], v[186:189], v[214:217], v[34:37]
	v_mfma_f32_16x16x32_bf16 v[22:25], v[178:181], v[222:225], v[22:25]
	v_mfma_f32_16x16x32_bf16 v[18:21], v[186:189], v[222:225], v[18:21]
	v_mfma_f32_16x16x32_bf16 v[6:9], v[178:181], v[230:233], v[6:9]
	v_mfma_f32_16x16x32_bf16 v[2:5], v[186:189], v[230:233], v[2:5]
	v_mfma_f32_16x16x32_bf16 v[54:57], v[182:185], v[210:213], v[54:57]
	v_mfma_f32_16x16x32_bf16 v[50:53], v[202:205], v[210:213], v[50:53]
	v_mfma_f32_16x16x32_bf16 v[38:41], v[182:185], v[218:221], v[38:41]
	v_mfma_f32_16x16x32_bf16 v[34:37], v[202:205], v[218:221], v[34:37]
	v_mfma_f32_16x16x32_bf16 v[22:25], v[182:185], v[226:229], v[22:25]
	v_mfma_f32_16x16x32_bf16 v[18:21], v[202:205], v[226:229], v[18:21]
	v_mfma_f32_16x16x32_bf16 v[6:9], v[182:185], v[234:237], v[6:9]
	v_mfma_f32_16x16x32_bf16 v[2:5], v[202:205], v[234:237], v[2:5]
	s_setprio 0
	s_barrier
	s_add_i32 s22, 0, 0x18000
	v_add_u32_e32 v165, s22, v162
	s_add_i32 s23, 0, 0x1c000
	ds_read_b128 v[158:161], v165
	ds_read_b128 v[166:169], v165 offset:1024
	ds_read_b128 v[170:173], v165 offset:2048
	ds_read_b128 v[174:177], v165 offset:3072
	v_add_u32_e32 v165, s23, v162
	ds_read_b128 v[178:181], v165
	ds_read_b128 v[182:185], v165 offset:1024
	ds_read_b128 v[186:189], v165 offset:2048
	ds_read_b128 v[202:205], v165 offset:3072
	s_add_u32 s4, s28, 0xb0000
	s_addc_u32 s5, s29, 0
	s_mov_b32 m0, s37
	v_lshl_add_u64 v[246:247], s[4:5], 0, v[152:153]
	ds_read_b128 v[206:209], v164 offset:32768
	ds_read_b128 v[210:213], v164 offset:33792
	ds_read_b128 v[214:217], v164 offset:34816
	ds_read_b128 v[218:221], v164 offset:35840
	ds_read_b128 v[222:225], v164 offset:36864
	ds_read_b128 v[226:229], v164 offset:37888
	ds_read_b128 v[230:233], v164 offset:38912
	ds_read_b128 v[234:237], v164 offset:39936
	global_load_lds_dwordx4 v[246:247], off
	v_lshl_add_u64 v[246:247], s[4:5], 0, v[150:151]
	s_mov_b32 m0, s38
	s_nop 0
	global_load_lds_dwordx4 v[246:247], off
	s_waitcnt vmcnt(9)
	s_waitcnt lgkmcnt(0)
	s_barrier
	s_setprio 1
	s_waitcnt lgkmcnt(0)
	v_mfma_f32_16x16x32_bf16 v[126:129], v[158:161], v[206:209], v[126:129]
	v_mfma_f32_16x16x32_bf16 v[122:125], v[170:173], v[206:209], v[122:125]
	v_mfma_f32_16x16x32_bf16 v[110:113], v[158:161], v[214:217], v[110:113]
	v_mfma_f32_16x16x32_bf16 v[106:109], v[170:173], v[214:217], v[106:109]
	v_mfma_f32_16x16x32_bf16 v[94:97], v[158:161], v[222:225], v[94:97]
	v_mfma_f32_16x16x32_bf16 v[90:93], v[170:173], v[222:225], v[90:93]
	v_mfma_f32_16x16x32_bf16 v[78:81], v[158:161], v[230:233], v[78:81]
	v_mfma_f32_16x16x32_bf16 v[74:77], v[170:173], v[230:233], v[74:77]
	v_mfma_f32_16x16x32_bf16 v[126:129], v[166:169], v[210:213], v[126:129]
	v_mfma_f32_16x16x32_bf16 v[122:125], v[174:177], v[210:213], v[122:125]
	v_mfma_f32_16x16x32_bf16 v[110:113], v[166:169], v[218:221], v[110:113]
	v_mfma_f32_16x16x32_bf16 v[106:109], v[174:177], v[218:221], v[106:109]
	v_mfma_f32_16x16x32_bf16 v[94:97], v[166:169], v[226:229], v[94:97]
	v_mfma_f32_16x16x32_bf16 v[90:93], v[174:177], v[226:229], v[90:93]
	v_mfma_f32_16x16x32_bf16 v[78:81], v[166:169], v[234:237], v[78:81]
	v_mfma_f32_16x16x32_bf16 v[74:77], v[174:177], v[234:237], v[74:77]
	v_mfma_f32_16x16x32_bf16 v[118:121], v[178:181], v[206:209], v[118:121]
	v_mfma_f32_16x16x32_bf16 v[114:117], v[186:189], v[206:209], v[114:117]
	v_mfma_f32_16x16x32_bf16 v[102:105], v[178:181], v[214:217], v[102:105]
	v_mfma_f32_16x16x32_bf16 v[98:101], v[186:189], v[214:217], v[98:101]
	v_mfma_f32_16x16x32_bf16 v[86:89], v[178:181], v[222:225], v[86:89]
	v_mfma_f32_16x16x32_bf16 v[82:85], v[186:189], v[222:225], v[82:85]
	v_mfma_f32_16x16x32_bf16 v[70:73], v[178:181], v[230:233], v[70:73]
	v_mfma_f32_16x16x32_bf16 v[66:69], v[186:189], v[230:233], v[66:69]
	v_mfma_f32_16x16x32_bf16 v[118:121], v[182:185], v[210:213], v[118:121]
	v_mfma_f32_16x16x32_bf16 v[114:117], v[202:205], v[210:213], v[114:117]
	v_mfma_f32_16x16x32_bf16 v[102:105], v[182:185], v[218:221], v[102:105]
	v_mfma_f32_16x16x32_bf16 v[98:101], v[202:205], v[218:221], v[98:101]
	v_mfma_f32_16x16x32_bf16 v[86:89], v[182:185], v[226:229], v[86:89]
	v_mfma_f32_16x16x32_bf16 v[82:85], v[202:205], v[226:229], v[82:85]
	v_mfma_f32_16x16x32_bf16 v[70:73], v[182:185], v[234:237], v[70:73]
	v_mfma_f32_16x16x32_bf16 v[66:69], v[202:205], v[234:237], v[66:69]
	s_setprio 0
	s_barrier
; #define PG8_STAGE(bufoff, gbase, voff) do { _Pragma("unroll") for (int _i = 0; _i < 2; ++_i) \
;         __builtin_amdgcn_global_load_lds((const unsigned*)((const char*)(gbase) + (voff)[_i]), (PG8_LAS unsigned*)(lds + (bufoff) + ldsw + _i * 8192), 16, 0, 0); } while (0)
; #define PG8_LDA(dst, b, h) do { _Pragma("unroll") for (int m = 0; m < 4; ++m) _Pragma("unroll") for (int k = 0; k < 2; ++k) dst[m][k] = *(const PG8_LAS bf16x8*)(lds + PG8_SA(b, h) + aoff + m * 2048 + k * 1024); } while (0)
; #define PG8_MMA(ai, bj, At, Bt) do { __builtin_amdgcn_s_setprio(1); _Pragma("unroll") for (int m = 0; m < 4; ++m) _Pragma("unroll") for (int n = 0; n < 2; ++n) _Pragma("unroll") for (int k = 0; k < 2; ++k) \
;         acc[ai][bj][m][n] = __builtin_amdgcn_mfma_f32_16x16x32_bf16(Bt[n][k], At[m][k], acc[ai][bj][m][n], 0, 0, 0); __builtin_amdgcn_s_setprio(0); } while (0)
; #define PG8_WAIT_V(n) asm volatile("s_waitcnt vmcnt(" #n ")" ::: "memory")
; #define PG8_WAIT_L(n) asm volatile("s_waitcnt lgkmcnt(" #n ")" ::: "memory")
; #define PG8_BAR __builtin_amdgcn_s_barrier()
; #define PG8_SCHED __builtin_amdgcn_sched_barrier(0)
; template <class Epi, class Sched, bool ALIGN_EPI = false, bool SP2 = false>
; __device__ __forceinline__ void gemm_phase(PG8_LAS unsigned char* lds, const Gemm g, const Sched& S, const Epi& E) {
;     ...
;             PG8_LDA(At, 1, 1); PG8_STAGE(PG8_SB(1, 0), b3, voffB); PG8_STAGE(PG8_SB(1, 1), b3 + hstep, voffB); PG8_STAGE(PG8_SA(1, 0), a3, voffA);
;             PG8_WAIT_V(8); PG8_WAIT_L(0); PG8_BAR; PG8_MMA(1, 0, At, B0); PG8_MMA(1, 1, At, B1); PG8_BAR; PG8_SCHED;
;     ...
;         }
;         if constexpr (ALIGN_EPI) { if (wr == 0) PG8_BAR; }
	s_add_i32 s4, s22, s34
	v_lshl_add_u64 v[238:239], v[238:239], 0, s[62:63]
	s_mov_b32 m0, s4
	ds_read_b128 v[206:209], v164 offset:49152
	ds_read_b128 v[210:213], v164 offset:50176
	ds_read_b128 v[214:217], v164 offset:51200
	ds_read_b128 v[218:221], v164 offset:52224
	ds_read_b128 v[222:225], v164 offset:53248
	ds_read_b128 v[226:229], v164 offset:54272
	ds_read_b128 v[230:233], v164 offset:55296
	ds_read_b128 v[234:237], v164 offset:56320
	global_load_lds_dwordx4 v[238:239], off
	s_add_i32 m0, s4, 0x2000
	s_add_u32 s4, s26, 0xb0080
	v_lshl_add_u64 v[238:239], v[240:241], 0, s[62:63]
	s_addc_u32 s5, s27, 0
	s_add_i32 s22, s23, s34
	global_load_lds_dwordx4 v[238:239], off
	v_lshl_add_u64 v[238:239], s[4:5], 0, v[152:153]
	s_mov_b32 m0, s22
	s_nop 0
	global_load_lds_dwordx4 v[238:239], off
	v_lshl_add_u64 v[238:239], s[4:5], 0, v[150:151]
	s_add_i32 m0, s22, 0x2000
	s_nop 0
	global_load_lds_dwordx4 v[238:239], off
	v_lshl_add_u64 v[238:239], v[242:243], 0, s[62:63]
	s_mov_b32 m0, s41
	s_nop 0
	global_load_lds_dwordx4 v[238:239], off
	v_lshl_add_u64 v[238:239], v[244:245], 0, s[62:63]
	s_mov_b32 m0, s42
	s_nop 0
	global_load_lds_dwordx4 v[238:239], off
	s_waitcnt vmcnt(8)
	s_waitcnt lgkmcnt(0)
	s_barrier
	s_setprio 1
	s_waitcnt lgkmcnt(0)
	v_mfma_f32_16x16x32_bf16 v[62:65], v[158:161], v[206:209], v[62:65]
	v_mfma_f32_16x16x32_bf16 v[58:61], v[170:173], v[206:209], v[58:61]
	v_mfma_f32_16x16x32_bf16 v[46:49], v[158:161], v[214:217], v[46:49]
	v_mfma_f32_16x16x32_bf16 v[42:45], v[170:173], v[214:217], v[42:45]
	v_mfma_f32_16x16x32_bf16 v[30:33], v[158:161], v[222:225], v[30:33]
	v_mfma_f32_16x16x32_bf16 v[26:29], v[170:173], v[222:225], v[26:29]
	v_mfma_f32_16x16x32_bf16 v[14:17], v[158:161], v[230:233], v[14:17]
	v_mfma_f32_16x16x32_bf16 v[10:13], v[170:173], v[230:233], v[10:13]
	v_mfma_f32_16x16x32_bf16 v[62:65], v[166:169], v[210:213], v[62:65]
	v_mfma_f32_16x16x32_bf16 v[58:61], v[174:177], v[210:213], v[58:61]
	v_mfma_f32_16x16x32_bf16 v[46:49], v[166:169], v[218:221], v[46:49]
	v_mfma_f32_16x16x32_bf16 v[42:45], v[174:177], v[218:221], v[42:45]
	v_mfma_f32_16x16x32_bf16 v[30:33], v[166:169], v[226:229], v[30:33]
	v_mfma_f32_16x16x32_bf16 v[26:29], v[174:177], v[226:229], v[26:29]
	v_mfma_f32_16x16x32_bf16 v[14:17], v[166:169], v[234:237], v[14:17]
	v_mfma_f32_16x16x32_bf16 v[10:13], v[174:177], v[234:237], v[10:13]
	v_mfma_f32_16x16x32_bf16 v[54:57], v[178:181], v[206:209], v[54:57]
	v_mfma_f32_16x16x32_bf16 v[50:53], v[186:189], v[206:209], v[50:53]
	v_mfma_f32_16x16x32_bf16 v[38:41], v[178:181], v[214:217], v[38:41]
	v_mfma_f32_16x16x32_bf16 v[34:37], v[186:189], v[214:217], v[34:37]
	v_mfma_f32_16x16x32_bf16 v[22:25], v[178:181], v[222:225], v[22:25]
	v_mfma_f32_16x16x32_bf16 v[18:21], v[186:189], v[222:225], v[18:21]
	v_mfma_f32_16x16x32_bf16 v[6:9], v[178:181], v[230:233], v[6:9]
	v_mfma_f32_16x16x32_bf16 v[2:5], v[186:189], v[230:233], v[2:5]
	v_mfma_f32_16x16x32_bf16 v[54:57], v[182:185], v[210:213], v[54:57]
	v_mfma_f32_16x16x32_bf16 v[50:53], v[202:205], v[210:213], v[50:53]
	v_mfma_f32_16x16x32_bf16 v[38:41], v[182:185], v[218:221], v[38:41]
	v_mfma_f32_16x16x32_bf16 v[34:37], v[202:205], v[218:221], v[34:37]
	v_mfma_f32_16x16x32_bf16 v[22:25], v[182:185], v[226:229], v[22:25]
	v_mfma_f32_16x16x32_bf16 v[18:21], v[202:205], v[226:229], v[18:21]
	v_mfma_f32_16x16x32_bf16 v[6:9], v[182:185], v[234:237], v[6:9]
	v_mfma_f32_16x16x32_bf16 v[2:5], v[202:205], v[234:237], v[2:5]
	s_setprio 0
	s_barrier
	s_add_i32 s50, s50, 2
	s_add_u32 s48, s48, 0x100
	s_addc_u32 s49, s49, 0
	s_cmp_gt_u32 s50, 41
	s_mov_b64 s[22:23], s[24:25]
	s_cbranch_scc0 .LBB0_1890
	s_and_b64 vcc, exec, s[18:19]
	s_cbranch_vccz .LBB0_1893
	s_barrier

; #define PG8_STAGE(bufoff, gbase, voff) do { _Pragma("unroll") for (int _i = 0; _i < 2; ++_i) \
;         __builtin_amdgcn_global_load_lds((const unsigned*)((const char*)(gbase) + (voff)[_i]), (PG8_LAS unsigned*)(lds + (bufoff) + ldsw + _i * 8192), 16, 0, 0); } while (0)
; #define PG8_LDA(dst, b, h) do { _Pragma("unroll") for (int m = 0; m < 4; ++m) _Pragma("unroll") for (int k = 0; k < 2; ++k) dst[m][k] = *(const PG8_LAS bf16x8*)(lds + PG8_SA(b, h) + aoff + m * 2048 + k * 1024); } while (0)
; #define PG8_LDB(dst, b, h) do { _Pragma("unroll") for (int n = 0; n < 2; ++n) _Pragma("unroll") for (int k = 0; k < 2; ++k) dst[n][k] = *(const PG8_LAS bf16x8*)(lds + PG8_SB(b, h) + boff + n * 2048 + k * 1024); } while (0)
; #define PG8_MMA(ai, bj, At, Bt) do { __builtin_amdgcn_s_setprio(1); _Pragma("unroll") for (int m = 0; m < 4; ++m) _Pragma("unroll") for (int n = 0; n < 2; ++n) _Pragma("unroll") for (int k = 0; k < 2; ++k) \
;         acc[ai][bj][m][n] = __builtin_amdgcn_mfma_f32_16x16x32_bf16(Bt[n][k], At[m][k], acc[ai][bj][m][n], 0, 0, 0); __builtin_amdgcn_s_setprio(0); } while (0)
; #define PG8_WAIT_V(n) asm volatile("s_waitcnt vmcnt(" #n ")" ::: "memory")
; #define PG8_WAIT_L(n) asm volatile("s_waitcnt lgkmcnt(" #n ")" ::: "memory")
; template <class Epi, class Sched, bool ALIGN_EPI = false, bool SP2 = false>
; __device__ __forceinline__ void gemm_phase(PG8_LAS unsigned char* lds, const Gemm g, const Sched& S, const Epi& E) {
;     ...
;             const bool last = (t == nt - 2);
;             const char* a1 = cA + (size_t)(t + 1) * kstep;
;             const char* a2 = last ? nA : cA + (size_t)(t + 2) * kstep; const char* b2 = last ? nB : cB + (size_t)(t + 2) * kstep;
;             const char* a3 = a2 + kstep; const char* b3 = b2 + kstep;
;             if (last && has_next) S.a_ready(nxt);
;             if constexpr (SP2) {
;             PG8_LDB(B0, 0, 0); PG8_LDB(B1, 0, 1); PG8_SCHED; PG8_LDA(At, 0, 0); PG8_STAGE(PG8_SA(1, 1), a1 + hstep, voffA);
;             PG8_WAIT_V(8); PG8_WAIT_L(0); PG8_BAR; PG8_MMA(0, 0, At, B0); PG8_MMA(0, 1, At, B1); PG8_BAR; PG8_SCHED;
;             PG8_LDA(At, 0, 1); PG8_STAGE(PG8_SB(0, 0), b2, voffB); PG8_STAGE(PG8_SB(0, 1), b2 + hstep, voffB); PG8_STAGE(PG8_SA(0, 0), a2, voffA);
;             PG8_WAIT_V(8); PG8_WAIT_L(0); PG8_BAR; PG8_MMA(1, 0, At, B0); PG8_MMA(1, 1, At, B1); PG8_BAR; PG8_SCHED;
.LBB0_1969:
	ds_read_b128 v[150:153], v144
	ds_read_b128 v[154:157], v144 offset:1024
	ds_read_b128 v[158:161], v144 offset:2048
	ds_read_b128 v[162:165], v144 offset:3072
	ds_read_b128 v[166:169], v145
	ds_read_b128 v[170:173], v145 offset:1024
	ds_read_b128 v[174:177], v145 offset:2048
	ds_read_b128 v[178:181], v145 offset:3072
	s_add_u32 s16, s12, s14
	s_addc_u32 s17, s13, s15
	s_add_u32 s16, s16, 0x3d00100
	s_addc_u32 s17, s17, 0
	s_add_u32 s43, s28, s14
	s_addc_u32 s44, s29, s15
	s_cmpk_eq_i32 s14, 0xa00
	s_cselect_b32 s19, s7, s17
	s_cselect_b32 s18, s6, s16
	s_cselect_b32 s17, s9, s44
	s_cselect_b32 s16, s8, s43
	s_mov_b32 m0, s31
	v_lshl_add_u64 v[220:221], v[138:139], 0, s[14:15]
	ds_read_b128 v[182:185], v146
	ds_read_b128 v[186:189], v146 offset:1024
	ds_read_b128 v[196:199], v146 offset:2048
	ds_read_b128 v[200:203], v146 offset:3072
	ds_read_b128 v[204:207], v146 offset:4096
	ds_read_b128 v[208:211], v146 offset:5120
	ds_read_b128 v[212:215], v146 offset:6144
	ds_read_b128 v[216:219], v146 offset:7168
	global_load_lds_dwordx4 v[220:221], off
	v_lshl_add_u64 v[220:221], v[140:141], 0, s[14:15]
	s_mov_b32 m0, s34
	s_nop 0
	global_load_lds_dwordx4 v[220:221], off
	s_waitcnt vmcnt(8)
	s_waitcnt lgkmcnt(0)
	s_barrier
	s_setprio 1
	s_waitcnt lgkmcnt(0)
	v_mfma_f32_16x16x32_bf16 v[124:127], v[150:153], v[182:185], v[124:127]
	v_mfma_f32_16x16x32_bf16 v[120:123], v[158:161], v[182:185], v[120:123]
	v_mfma_f32_16x16x32_bf16 v[116:119], v[150:153], v[196:199], v[116:119]
	v_mfma_f32_16x16x32_bf16 v[112:115], v[158:161], v[196:199], v[112:115]
	v_mfma_f32_16x16x32_bf16 v[104:107], v[150:153], v[204:207], v[104:107]
	v_mfma_f32_16x16x32_bf16 v[96:99], v[158:161], v[204:207], v[96:99]
	v_mfma_f32_16x16x32_bf16 v[88:91], v[150:153], v[212:215], v[88:91]
	v_mfma_f32_16x16x32_bf16 v[80:83], v[158:161], v[212:215], v[80:83]
	v_mfma_f32_16x16x32_bf16 v[124:127], v[154:157], v[186:189], v[124:127]
	v_mfma_f32_16x16x32_bf16 v[120:123], v[162:165], v[186:189], v[120:123]
	v_mfma_f32_16x16x32_bf16 v[116:119], v[154:157], v[200:203], v[116:119]
	v_mfma_f32_16x16x32_bf16 v[112:115], v[162:165], v[200:203], v[112:115]
	v_mfma_f32_16x16x32_bf16 v[104:107], v[154:157], v[208:211], v[104:107]
	v_mfma_f32_16x16x32_bf16 v[96:99], v[162:165], v[208:211], v[96:99]
	v_mfma_f32_16x16x32_bf16 v[88:91], v[154:157], v[216:219], v[88:91]
	v_mfma_f32_16x16x32_bf16 v[80:83], v[162:165], v[216:219], v[80:83]
	v_mfma_f32_16x16x32_bf16 v[108:111], v[166:169], v[182:185], v[108:111]
	v_mfma_f32_16x16x32_bf16 v[100:103], v[174:177], v[182:185], v[100:103]
	v_mfma_f32_16x16x32_bf16 v[92:95], v[166:169], v[196:199], v[92:95]
	v_mfma_f32_16x16x32_bf16 v[84:87], v[174:177], v[196:199], v[84:87]
	v_mfma_f32_16x16x32_bf16 v[76:79], v[166:169], v[204:207], v[76:79]
	v_mfma_f32_16x16x32_bf16 v[72:75], v[174:177], v[204:207], v[72:75]
	v_mfma_f32_16x16x32_bf16 v[68:71], v[166:169], v[212:215], v[68:71]
	v_mfma_f32_16x16x32_bf16 v[64:67], v[174:177], v[212:215], v[64:67]
	v_mfma_f32_16x16x32_bf16 v[108:111], v[170:173], v[186:189], v[108:111]
	v_mfma_f32_16x16x32_bf16 v[100:103], v[178:181], v[186:189], v[100:103]
	v_mfma_f32_16x16x32_bf16 v[92:95], v[170:173], v[200:203], v[92:95]
	v_mfma_f32_16x16x32_bf16 v[84:87], v[178:181], v[200:203], v[84:87]
	v_mfma_f32_16x16x32_bf16 v[76:79], v[170:173], v[208:211], v[76:79]
	v_mfma_f32_16x16x32_bf16 v[72:75], v[178:181], v[208:211], v[72:75]
	v_mfma_f32_16x16x32_bf16 v[68:71], v[170:173], v[216:219], v[68:71]
	v_mfma_f32_16x16x32_bf16 v[64:67], v[178:181], v[216:219], v[64:67]
	s_setprio 0
	s_barrier
	s_mov_b32 m0, s35
	v_lshl_add_u64 v[220:221], s[16:17], 0, v[136:137]
	s_add_u32 s44, s16, 0x58000
	ds_read_b128 v[182:185], v146 offset:16384
	ds_read_b128 v[186:189], v146 offset:17408
	ds_read_b128 v[196:199], v146 offset:18432
	ds_read_b128 v[200:203], v146 offset:19456
	ds_read_b128 v[204:207], v146 offset:20480
	ds_read_b128 v[208:211], v146 offset:21504
	ds_read_b128 v[212:215], v146 offset:22528
	ds_read_b128 v[216:219], v146 offset:23552
	global_load_lds_dwordx4 v[220:221], off
	v_lshl_add_u64 v[222:223], s[16:17], 0, v[128:129]
	s_mov_b32 m0, s36
	s_addc_u32 s45, s17, 0
	global_load_lds_dwordx4 v[222:223], off
	v_lshl_add_u64 v[224:225], s[44:45], 0, v[136:137]
	s_mov_b32 m0, s37
	v_lshl_add_u64 v[226:227], s[18:19], 0, v[128:129]
	global_load_lds_dwordx4 v[224:225], off
	v_lshl_add_u64 v[224:225], s[44:45], 0, v[128:129]
	s_mov_b32 m0, s38
	s_nop 0
	global_load_lds_dwordx4 v[224:225], off
	v_lshl_add_u64 v[224:225], s[18:19], 0, v[136:137]
	s_mov_b32 m0, s5
	s_nop 0
	global_load_lds_dwordx4 v[224:225], off
	s_mov_b32 m0, s20
	s_nop 0
	global_load_lds_dwordx4 v[226:227], off
	s_waitcnt vmcnt(8)
	s_waitcnt lgkmcnt(0)
	s_barrier
; #define PG8_STAGE(bufoff, gbase, voff) do { _Pragma("unroll") for (int _i = 0; _i < 2; ++_i) \
;         __builtin_amdgcn_global_load_lds((const unsigned*)((const char*)(gbase) + (voff)[_i]), (PG8_LAS unsigned*)(lds + (bufoff) + ldsw + _i * 8192), 16, 0, 0); } while (0)
; #define PG8_LDA(dst, b, h) do { _Pragma("unroll") for (int m = 0; m < 4; ++m) _Pragma("unroll") for (int k = 0; k < 2; ++k) dst[m][k] = *(const PG8_LAS bf16x8*)(lds + PG8_SA(b, h) + aoff + m * 2048 + k * 1024); } while (0)
; #define PG8_LDB(dst, b, h) do { _Pragma("unroll") for (int n = 0; n < 2; ++n) _Pragma("unroll") for (int k = 0; k < 2; ++k) dst[n][k] = *(const PG8_LAS bf16x8*)(lds + PG8_SB(b, h) + boff + n * 2048 + k * 1024); } while (0)
; #define PG8_MMA(ai, bj, At, Bt) do { __builtin_amdgcn_s_setprio(1); _Pragma("unroll") for (int m = 0; m < 4; ++m) _Pragma("unroll") for (int n = 0; n < 2; ++n) _Pragma("unroll") for (int k = 0; k < 2; ++k) \
;         acc[ai][bj][m][n] = __builtin_amdgcn_mfma_f32_16x16x32_bf16(Bt[n][k], At[m][k], acc[ai][bj][m][n], 0, 0, 0); __builtin_amdgcn_s_setprio(0); } while (0)
; #define PG8_WAIT_V(n) asm volatile("s_waitcnt vmcnt(" #n ")" ::: "memory")
; #define PG8_WAIT_L(n) asm volatile("s_waitcnt lgkmcnt(" #n ")" ::: "memory")
; #define PG8_BAR __builtin_amdgcn_s_barrier()
; #define PG8_SCHED __builtin_amdgcn_sched_barrier(0)
; template <class Epi, class Sched, bool ALIGN_EPI = false, bool SP2 = false>
; __device__ __forceinline__ void gemm_phase(PG8_LAS unsigned char* lds, const Gemm g, const Sched& S, const Epi& E) {
;     ...
;             PG8_WAIT_V(8); PG8_WAIT_L(0); PG8_BAR; PG8_MMA(1, 0, At, B0); PG8_MMA(1, 1, At, B1); PG8_BAR; PG8_SCHED;
;             PG8_LDB(B0, 1, 0); PG8_LDB(B1, 1, 1); PG8_SCHED; PG8_LDA(At, 1, 0); PG8_STAGE(PG8_SA(0, 1), a2 + hstep, voffA);
;             PG8_WAIT_V(8); PG8_WAIT_L(0); PG8_BAR; PG8_MMA(0, 0, At, B0); PG8_MMA(0, 1, At, B1); PG8_BAR; PG8_SCHED;
	s_setprio 1
	s_waitcnt lgkmcnt(0)
	v_mfma_f32_16x16x32_bf16 v[60:63], v[150:153], v[182:185], v[60:63]
	v_mfma_f32_16x16x32_bf16 v[56:59], v[158:161], v[182:185], v[56:59]
	v_mfma_f32_16x16x32_bf16 v[52:55], v[150:153], v[196:199], v[52:55]
	v_mfma_f32_16x16x32_bf16 v[48:51], v[158:161], v[196:199], v[48:51]
	v_mfma_f32_16x16x32_bf16 v[40:43], v[150:153], v[204:207], v[40:43]
	v_mfma_f32_16x16x32_bf16 v[32:35], v[158:161], v[204:207], v[32:35]
	v_mfma_f32_16x16x32_bf16 v[24:27], v[150:153], v[212:215], v[24:27]
	v_mfma_f32_16x16x32_bf16 v[16:19], v[158:161], v[212:215], v[16:19]
	v_mfma_f32_16x16x32_bf16 v[60:63], v[154:157], v[186:189], v[60:63]
	v_mfma_f32_16x16x32_bf16 v[56:59], v[162:165], v[186:189], v[56:59]
	v_mfma_f32_16x16x32_bf16 v[52:55], v[154:157], v[200:203], v[52:55]
	v_mfma_f32_16x16x32_bf16 v[48:51], v[162:165], v[200:203], v[48:51]
	v_mfma_f32_16x16x32_bf16 v[40:43], v[154:157], v[208:211], v[40:43]
	v_mfma_f32_16x16x32_bf16 v[32:35], v[162:165], v[208:211], v[32:35]
	v_mfma_f32_16x16x32_bf16 v[24:27], v[154:157], v[216:219], v[24:27]
	v_mfma_f32_16x16x32_bf16 v[16:19], v[162:165], v[216:219], v[16:19]
	v_mfma_f32_16x16x32_bf16 v[44:47], v[166:169], v[182:185], v[44:47]
	v_mfma_f32_16x16x32_bf16 v[36:39], v[174:177], v[182:185], v[36:39]
	v_mfma_f32_16x16x32_bf16 v[28:31], v[166:169], v[196:199], v[28:31]
	v_mfma_f32_16x16x32_bf16 v[20:23], v[174:177], v[196:199], v[20:23]
	v_mfma_f32_16x16x32_bf16 v[12:15], v[166:169], v[204:207], v[12:15]
	v_mfma_f32_16x16x32_bf16 v[8:11], v[174:177], v[204:207], v[8:11]
	v_mfma_f32_16x16x32_bf16 v[4:7], v[166:169], v[212:215], v[4:7]
	v_mfma_f32_16x16x32_bf16 v[0:3], v[174:177], v[212:215], v[0:3]
	v_mfma_f32_16x16x32_bf16 v[44:47], v[170:173], v[186:189], v[44:47]
	v_mfma_f32_16x16x32_bf16 v[36:39], v[178:181], v[186:189], v[36:39]
	v_mfma_f32_16x16x32_bf16 v[28:31], v[170:173], v[200:203], v[28:31]
	v_mfma_f32_16x16x32_bf16 v[20:23], v[178:181], v[200:203], v[20:23]
	v_mfma_f32_16x16x32_bf16 v[12:15], v[170:173], v[208:211], v[12:15]
	v_mfma_f32_16x16x32_bf16 v[8:11], v[178:181], v[208:211], v[8:11]
	v_mfma_f32_16x16x32_bf16 v[4:7], v[170:173], v[216:219], v[4:7]
	v_mfma_f32_16x16x32_bf16 v[0:3], v[178:181], v[216:219], v[0:3]
	s_setprio 0
	s_barrier
	ds_read_b128 v[150:153], v147
	ds_read_b128 v[154:157], v147 offset:1024
	ds_read_b128 v[158:161], v147 offset:2048
	ds_read_b128 v[162:165], v147 offset:3072
	ds_read_b128 v[166:169], v148
	ds_read_b128 v[170:173], v148 offset:1024
	ds_read_b128 v[174:177], v148 offset:2048
	ds_read_b128 v[178:181], v148 offset:3072
	s_add_u32 s18, s18, 0x58000
	s_addc_u32 s19, s19, 0
	s_mov_b32 m0, s21
	v_lshl_add_u64 v[228:229], s[18:19], 0, v[136:137]
	ds_read_b128 v[182:185], v146 offset:32768
	ds_read_b128 v[186:189], v146 offset:33792
	ds_read_b128 v[196:199], v146 offset:34816
	ds_read_b128 v[200:203], v146 offset:35840
	ds_read_b128 v[204:207], v146 offset:36864
	ds_read_b128 v[208:211], v146 offset:37888
	ds_read_b128 v[212:215], v146 offset:38912
	ds_read_b128 v[216:219], v146 offset:39936
	global_load_lds_dwordx4 v[228:229], off
	v_lshl_add_u64 v[228:229], s[18:19], 0, v[128:129]
	s_mov_b32 m0, s22
	s_nop 0
	global_load_lds_dwordx4 v[228:229], off
	s_waitcnt vmcnt(8)
	s_waitcnt lgkmcnt(0)
	s_barrier
	s_setprio 1
	s_waitcnt lgkmcnt(0)
	v_mfma_f32_16x16x32_bf16 v[124:127], v[150:153], v[182:185], v[124:127]
	v_mfma_f32_16x16x32_bf16 v[120:123], v[158:161], v[182:185], v[120:123]
	v_mfma_f32_16x16x32_bf16 v[116:119], v[150:153], v[196:199], v[116:119]
	v_mfma_f32_16x16x32_bf16 v[112:115], v[158:161], v[196:199], v[112:115]
	v_mfma_f32_16x16x32_bf16 v[104:107], v[150:153], v[204:207], v[104:107]
	v_mfma_f32_16x16x32_bf16 v[96:99], v[158:161], v[204:207], v[96:99]
	v_mfma_f32_16x16x32_bf16 v[88:91], v[150:153], v[212:215], v[88:91]
	v_mfma_f32_16x16x32_bf16 v[80:83], v[158:161], v[212:215], v[80:83]
	v_mfma_f32_16x16x32_bf16 v[124:127], v[154:157], v[186:189], v[124:127]
	v_mfma_f32_16x16x32_bf16 v[120:123], v[162:165], v[186:189], v[120:123]
	v_mfma_f32_16x16x32_bf16 v[116:119], v[154:157], v[200:203], v[116:119]
	v_mfma_f32_16x16x32_bf16 v[112:115], v[162:165], v[200:203], v[112:115]
	v_mfma_f32_16x16x32_bf16 v[104:107], v[154:157], v[208:211], v[104:107]
	v_mfma_f32_16x16x32_bf16 v[96:99], v[162:165], v[208:211], v[96:99]
	v_mfma_f32_16x16x32_bf16 v[88:91], v[154:157], v[216:219], v[88:91]
	v_mfma_f32_16x16x32_bf16 v[80:83], v[162:165], v[216:219], v[80:83]
	v_mfma_f32_16x16x32_bf16 v[108:111], v[166:169], v[182:185], v[108:111]
	v_mfma_f32_16x16x32_bf16 v[100:103], v[174:177], v[182:185], v[100:103]
	v_mfma_f32_16x16x32_bf16 v[92:95], v[166:169], v[196:199], v[92:95]
	v_mfma_f32_16x16x32_bf16 v[84:87], v[174:177], v[196:199], v[84:87]
	v_mfma_f32_16x16x32_bf16 v[76:79], v[166:169], v[204:207], v[76:79]
	v_mfma_f32_16x16x32_bf16 v[72:75], v[174:177], v[204:207], v[72:75]
	v_mfma_f32_16x16x32_bf16 v[68:71], v[166:169], v[212:215], v[68:71]
	v_mfma_f32_16x16x32_bf16 v[64:67], v[174:177], v[212:215], v[64:67]
	v_mfma_f32_16x16x32_bf16 v[108:111], v[170:173], v[186:189], v[108:111]
	v_mfma_f32_16x16x32_bf16 v[100:103], v[178:181], v[186:189], v[100:103]
	v_mfma_f32_16x16x32_bf16 v[92:95], v[170:173], v[200:203], v[92:95]
	v_mfma_f32_16x16x32_bf16 v[84:87], v[178:181], v[200:203], v[84:87]
	v_mfma_f32_16x16x32_bf16 v[76:79], v[170:173], v[208:211], v[76:79]
	v_mfma_f32_16x16x32_bf16 v[72:75], v[178:181], v[208:211], v[72:75]
	v_mfma_f32_16x16x32_bf16 v[68:71], v[170:173], v[216:219], v[68:71]
	v_mfma_f32_16x16x32_bf16 v[64:67], v[178:181], v[216:219], v[64:67]
	s_setprio 0
	s_barrier
; #define PG8_STAGE(bufoff, gbase, voff) do { _Pragma("unroll") for (int _i = 0; _i < 2; ++_i) \
;         __builtin_amdgcn_global_load_lds((const unsigned*)((const char*)(gbase) + (voff)[_i]), (PG8_LAS unsigned*)(lds + (bufoff) + ldsw + _i * 8192), 16, 0, 0); } while (0)
; #define PG8_LDA(dst, b, h) do { _Pragma("unroll") for (int m = 0; m < 4; ++m) _Pragma("unroll") for (int k = 0; k < 2; ++k) dst[m][k] = *(const PG8_LAS bf16x8*)(lds + PG8_SA(b, h) + aoff + m * 2048 + k * 1024); } while (0)
; #define PG8_MMA(ai, bj, At, Bt) do { __builtin_amdgcn_s_setprio(1); _Pragma("unroll") for (int m = 0; m < 4; ++m) _Pragma("unroll") for (int n = 0; n < 2; ++n) _Pragma("unroll") for (int k = 0; k < 2; ++k) \
;         acc[ai][bj][m][n] = __builtin_amdgcn_mfma_f32_16x16x32_bf16(Bt[n][k], At[m][k], acc[ai][bj][m][n], 0, 0, 0); __builtin_amdgcn_s_setprio(0); } while (0)
; #define PG8_WAIT_V(n) asm volatile("s_waitcnt vmcnt(" #n ")" ::: "memory")
; #define PG8_WAIT_L(n) asm volatile("s_waitcnt lgkmcnt(" #n ")" ::: "memory")
; #define PG8_BAR __builtin_amdgcn_s_barrier()
; #define PG8_SCHED __builtin_amdgcn_sched_barrier(0)
; template <class Epi, class Sched, bool ALIGN_EPI = false, bool SP2 = false>
; __device__ __forceinline__ void gemm_phase(PG8_LAS unsigned char* lds, const Gemm g, const Sched& S, const Epi& E) {
;     ...
;             PG8_LDA(At, 1, 1); PG8_STAGE(PG8_SB(1, 0), b3, voffB); PG8_STAGE(PG8_SB(1, 1), b3 + hstep, voffB); PG8_STAGE(PG8_SA(1, 0), a3, voffA);
;             PG8_WAIT_V(8); PG8_WAIT_L(0); PG8_BAR; PG8_MMA(1, 0, At, B0); PG8_MMA(1, 1, At, B1); PG8_BAR; PG8_SCHED;
;     ...
;         }
;         if constexpr (ALIGN_EPI) { if (wr == 0) PG8_BAR; }
	s_mov_b32 m0, s39
	v_lshl_add_u64 v[220:221], v[220:221], 0, s[10:11]
	s_add_u32 s16, s16, 0x58080
	ds_read_b128 v[182:185], v146 offset:49152
	ds_read_b128 v[186:189], v146 offset:50176
	ds_read_b128 v[196:199], v146 offset:51200
	ds_read_b128 v[200:203], v146 offset:52224
	ds_read_b128 v[204:207], v146 offset:53248
	ds_read_b128 v[208:211], v146 offset:54272
	ds_read_b128 v[212:215], v146 offset:55296
	ds_read_b128 v[216:219], v146 offset:56320
	global_load_lds_dwordx4 v[220:221], off
	v_lshl_add_u64 v[220:221], v[222:223], 0, s[10:11]
	s_mov_b32 m0, s40
	s_addc_u32 s17, s17, 0
	global_load_lds_dwordx4 v[220:221], off
	v_lshl_add_u64 v[220:221], s[16:17], 0, v[136:137]
	s_mov_b32 m0, s41
	s_nop 0
	global_load_lds_dwordx4 v[220:221], off
	v_lshl_add_u64 v[220:221], s[16:17], 0, v[128:129]
	s_mov_b32 m0, s42
	s_nop 0
	global_load_lds_dwordx4 v[220:221], off
	v_lshl_add_u64 v[220:221], v[224:225], 0, s[10:11]
	s_mov_b32 m0, s26
	s_nop 0
	global_load_lds_dwordx4 v[220:221], off
	v_lshl_add_u64 v[220:221], v[226:227], 0, s[10:11]
	s_mov_b32 m0, s27
	s_nop 0
	global_load_lds_dwordx4 v[220:221], off
	s_waitcnt vmcnt(8)
	s_waitcnt lgkmcnt(0)
	s_barrier
	s_setprio 1
	s_waitcnt lgkmcnt(0)
	v_mfma_f32_16x16x32_bf16 v[60:63], v[150:153], v[182:185], v[60:63]
	v_mfma_f32_16x16x32_bf16 v[56:59], v[158:161], v[182:185], v[56:59]
	v_mfma_f32_16x16x32_bf16 v[52:55], v[150:153], v[196:199], v[52:55]
	v_mfma_f32_16x16x32_bf16 v[48:51], v[158:161], v[196:199], v[48:51]
	v_mfma_f32_16x16x32_bf16 v[40:43], v[150:153], v[204:207], v[40:43]
	v_mfma_f32_16x16x32_bf16 v[32:35], v[158:161], v[204:207], v[32:35]
	v_mfma_f32_16x16x32_bf16 v[24:27], v[150:153], v[212:215], v[24:27]
	v_mfma_f32_16x16x32_bf16 v[16:19], v[158:161], v[212:215], v[16:19]
	v_mfma_f32_16x16x32_bf16 v[60:63], v[154:157], v[186:189], v[60:63]
	v_mfma_f32_16x16x32_bf16 v[56:59], v[162:165], v[186:189], v[56:59]
	v_mfma_f32_16x16x32_bf16 v[52:55], v[154:157], v[200:203], v[52:55]
	v_mfma_f32_16x16x32_bf16 v[48:51], v[162:165], v[200:203], v[48:51]
	v_mfma_f32_16x16x32_bf16 v[40:43], v[154:157], v[208:211], v[40:43]
	v_mfma_f32_16x16x32_bf16 v[32:35], v[162:165], v[208:211], v[32:35]
	v_mfma_f32_16x16x32_bf16 v[24:27], v[154:157], v[216:219], v[24:27]
	v_mfma_f32_16x16x32_bf16 v[16:19], v[162:165], v[216:219], v[16:19]
	v_mfma_f32_16x16x32_bf16 v[44:47], v[166:169], v[182:185], v[44:47]
	v_mfma_f32_16x16x32_bf16 v[36:39], v[174:177], v[182:185], v[36:39]
	v_mfma_f32_16x16x32_bf16 v[28:31], v[166:169], v[196:199], v[28:31]
	v_mfma_f32_16x16x32_bf16 v[20:23], v[174:177], v[196:199], v[20:23]
	v_mfma_f32_16x16x32_bf16 v[12:15], v[166:169], v[204:207], v[12:15]
	v_mfma_f32_16x16x32_bf16 v[8:11], v[174:177], v[204:207], v[8:11]
	v_mfma_f32_16x16x32_bf16 v[4:7], v[166:169], v[212:215], v[4:7]
	v_mfma_f32_16x16x32_bf16 v[0:3], v[174:177], v[212:215], v[0:3]
	v_mfma_f32_16x16x32_bf16 v[44:47], v[170:173], v[186:189], v[44:47]
	v_mfma_f32_16x16x32_bf16 v[36:39], v[178:181], v[186:189], v[36:39]
	v_mfma_f32_16x16x32_bf16 v[28:31], v[170:173], v[200:203], v[28:31]
	v_mfma_f32_16x16x32_bf16 v[20:23], v[178:181], v[200:203], v[20:23]
	v_mfma_f32_16x16x32_bf16 v[12:15], v[170:173], v[208:211], v[12:15]
	v_mfma_f32_16x16x32_bf16 v[8:11], v[178:181], v[208:211], v[8:11]
	v_mfma_f32_16x16x32_bf16 v[4:7], v[170:173], v[216:219], v[4:7]
	v_mfma_f32_16x16x32_bf16 v[0:3], v[178:181], v[216:219], v[0:3]
	s_setprio 0
	s_barrier
	s_add_i32 s30, s30, 2
	s_add_u32 s14, s14, 0x100
	s_addc_u32 s15, s15, 0
	s_cmp_gt_u32 s30, 19
	s_cbranch_scc0 .LBB0_1969
	s_cmpk_lt_u32 s4, 0x100
	s_cbranch_scc0 .LBB0_1972
	s_barrier
